# LayerNorm phase stores marked sc1 (written through the XCD L2 as they stream, so the release at the following grid barrier finds few dirty lines)
# speedup vs baseline: 1.0050x; 1.0050x over previous
; __device__ __forceinline__ int otid() { int t = threadIdx.x; asm volatile("" : "+v"(t)); return t; }
; __device__ __forceinline__ void phase_ln(float* R, const float* __restrict__ g, const float* __restrict__ b, bf16_t* xbf, float samp_scale, const float* __restrict__ part, int nsplit, bool f32_all) {
;   const int tid = otid(), lane = tid & 63, gw = blockIdx.x * 8 + (tid >> 6), nw = gridDim.x * 8;
;   f32x4 gv[4], bv[4];
; #pragma unroll
;   for (int i = 0; i < 4; ++i) { gv[i] = *(const f32x4*)(g + i * 256 + lane * 4); bv[i] = *(const f32x4*)(b + i * 256 + lane * 4); }
;   for (int r = gw; r < MT; r += nw) {
;     float* row = R + (size_t)r * 1024;
;     f32x4 v[4];
; #pragma unroll
;     for (int i = 0; i < 4; ++i) v[i] = *(const f32x4*)(row + i * 256 + lane * 4);
;     if (r >= MP) {
;       for (int sp = 0; sp < nsplit; ++sp) {
;         const float* prow = part + ((size_t)sp * MS + (r - MP)) * 1024;
; #pragma unroll
;         for (int i = 0; i < 4; ++i) v[i] = v[i] + *(const f32x4*)(prow + i * 256 + lane * 4);
;       }
;     }
;     float s = 0.f;
; #pragma unroll
;     for (int i = 0; i < 4; ++i) s += v[i][0] + v[i][1] + v[i][2] + v[i][3];
; #pragma unroll
;     for (int o = 32; o >= 1; o >>= 1) s += __shfl_xor(s, o);
;     const float mean = s * (1.f / 1024.f);
;     float ss = 0.f;
; #pragma unroll
;     for (int i = 0; i < 4; ++i) { v[i] = v[i] - mean; ss += v[i][0] * v[i][0] + v[i][1] * v[i][1] + v[i][2] * v[i][2] + v[i][3] * v[i][3]; }
; #pragma unroll
;     for (int o = 32; o >= 1; o >>= 1) ss += __shfl_xor(ss, o);
;     const float rstd = rsqrtf(ss * (1.f / 1024.f) + LN_EPS);
; #pragma unroll
;     for (int i = 0; i < 4; ++i) {
;       const f32x4 y = v[i] * rstd * gv[i] + bv[i];
;       if (r >= MP) *(f32x4*)(row + i * 256 + lane * 4) = y * samp_scale;
;       else if (f32_all) *(f32x4*)(row + i * 256 + lane * 4) = y;
;       if (xbf) {
;         u32x2 wv;
;         wv[0] = cvt_pk_bf16(y[0], y[1]); wv[1] = cvt_pk_bf16(y[2], y[3]);
;         *(u32x2*)(xbf + (size_t)r * 1024 + i * 256 + lane * 4) = wv;
;       }
;     }
;   }
.LBB0_3720:
	s_or_b64 exec, exec, s[0:1]
	v_readlane_b32 s0, v254, 51
	s_nop 0
	s_cmp_lg_u32 s0, 0
	s_cbranch_scc1 .Lln1_orig
	v_readlane_b32 s6, v254, 2
	v_readlane_b32 s7, v254, 3
	v_readlane_b32 s8, v255, 22
	s_waitcnt lgkmcnt(0)
	s_barrier
	s_load_dwordx4 s[0:3], s[6:7], 0x78
	s_load_dwordx4 s[4:7], s[6:7], 0xa8
	v_readlane_b32 s9, v254, 15
	v_readfirstlane_b32 s10, v244
	v_lshlrev_b32_e32 v114, 4, v252
	v_lshlrev_b32_e32 v115, 3, v252
	s_lshr_b32 s10, s10, 6
	s_add_i32 s9, s9, s10
	s_lshl_b32 s11, s8, 12
	s_waitcnt lgkmcnt(0)
	s_add_u32 s0, s0, s11
	s_addc_u32 s1, s1, 0
	s_add_u32 s2, s2, s11
	s_addc_u32 s3, s3, 0
	global_load_dwordx4 v[34:37], v114, s[0:1] offset:0
	global_load_dwordx4 v[38:41], v114, s[0:1] offset:1024
	global_load_dwordx4 v[42:45], v114, s[0:1] offset:2048
	global_load_dwordx4 v[46:49], v114, s[0:1] offset:3072
	global_load_dwordx4 v[50:53], v114, s[2:3] offset:0
	global_load_dwordx4 v[54:57], v114, s[2:3] offset:1024
	global_load_dwordx4 v[58:61], v114, s[2:3] offset:2048
	global_load_dwordx4 v[62:65], v114, s[2:3] offset:3072
	s_lshl_b32 s11, s9, 12
	s_add_u32 s0, s4, s11
	s_addc_u32 s1, s5, 0
	s_lshl_b32 s11, s9, 11
	s_add_u32 s11, s11, 0x39c0000
	s_add_u32 s2, s6, s11
	s_addc_u32 s3, s7, 0
	global_load_dwordx4 v[0:3], v114, s[0:1] offset:0
	global_load_dwordx4 v[4:7], v114, s[0:1] offset:1024
	global_load_dwordx4 v[8:11], v114, s[0:1] offset:2048
	global_load_dwordx4 v[12:15], v114, s[0:1] offset:3072
	s_add_u32 s0, s0, 0x800000
	s_addc_u32 s1, s1, 0
	global_load_dwordx4 v[18:21], v114, s[0:1] offset:0
	global_load_dwordx4 v[22:25], v114, s[0:1] offset:1024
	global_load_dwordx4 v[26:29], v114, s[0:1] offset:2048
	global_load_dwordx4 v[30:33], v114, s[0:1] offset:3072
	s_waitcnt vmcnt(4)
	v_pk_add_f32 v[66:67], v[0:1], v[2:3]
	v_pk_add_f32 v[68:69], v[4:5], v[6:7]
	v_pk_add_f32 v[70:71], v[8:9], v[10:11]
	v_pk_add_f32 v[72:73], v[12:13], v[14:15]
	v_pk_add_f32 v[66:67], v[66:67], v[68:69]
	v_pk_add_f32 v[70:71], v[70:71], v[72:73]
	v_pk_add_f32 v[66:67], v[66:67], v[70:71]
	v_add_f32_e32 v66, v66, v67
	s_nop 1
	v_add_f32_dpp v66, v66, v66 row_shr:1 row_mask:0xf bank_mask:0xf bound_ctrl:1
	s_nop 1
	v_add_f32_dpp v66, v66, v66 row_shr:2 row_mask:0xf bank_mask:0xf bound_ctrl:1
	s_nop 1
	v_add_f32_dpp v66, v66, v66 row_shr:4 row_mask:0xf bank_mask:0xf bound_ctrl:1
	s_nop 1
	v_add_f32_dpp v66, v66, v66 row_shr:8 row_mask:0xf bank_mask:0xf bound_ctrl:1
	s_nop 0
	v_readlane_b32 s9, v66, 15
	v_readlane_b32 s10, v66, 31
	v_readlane_b32 s11, v66, 47
	v_readlane_b32 vcc_lo, v66, 63
	s_nop 1
	v_mov_b32_e32 v66, s9
	v_add_f32_e32 v66, s10, v66
	v_add_f32_e32 v66, s11, v66
	v_add_f32_e32 v66, vcc_lo, v66
	v_mul_f32_e32 v116, 0x3a800000, v66
	v_mov_b32_e32 v117, v116
	v_pk_add_f32 v[0:1], v[0:1], v[116:117] neg_lo:[0,1] neg_hi:[0,1]
	v_pk_add_f32 v[2:3], v[2:3], v[116:117] neg_lo:[0,1] neg_hi:[0,1]
	v_pk_add_f32 v[4:5], v[4:5], v[116:117] neg_lo:[0,1] neg_hi:[0,1]
	v_pk_add_f32 v[6:7], v[6:7], v[116:117] neg_lo:[0,1] neg_hi:[0,1]
	v_pk_add_f32 v[8:9], v[8:9], v[116:117] neg_lo:[0,1] neg_hi:[0,1]
	v_pk_add_f32 v[10:11], v[10:11], v[116:117] neg_lo:[0,1] neg_hi:[0,1]
	v_pk_add_f32 v[12:13], v[12:13], v[116:117] neg_lo:[0,1] neg_hi:[0,1]
	v_pk_add_f32 v[14:15], v[14:15], v[116:117] neg_lo:[0,1] neg_hi:[0,1]
	v_pk_mul_f32 v[66:67], v[0:1], v[0:1]
	v_pk_mul_f32 v[68:69], v[2:3], v[2:3]
	v_pk_fma_f32 v[66:67], v[4:5], v[4:5], v[66:67]
	v_pk_fma_f32 v[68:69], v[6:7], v[6:7], v[68:69]
	v_pk_fma_f32 v[66:67], v[8:9], v[8:9], v[66:67]
	v_pk_fma_f32 v[68:69], v[10:11], v[10:11], v[68:69]
	v_pk_fma_f32 v[66:67], v[12:13], v[12:13], v[66:67]
	v_pk_fma_f32 v[68:69], v[14:15], v[14:15], v[68:69]
	v_pk_add_f32 v[66:67], v[66:67], v[68:69]
	v_add_f32_e32 v66, v66, v67
	s_nop 1
	v_add_f32_dpp v66, v66, v66 row_shr:1 row_mask:0xf bank_mask:0xf bound_ctrl:1
	s_nop 1
	v_add_f32_dpp v66, v66, v66 row_shr:2 row_mask:0xf bank_mask:0xf bound_ctrl:1
	s_nop 1
	v_add_f32_dpp v66, v66, v66 row_shr:4 row_mask:0xf bank_mask:0xf bound_ctrl:1
	s_nop 1
	v_add_f32_dpp v66, v66, v66 row_shr:8 row_mask:0xf bank_mask:0xf bound_ctrl:1
	s_nop 0
	v_readlane_b32 s9, v66, 15
	v_readlane_b32 s10, v66, 31
	v_readlane_b32 s11, v66, 47
	v_readlane_b32 vcc_lo, v66, 63
	s_nop 1
	v_mov_b32_e32 v66, s9
	v_add_f32_e32 v66, s10, v66
	v_add_f32_e32 v66, s11, v66
	v_add_f32_e32 v66, vcc_lo, v66
	v_mul_f32_e32 v66, 0x3a800000, v66
	v_add_f32_e32 v66, 0x3727c5ac, v66
	v_rsq_f32_e32 v118, v66
	s_nop 0
	v_mov_b32_e32 v119, v118
	v_pk_mul_f32 v[0:1], v[0:1], v[118:119]
	v_pk_mul_f32 v[2:3], v[2:3], v[118:119]
	v_pk_mul_f32 v[4:5], v[4:5], v[118:119]
	v_pk_mul_f32 v[6:7], v[6:7], v[118:119]
	v_pk_mul_f32 v[8:9], v[8:9], v[118:119]
	v_pk_mul_f32 v[10:11], v[10:11], v[118:119]
	v_pk_mul_f32 v[12:13], v[12:13], v[118:119]
	v_pk_mul_f32 v[14:15], v[14:15], v[118:119]
	v_pk_fma_f32 v[76:77], v[0:1], v[34:35], v[50:51]
	v_pk_fma_f32 v[78:79], v[2:3], v[36:37], v[52:53]
	v_pk_fma_f32 v[80:81], v[4:5], v[38:39], v[54:55]
	v_pk_fma_f32 v[82:83], v[6:7], v[40:41], v[56:57]
	v_pk_fma_f32 v[84:85], v[8:9], v[42:43], v[58:59]
	v_pk_fma_f32 v[86:87], v[10:11], v[44:45], v[60:61]
	v_pk_fma_f32 v[88:89], v[12:13], v[46:47], v[62:63]
	v_pk_fma_f32 v[90:91], v[14:15], v[48:49], v[64:65]
	v_cvt_pk_bf16_f32 v92, v76, v77
	v_cvt_pk_bf16_f32 v93, v78, v79
	v_cvt_pk_bf16_f32 v94, v80, v81
	v_cvt_pk_bf16_f32 v95, v82, v83
	v_cvt_pk_bf16_f32 v96, v84, v85
	v_cvt_pk_bf16_f32 v97, v86, v87
	v_cvt_pk_bf16_f32 v98, v88, v89
	v_cvt_pk_bf16_f32 v99, v90, v91
	global_store_dwordx2 v115, v[92:93], s[2:3] offset:0 sc1
	global_store_dwordx2 v115, v[94:95], s[2:3] offset:512 sc1
	global_store_dwordx2 v115, v[96:97], s[2:3] offset:1024 sc1
	global_store_dwordx2 v115, v[98:99], s[2:3] offset:1536 sc1
	s_add_u32 s2, s2, 0x400000
	s_addc_u32 s3, s3, 0
	s_add_u32 s0, s0, 0x800000
	s_addc_u32 s1, s1, 0
	global_load_dwordx4 v[0:3], v114, s[0:1] offset:0
	global_load_dwordx4 v[4:7], v114, s[0:1] offset:1024
	global_load_dwordx4 v[8:11], v114, s[0:1] offset:2048
	global_load_dwordx4 v[12:15], v114, s[0:1] offset:3072
	s_waitcnt vmcnt(8)
; __device__ __forceinline__ void phase_ln(float* R, const float* __restrict__ g, const float* __restrict__ b, bf16_t* xbf, float samp_scale, const float* __restrict__ part, int nsplit, bool f32_all) {
;     ...
;   for (int r = gw; r < MT; r += nw) {
;     float* row = R + (size_t)r * 1024;
;     f32x4 v[4];
; #pragma unroll
;     for (int i = 0; i < 4; ++i) v[i] = *(const f32x4*)(row + i * 256 + lane * 4);
;     if (r >= MP) {
;       for (int sp = 0; sp < nsplit; ++sp) {
;         const float* prow = part + ((size_t)sp * MS + (r - MP)) * 1024;
; #pragma unroll
;         for (int i = 0; i < 4; ++i) v[i] = v[i] + *(const f32x4*)(prow + i * 256 + lane * 4);
;       }
;     }
;     float s = 0.f;
; #pragma unroll
;     for (int i = 0; i < 4; ++i) s += v[i][0] + v[i][1] + v[i][2] + v[i][3];
; #pragma unroll
;     for (int o = 32; o >= 1; o >>= 1) s += __shfl_xor(s, o);
;     const float mean = s * (1.f / 1024.f);
;     float ss = 0.f;
; #pragma unroll
;     for (int i = 0; i < 4; ++i) { v[i] = v[i] - mean; ss += v[i][0] * v[i][0] + v[i][1] * v[i][1] + v[i][2] * v[i][2] + v[i][3] * v[i][3]; }
; #pragma unroll
;     for (int o = 32; o >= 1; o >>= 1) ss += __shfl_xor(ss, o);
;     const float rstd = rsqrtf(ss * (1.f / 1024.f) + LN_EPS);
; #pragma unroll
;     for (int i = 0; i < 4; ++i) {
;       const f32x4 y = v[i] * rstd * gv[i] + bv[i];
;       if (r >= MP) *(f32x4*)(row + i * 256 + lane * 4) = y * samp_scale;
;       else if (f32_all) *(f32x4*)(row + i * 256 + lane * 4) = y;
;       if (xbf) {
;         u32x2 wv;
;         wv[0] = cvt_pk_bf16(y[0], y[1]); wv[1] = cvt_pk_bf16(y[2], y[3]);
;         *(u32x2*)(xbf + (size_t)r * 1024 + i * 256 + lane * 4) = wv;
;       }
;     }
;   }
	v_pk_add_f32 v[66:67], v[18:19], v[20:21]
	v_pk_add_f32 v[68:69], v[22:23], v[24:25]
	v_pk_add_f32 v[70:71], v[26:27], v[28:29]
	v_pk_add_f32 v[72:73], v[30:31], v[32:33]
	v_pk_add_f32 v[66:67], v[66:67], v[68:69]
	v_pk_add_f32 v[70:71], v[70:71], v[72:73]
	v_pk_add_f32 v[66:67], v[66:67], v[70:71]
	v_add_f32_e32 v66, v66, v67
	s_nop 1
	v_add_f32_dpp v66, v66, v66 row_shr:1 row_mask:0xf bank_mask:0xf bound_ctrl:1
	s_nop 1
	v_add_f32_dpp v66, v66, v66 row_shr:2 row_mask:0xf bank_mask:0xf bound_ctrl:1
	s_nop 1
	v_add_f32_dpp v66, v66, v66 row_shr:4 row_mask:0xf bank_mask:0xf bound_ctrl:1
	s_nop 1
	v_add_f32_dpp v66, v66, v66 row_shr:8 row_mask:0xf bank_mask:0xf bound_ctrl:1
	s_nop 0
	v_readlane_b32 s9, v66, 15
	v_readlane_b32 s10, v66, 31
	v_readlane_b32 s11, v66, 47
	v_readlane_b32 vcc_lo, v66, 63
	s_nop 1
	v_mov_b32_e32 v66, s9
	v_add_f32_e32 v66, s10, v66
	v_add_f32_e32 v66, s11, v66
	v_add_f32_e32 v66, vcc_lo, v66
	v_mul_f32_e32 v116, 0x3a800000, v66
	v_mov_b32_e32 v117, v116
	v_pk_add_f32 v[18:19], v[18:19], v[116:117] neg_lo:[0,1] neg_hi:[0,1]
	v_pk_add_f32 v[20:21], v[20:21], v[116:117] neg_lo:[0,1] neg_hi:[0,1]
	v_pk_add_f32 v[22:23], v[22:23], v[116:117] neg_lo:[0,1] neg_hi:[0,1]
	v_pk_add_f32 v[24:25], v[24:25], v[116:117] neg_lo:[0,1] neg_hi:[0,1]
	v_pk_add_f32 v[26:27], v[26:27], v[116:117] neg_lo:[0,1] neg_hi:[0,1]
	v_pk_add_f32 v[28:29], v[28:29], v[116:117] neg_lo:[0,1] neg_hi:[0,1]
	v_pk_add_f32 v[30:31], v[30:31], v[116:117] neg_lo:[0,1] neg_hi:[0,1]
	v_pk_add_f32 v[32:33], v[32:33], v[116:117] neg_lo:[0,1] neg_hi:[0,1]
	v_pk_mul_f32 v[66:67], v[18:19], v[18:19]
	v_pk_mul_f32 v[68:69], v[20:21], v[20:21]
	v_pk_fma_f32 v[66:67], v[22:23], v[22:23], v[66:67]
	v_pk_fma_f32 v[68:69], v[24:25], v[24:25], v[68:69]
	v_pk_fma_f32 v[66:67], v[26:27], v[26:27], v[66:67]
	v_pk_fma_f32 v[68:69], v[28:29], v[28:29], v[68:69]
	v_pk_fma_f32 v[66:67], v[30:31], v[30:31], v[66:67]
	v_pk_fma_f32 v[68:69], v[32:33], v[32:33], v[68:69]
	v_pk_add_f32 v[66:67], v[66:67], v[68:69]
	v_add_f32_e32 v66, v66, v67
	s_nop 1
	v_add_f32_dpp v66, v66, v66 row_shr:1 row_mask:0xf bank_mask:0xf bound_ctrl:1
	s_nop 1
	v_add_f32_dpp v66, v66, v66 row_shr:2 row_mask:0xf bank_mask:0xf bound_ctrl:1
	s_nop 1
	v_add_f32_dpp v66, v66, v66 row_shr:4 row_mask:0xf bank_mask:0xf bound_ctrl:1
	s_nop 1
	v_add_f32_dpp v66, v66, v66 row_shr:8 row_mask:0xf bank_mask:0xf bound_ctrl:1
	s_nop 0
	v_readlane_b32 s9, v66, 15
	v_readlane_b32 s10, v66, 31
	v_readlane_b32 s11, v66, 47
	v_readlane_b32 vcc_lo, v66, 63
	s_nop 1
	v_mov_b32_e32 v66, s9
	v_add_f32_e32 v66, s10, v66
	v_add_f32_e32 v66, s11, v66
	v_add_f32_e32 v66, vcc_lo, v66
	v_mul_f32_e32 v66, 0x3a800000, v66
	v_add_f32_e32 v66, 0x3727c5ac, v66
	v_rsq_f32_e32 v118, v66
	s_nop 0
	v_mov_b32_e32 v119, v118
	v_pk_mul_f32 v[18:19], v[18:19], v[118:119]
	v_pk_mul_f32 v[20:21], v[20:21], v[118:119]
	v_pk_mul_f32 v[22:23], v[22:23], v[118:119]
	v_pk_mul_f32 v[24:25], v[24:25], v[118:119]
	v_pk_mul_f32 v[26:27], v[26:27], v[118:119]
	v_pk_mul_f32 v[28:29], v[28:29], v[118:119]
	v_pk_mul_f32 v[30:31], v[30:31], v[118:119]
	v_pk_mul_f32 v[32:33], v[32:33], v[118:119]
	v_pk_fma_f32 v[76:77], v[18:19], v[34:35], v[50:51]
	v_pk_fma_f32 v[78:79], v[20:21], v[36:37], v[52:53]
	v_pk_fma_f32 v[80:81], v[22:23], v[38:39], v[54:55]
	v_pk_fma_f32 v[82:83], v[24:25], v[40:41], v[56:57]
	v_pk_fma_f32 v[84:85], v[26:27], v[42:43], v[58:59]
	v_pk_fma_f32 v[86:87], v[28:29], v[44:45], v[60:61]
	v_pk_fma_f32 v[88:89], v[30:31], v[46:47], v[62:63]
	v_pk_fma_f32 v[90:91], v[32:33], v[48:49], v[64:65]
	v_cvt_pk_bf16_f32 v92, v76, v77
	v_cvt_pk_bf16_f32 v93, v78, v79
	v_cvt_pk_bf16_f32 v94, v80, v81
	v_cvt_pk_bf16_f32 v95, v82, v83
	v_cvt_pk_bf16_f32 v96, v84, v85
	v_cvt_pk_bf16_f32 v97, v86, v87
	v_cvt_pk_bf16_f32 v98, v88, v89
	v_cvt_pk_bf16_f32 v99, v90, v91
	global_store_dwordx2 v115, v[92:93], s[2:3] offset:0 sc1
	global_store_dwordx2 v115, v[94:95], s[2:3] offset:512 sc1
	global_store_dwordx2 v115, v[96:97], s[2:3] offset:1024 sc1
	global_store_dwordx2 v115, v[98:99], s[2:3] offset:1536 sc1
	s_add_u32 s2, s2, 0x400000
	s_addc_u32 s3, s3, 0
	s_add_u32 s0, s0, 0x800000
	s_addc_u32 s1, s1, 0
	global_load_dwordx4 v[18:21], v114, s[0:1] offset:0
	global_load_dwordx4 v[22:25], v114, s[0:1] offset:1024
	global_load_dwordx4 v[26:29], v114, s[0:1] offset:2048
	global_load_dwordx4 v[30:33], v114, s[0:1] offset:3072
	s_waitcnt vmcnt(8)
; __device__ __forceinline__ void phase_ln(float* R, const float* __restrict__ g, const float* __restrict__ b, bf16_t* xbf, float samp_scale, const float* __restrict__ part, int nsplit, bool f32_all) {
;     ...
;   for (int r = gw; r < MT; r += nw) {
;     float* row = R + (size_t)r * 1024;
;     f32x4 v[4];
; #pragma unroll
;     for (int i = 0; i < 4; ++i) v[i] = *(const f32x4*)(row + i * 256 + lane * 4);
;     if (r >= MP) {
;       for (int sp = 0; sp < nsplit; ++sp) {
;         const float* prow = part + ((size_t)sp * MS + (r - MP)) * 1024;
; #pragma unroll
;         for (int i = 0; i < 4; ++i) v[i] = v[i] + *(const f32x4*)(prow + i * 256 + lane * 4);
;       }
;     }
;     float s = 0.f;
; #pragma unroll
;     for (int i = 0; i < 4; ++i) s += v[i][0] + v[i][1] + v[i][2] + v[i][3];
; #pragma unroll
;     for (int o = 32; o >= 1; o >>= 1) s += __shfl_xor(s, o);
;     const float mean = s * (1.f / 1024.f);
;     float ss = 0.f;
; #pragma unroll
;     for (int i = 0; i < 4; ++i) { v[i] = v[i] - mean; ss += v[i][0] * v[i][0] + v[i][1] * v[i][1] + v[i][2] * v[i][2] + v[i][3] * v[i][3]; }
; #pragma unroll
;     for (int o = 32; o >= 1; o >>= 1) ss += __shfl_xor(ss, o);
;     const float rstd = rsqrtf(ss * (1.f / 1024.f) + LN_EPS);
; #pragma unroll
;     for (int i = 0; i < 4; ++i) {
;       const f32x4 y = v[i] * rstd * gv[i] + bv[i];
;       if (r >= MP) *(f32x4*)(row + i * 256 + lane * 4) = y * samp_scale;
;       else if (f32_all) *(f32x4*)(row + i * 256 + lane * 4) = y;
;       if (xbf) {
;         u32x2 wv;
;         wv[0] = cvt_pk_bf16(y[0], y[1]); wv[1] = cvt_pk_bf16(y[2], y[3]);
;         *(u32x2*)(xbf + (size_t)r * 1024 + i * 256 + lane * 4) = wv;
;       }
;     }
;   }
	v_pk_add_f32 v[66:67], v[0:1], v[2:3]
	v_pk_add_f32 v[68:69], v[4:5], v[6:7]
	v_pk_add_f32 v[70:71], v[8:9], v[10:11]
	v_pk_add_f32 v[72:73], v[12:13], v[14:15]
	v_pk_add_f32 v[66:67], v[66:67], v[68:69]
	v_pk_add_f32 v[70:71], v[70:71], v[72:73]
	v_pk_add_f32 v[66:67], v[66:67], v[70:71]
	v_add_f32_e32 v66, v66, v67
	s_nop 1
	v_add_f32_dpp v66, v66, v66 row_shr:1 row_mask:0xf bank_mask:0xf bound_ctrl:1
	s_nop 1
	v_add_f32_dpp v66, v66, v66 row_shr:2 row_mask:0xf bank_mask:0xf bound_ctrl:1
	s_nop 1
	v_add_f32_dpp v66, v66, v66 row_shr:4 row_mask:0xf bank_mask:0xf bound_ctrl:1
	s_nop 1
	v_add_f32_dpp v66, v66, v66 row_shr:8 row_mask:0xf bank_mask:0xf bound_ctrl:1
	s_nop 0
	v_readlane_b32 s9, v66, 15
	v_readlane_b32 s10, v66, 31
	v_readlane_b32 s11, v66, 47
	v_readlane_b32 vcc_lo, v66, 63
	s_nop 1
	v_mov_b32_e32 v66, s9
	v_add_f32_e32 v66, s10, v66
	v_add_f32_e32 v66, s11, v66
	v_add_f32_e32 v66, vcc_lo, v66
	v_mul_f32_e32 v116, 0x3a800000, v66
	v_mov_b32_e32 v117, v116
	v_pk_add_f32 v[0:1], v[0:1], v[116:117] neg_lo:[0,1] neg_hi:[0,1]
	v_pk_add_f32 v[2:3], v[2:3], v[116:117] neg_lo:[0,1] neg_hi:[0,1]
	v_pk_add_f32 v[4:5], v[4:5], v[116:117] neg_lo:[0,1] neg_hi:[0,1]
	v_pk_add_f32 v[6:7], v[6:7], v[116:117] neg_lo:[0,1] neg_hi:[0,1]
	v_pk_add_f32 v[8:9], v[8:9], v[116:117] neg_lo:[0,1] neg_hi:[0,1]
	v_pk_add_f32 v[10:11], v[10:11], v[116:117] neg_lo:[0,1] neg_hi:[0,1]
	v_pk_add_f32 v[12:13], v[12:13], v[116:117] neg_lo:[0,1] neg_hi:[0,1]
	v_pk_add_f32 v[14:15], v[14:15], v[116:117] neg_lo:[0,1] neg_hi:[0,1]
	v_pk_mul_f32 v[66:67], v[0:1], v[0:1]
	v_pk_mul_f32 v[68:69], v[2:3], v[2:3]
	v_pk_fma_f32 v[66:67], v[4:5], v[4:5], v[66:67]
	v_pk_fma_f32 v[68:69], v[6:7], v[6:7], v[68:69]
	v_pk_fma_f32 v[66:67], v[8:9], v[8:9], v[66:67]
	v_pk_fma_f32 v[68:69], v[10:11], v[10:11], v[68:69]
	v_pk_fma_f32 v[66:67], v[12:13], v[12:13], v[66:67]
	v_pk_fma_f32 v[68:69], v[14:15], v[14:15], v[68:69]
	v_pk_add_f32 v[66:67], v[66:67], v[68:69]
	v_add_f32_e32 v66, v66, v67
	s_nop 1
	v_add_f32_dpp v66, v66, v66 row_shr:1 row_mask:0xf bank_mask:0xf bound_ctrl:1
	s_nop 1
	v_add_f32_dpp v66, v66, v66 row_shr:2 row_mask:0xf bank_mask:0xf bound_ctrl:1
	s_nop 1
	v_add_f32_dpp v66, v66, v66 row_shr:4 row_mask:0xf bank_mask:0xf bound_ctrl:1
	s_nop 1
	v_add_f32_dpp v66, v66, v66 row_shr:8 row_mask:0xf bank_mask:0xf bound_ctrl:1
	s_nop 0
	v_readlane_b32 s9, v66, 15
	v_readlane_b32 s10, v66, 31
	v_readlane_b32 s11, v66, 47
	v_readlane_b32 vcc_lo, v66, 63
	s_nop 1
	v_mov_b32_e32 v66, s9
	v_add_f32_e32 v66, s10, v66
	v_add_f32_e32 v66, s11, v66
	v_add_f32_e32 v66, vcc_lo, v66
	v_mul_f32_e32 v66, 0x3a800000, v66
	v_add_f32_e32 v66, 0x3727c5ac, v66
	v_rsq_f32_e32 v118, v66
	s_nop 0
	v_mov_b32_e32 v119, v118
	v_pk_mul_f32 v[0:1], v[0:1], v[118:119]
	v_pk_mul_f32 v[2:3], v[2:3], v[118:119]
	v_pk_mul_f32 v[4:5], v[4:5], v[118:119]
	v_pk_mul_f32 v[6:7], v[6:7], v[118:119]
	v_pk_mul_f32 v[8:9], v[8:9], v[118:119]
	v_pk_mul_f32 v[10:11], v[10:11], v[118:119]
	v_pk_mul_f32 v[12:13], v[12:13], v[118:119]
	v_pk_mul_f32 v[14:15], v[14:15], v[118:119]
	v_pk_fma_f32 v[76:77], v[0:1], v[34:35], v[50:51]
	v_pk_fma_f32 v[78:79], v[2:3], v[36:37], v[52:53]
	v_pk_fma_f32 v[80:81], v[4:5], v[38:39], v[54:55]
	v_pk_fma_f32 v[82:83], v[6:7], v[40:41], v[56:57]
	v_pk_fma_f32 v[84:85], v[8:9], v[42:43], v[58:59]
	v_pk_fma_f32 v[86:87], v[10:11], v[44:45], v[60:61]
	v_pk_fma_f32 v[88:89], v[12:13], v[46:47], v[62:63]
	v_pk_fma_f32 v[90:91], v[14:15], v[48:49], v[64:65]
	v_cvt_pk_bf16_f32 v92, v76, v77
	v_cvt_pk_bf16_f32 v93, v78, v79
	v_cvt_pk_bf16_f32 v94, v80, v81
	v_cvt_pk_bf16_f32 v95, v82, v83
	v_cvt_pk_bf16_f32 v96, v84, v85
	v_cvt_pk_bf16_f32 v97, v86, v87
	v_cvt_pk_bf16_f32 v98, v88, v89
	v_cvt_pk_bf16_f32 v99, v90, v91
	global_store_dwordx2 v115, v[92:93], s[2:3] offset:0 sc1
	global_store_dwordx2 v115, v[94:95], s[2:3] offset:512 sc1
	global_store_dwordx2 v115, v[96:97], s[2:3] offset:1024 sc1
	global_store_dwordx2 v115, v[98:99], s[2:3] offset:1536 sc1
	s_add_u32 s2, s2, 0x400000
	s_addc_u32 s3, s3, 0
	s_add_u32 s0, s0, 0x800000
	s_addc_u32 s1, s1, 0
	global_load_dwordx4 v[0:3], v114, s[0:1] offset:0
	global_load_dwordx4 v[4:7], v114, s[0:1] offset:1024
	global_load_dwordx4 v[8:11], v114, s[0:1] offset:2048
	global_load_dwordx4 v[12:15], v114, s[0:1] offset:3072
	s_waitcnt vmcnt(8)
; __device__ __forceinline__ void phase_ln(float* R, const float* __restrict__ g, const float* __restrict__ b, bf16_t* xbf, float samp_scale, const float* __restrict__ part, int nsplit, bool f32_all) {
;     ...
;   for (int r = gw; r < MT; r += nw) {
;     float* row = R + (size_t)r * 1024;
;     f32x4 v[4];
; #pragma unroll
;     for (int i = 0; i < 4; ++i) v[i] = *(const f32x4*)(row + i * 256 + lane * 4);
;     if (r >= MP) {
;       for (int sp = 0; sp < nsplit; ++sp) {
;         const float* prow = part + ((size_t)sp * MS + (r - MP)) * 1024;
; #pragma unroll
;         for (int i = 0; i < 4; ++i) v[i] = v[i] + *(const f32x4*)(prow + i * 256 + lane * 4);
;       }
;     }
;     float s = 0.f;
; #pragma unroll
;     for (int i = 0; i < 4; ++i) s += v[i][0] + v[i][1] + v[i][2] + v[i][3];
; #pragma unroll
;     for (int o = 32; o >= 1; o >>= 1) s += __shfl_xor(s, o);
;     const float mean = s * (1.f / 1024.f);
;     float ss = 0.f;
; #pragma unroll
;     for (int i = 0; i < 4; ++i) { v[i] = v[i] - mean; ss += v[i][0] * v[i][0] + v[i][1] * v[i][1] + v[i][2] * v[i][2] + v[i][3] * v[i][3]; }
; #pragma unroll
;     for (int o = 32; o >= 1; o >>= 1) ss += __shfl_xor(ss, o);
;     const float rstd = rsqrtf(ss * (1.f / 1024.f) + LN_EPS);
; #pragma unroll
;     for (int i = 0; i < 4; ++i) {
;       const f32x4 y = v[i] * rstd * gv[i] + bv[i];
;       if (r >= MP) *(f32x4*)(row + i * 256 + lane * 4) = y * samp_scale;
;       else if (f32_all) *(f32x4*)(row + i * 256 + lane * 4) = y;
;       if (xbf) {
;         u32x2 wv;
;         wv[0] = cvt_pk_bf16(y[0], y[1]); wv[1] = cvt_pk_bf16(y[2], y[3]);
;         *(u32x2*)(xbf + (size_t)r * 1024 + i * 256 + lane * 4) = wv;
;       }
;     }
;   }
	v_pk_add_f32 v[66:67], v[18:19], v[20:21]
	v_pk_add_f32 v[68:69], v[22:23], v[24:25]
	v_pk_add_f32 v[70:71], v[26:27], v[28:29]
	v_pk_add_f32 v[72:73], v[30:31], v[32:33]
	v_pk_add_f32 v[66:67], v[66:67], v[68:69]
	v_pk_add_f32 v[70:71], v[70:71], v[72:73]
	v_pk_add_f32 v[66:67], v[66:67], v[70:71]
	v_add_f32_e32 v66, v66, v67
	s_nop 1
	v_add_f32_dpp v66, v66, v66 row_shr:1 row_mask:0xf bank_mask:0xf bound_ctrl:1
	s_nop 1
	v_add_f32_dpp v66, v66, v66 row_shr:2 row_mask:0xf bank_mask:0xf bound_ctrl:1
	s_nop 1
	v_add_f32_dpp v66, v66, v66 row_shr:4 row_mask:0xf bank_mask:0xf bound_ctrl:1
	s_nop 1
	v_add_f32_dpp v66, v66, v66 row_shr:8 row_mask:0xf bank_mask:0xf bound_ctrl:1
	s_nop 0
	v_readlane_b32 s9, v66, 15
	v_readlane_b32 s10, v66, 31
	v_readlane_b32 s11, v66, 47
	v_readlane_b32 vcc_lo, v66, 63
	s_nop 1
	v_mov_b32_e32 v66, s9
	v_add_f32_e32 v66, s10, v66
	v_add_f32_e32 v66, s11, v66
	v_add_f32_e32 v66, vcc_lo, v66
	v_mul_f32_e32 v116, 0x3a800000, v66
	v_mov_b32_e32 v117, v116
	v_pk_add_f32 v[18:19], v[18:19], v[116:117] neg_lo:[0,1] neg_hi:[0,1]
	v_pk_add_f32 v[20:21], v[20:21], v[116:117] neg_lo:[0,1] neg_hi:[0,1]
	v_pk_add_f32 v[22:23], v[22:23], v[116:117] neg_lo:[0,1] neg_hi:[0,1]
	v_pk_add_f32 v[24:25], v[24:25], v[116:117] neg_lo:[0,1] neg_hi:[0,1]
	v_pk_add_f32 v[26:27], v[26:27], v[116:117] neg_lo:[0,1] neg_hi:[0,1]
	v_pk_add_f32 v[28:29], v[28:29], v[116:117] neg_lo:[0,1] neg_hi:[0,1]
	v_pk_add_f32 v[30:31], v[30:31], v[116:117] neg_lo:[0,1] neg_hi:[0,1]
	v_pk_add_f32 v[32:33], v[32:33], v[116:117] neg_lo:[0,1] neg_hi:[0,1]
	v_pk_mul_f32 v[66:67], v[18:19], v[18:19]
	v_pk_mul_f32 v[68:69], v[20:21], v[20:21]
	v_pk_fma_f32 v[66:67], v[22:23], v[22:23], v[66:67]
	v_pk_fma_f32 v[68:69], v[24:25], v[24:25], v[68:69]
	v_pk_fma_f32 v[66:67], v[26:27], v[26:27], v[66:67]
	v_pk_fma_f32 v[68:69], v[28:29], v[28:29], v[68:69]
	v_pk_fma_f32 v[66:67], v[30:31], v[30:31], v[66:67]
	v_pk_fma_f32 v[68:69], v[32:33], v[32:33], v[68:69]
	v_pk_add_f32 v[66:67], v[66:67], v[68:69]
	v_add_f32_e32 v66, v66, v67
	s_nop 1
	v_add_f32_dpp v66, v66, v66 row_shr:1 row_mask:0xf bank_mask:0xf bound_ctrl:1
	s_nop 1
	v_add_f32_dpp v66, v66, v66 row_shr:2 row_mask:0xf bank_mask:0xf bound_ctrl:1
	s_nop 1
	v_add_f32_dpp v66, v66, v66 row_shr:4 row_mask:0xf bank_mask:0xf bound_ctrl:1
	s_nop 1
	v_add_f32_dpp v66, v66, v66 row_shr:8 row_mask:0xf bank_mask:0xf bound_ctrl:1
	s_nop 0
	v_readlane_b32 s9, v66, 15
	v_readlane_b32 s10, v66, 31
	v_readlane_b32 s11, v66, 47
	v_readlane_b32 vcc_lo, v66, 63
	s_nop 1
	v_mov_b32_e32 v66, s9
	v_add_f32_e32 v66, s10, v66
	v_add_f32_e32 v66, s11, v66
	v_add_f32_e32 v66, vcc_lo, v66
	v_mul_f32_e32 v66, 0x3a800000, v66
	v_add_f32_e32 v66, 0x3727c5ac, v66
	v_rsq_f32_e32 v118, v66
	s_nop 0
	v_mov_b32_e32 v119, v118
	v_pk_mul_f32 v[18:19], v[18:19], v[118:119]
	v_pk_mul_f32 v[20:21], v[20:21], v[118:119]
	v_pk_mul_f32 v[22:23], v[22:23], v[118:119]
	v_pk_mul_f32 v[24:25], v[24:25], v[118:119]
	v_pk_mul_f32 v[26:27], v[26:27], v[118:119]
	v_pk_mul_f32 v[28:29], v[28:29], v[118:119]
	v_pk_mul_f32 v[30:31], v[30:31], v[118:119]
	v_pk_mul_f32 v[32:33], v[32:33], v[118:119]
	v_pk_fma_f32 v[76:77], v[18:19], v[34:35], v[50:51]
	v_pk_fma_f32 v[78:79], v[20:21], v[36:37], v[52:53]
	v_pk_fma_f32 v[80:81], v[22:23], v[38:39], v[54:55]
	v_pk_fma_f32 v[82:83], v[24:25], v[40:41], v[56:57]
	v_pk_fma_f32 v[84:85], v[26:27], v[42:43], v[58:59]
	v_pk_fma_f32 v[86:87], v[28:29], v[44:45], v[60:61]
	v_pk_fma_f32 v[88:89], v[30:31], v[46:47], v[62:63]
	v_pk_fma_f32 v[90:91], v[32:33], v[48:49], v[64:65]
	v_cvt_pk_bf16_f32 v92, v76, v77
	v_cvt_pk_bf16_f32 v93, v78, v79
	v_cvt_pk_bf16_f32 v94, v80, v81
	v_cvt_pk_bf16_f32 v95, v82, v83
	v_cvt_pk_bf16_f32 v96, v84, v85
	v_cvt_pk_bf16_f32 v97, v86, v87
	v_cvt_pk_bf16_f32 v98, v88, v89
	v_cvt_pk_bf16_f32 v99, v90, v91
	global_store_dwordx2 v115, v[92:93], s[2:3] offset:0 sc1
	global_store_dwordx2 v115, v[94:95], s[2:3] offset:512 sc1
	global_store_dwordx2 v115, v[96:97], s[2:3] offset:1024 sc1
	global_store_dwordx2 v115, v[98:99], s[2:3] offset:1536 sc1
	s_add_u32 s2, s2, 0x400000
	s_addc_u32 s3, s3, 0
	s_add_u32 s0, s0, 0x800000
	s_addc_u32 s1, s1, 0
	global_load_dwordx4 v[18:21], v114, s[0:1] offset:0
	global_load_dwordx4 v[22:25], v114, s[0:1] offset:1024
	global_load_dwordx4 v[26:29], v114, s[0:1] offset:2048
	global_load_dwordx4 v[30:33], v114, s[0:1] offset:3072
	s_waitcnt vmcnt(8)
; __device__ __forceinline__ void phase_ln(float* R, const float* __restrict__ g, const float* __restrict__ b, bf16_t* xbf, float samp_scale, const float* __restrict__ part, int nsplit, bool f32_all) {
;     ...
;   for (int r = gw; r < MT; r += nw) {
;     float* row = R + (size_t)r * 1024;
;     f32x4 v[4];
; #pragma unroll
;     for (int i = 0; i < 4; ++i) v[i] = *(const f32x4*)(row + i * 256 + lane * 4);
;     if (r >= MP) {
;       for (int sp = 0; sp < nsplit; ++sp) {
;         const float* prow = part + ((size_t)sp * MS + (r - MP)) * 1024;
; #pragma unroll
;         for (int i = 0; i < 4; ++i) v[i] = v[i] + *(const f32x4*)(prow + i * 256 + lane * 4);
;       }
;     }
;     float s = 0.f;
; #pragma unroll
;     for (int i = 0; i < 4; ++i) s += v[i][0] + v[i][1] + v[i][2] + v[i][3];
; #pragma unroll
;     for (int o = 32; o >= 1; o >>= 1) s += __shfl_xor(s, o);
;     const float mean = s * (1.f / 1024.f);
;     float ss = 0.f;
; #pragma unroll
;     for (int i = 0; i < 4; ++i) { v[i] = v[i] - mean; ss += v[i][0] * v[i][0] + v[i][1] * v[i][1] + v[i][2] * v[i][2] + v[i][3] * v[i][3]; }
; #pragma unroll
;     for (int o = 32; o >= 1; o >>= 1) ss += __shfl_xor(ss, o);
;     const float rstd = rsqrtf(ss * (1.f / 1024.f) + LN_EPS);
; #pragma unroll
;     for (int i = 0; i < 4; ++i) {
;       const f32x4 y = v[i] * rstd * gv[i] + bv[i];
;       if (r >= MP) *(f32x4*)(row + i * 256 + lane * 4) = y * samp_scale;
;       else if (f32_all) *(f32x4*)(row + i * 256 + lane * 4) = y;
;       if (xbf) {
;         u32x2 wv;
;         wv[0] = cvt_pk_bf16(y[0], y[1]); wv[1] = cvt_pk_bf16(y[2], y[3]);
;         *(u32x2*)(xbf + (size_t)r * 1024 + i * 256 + lane * 4) = wv;
;       }
;     }
;   }
	v_pk_add_f32 v[66:67], v[0:1], v[2:3]
	v_pk_add_f32 v[68:69], v[4:5], v[6:7]
	v_pk_add_f32 v[70:71], v[8:9], v[10:11]
	v_pk_add_f32 v[72:73], v[12:13], v[14:15]
	v_pk_add_f32 v[66:67], v[66:67], v[68:69]
	v_pk_add_f32 v[70:71], v[70:71], v[72:73]
	v_pk_add_f32 v[66:67], v[66:67], v[70:71]
	v_add_f32_e32 v66, v66, v67
	s_nop 1
	v_add_f32_dpp v66, v66, v66 row_shr:1 row_mask:0xf bank_mask:0xf bound_ctrl:1
	s_nop 1
	v_add_f32_dpp v66, v66, v66 row_shr:2 row_mask:0xf bank_mask:0xf bound_ctrl:1
	s_nop 1
	v_add_f32_dpp v66, v66, v66 row_shr:4 row_mask:0xf bank_mask:0xf bound_ctrl:1
	s_nop 1
	v_add_f32_dpp v66, v66, v66 row_shr:8 row_mask:0xf bank_mask:0xf bound_ctrl:1
	s_nop 0
	v_readlane_b32 s9, v66, 15
	v_readlane_b32 s10, v66, 31
	v_readlane_b32 s11, v66, 47
	v_readlane_b32 vcc_lo, v66, 63
	s_nop 1
	v_mov_b32_e32 v66, s9
	v_add_f32_e32 v66, s10, v66
	v_add_f32_e32 v66, s11, v66
	v_add_f32_e32 v66, vcc_lo, v66
	v_mul_f32_e32 v116, 0x3a800000, v66
	v_mov_b32_e32 v117, v116
	v_pk_add_f32 v[0:1], v[0:1], v[116:117] neg_lo:[0,1] neg_hi:[0,1]
	v_pk_add_f32 v[2:3], v[2:3], v[116:117] neg_lo:[0,1] neg_hi:[0,1]
	v_pk_add_f32 v[4:5], v[4:5], v[116:117] neg_lo:[0,1] neg_hi:[0,1]
	v_pk_add_f32 v[6:7], v[6:7], v[116:117] neg_lo:[0,1] neg_hi:[0,1]
	v_pk_add_f32 v[8:9], v[8:9], v[116:117] neg_lo:[0,1] neg_hi:[0,1]
	v_pk_add_f32 v[10:11], v[10:11], v[116:117] neg_lo:[0,1] neg_hi:[0,1]
	v_pk_add_f32 v[12:13], v[12:13], v[116:117] neg_lo:[0,1] neg_hi:[0,1]
	v_pk_add_f32 v[14:15], v[14:15], v[116:117] neg_lo:[0,1] neg_hi:[0,1]
	v_pk_mul_f32 v[66:67], v[0:1], v[0:1]
	v_pk_mul_f32 v[68:69], v[2:3], v[2:3]
	v_pk_fma_f32 v[66:67], v[4:5], v[4:5], v[66:67]
	v_pk_fma_f32 v[68:69], v[6:7], v[6:7], v[68:69]
	v_pk_fma_f32 v[66:67], v[8:9], v[8:9], v[66:67]
	v_pk_fma_f32 v[68:69], v[10:11], v[10:11], v[68:69]
	v_pk_fma_f32 v[66:67], v[12:13], v[12:13], v[66:67]
	v_pk_fma_f32 v[68:69], v[14:15], v[14:15], v[68:69]
	v_pk_add_f32 v[66:67], v[66:67], v[68:69]
	v_add_f32_e32 v66, v66, v67
	s_nop 1
	v_add_f32_dpp v66, v66, v66 row_shr:1 row_mask:0xf bank_mask:0xf bound_ctrl:1
	s_nop 1
	v_add_f32_dpp v66, v66, v66 row_shr:2 row_mask:0xf bank_mask:0xf bound_ctrl:1
	s_nop 1
	v_add_f32_dpp v66, v66, v66 row_shr:4 row_mask:0xf bank_mask:0xf bound_ctrl:1
	s_nop 1
	v_add_f32_dpp v66, v66, v66 row_shr:8 row_mask:0xf bank_mask:0xf bound_ctrl:1
	s_nop 0
	v_readlane_b32 s9, v66, 15
	v_readlane_b32 s10, v66, 31
	v_readlane_b32 s11, v66, 47
	v_readlane_b32 vcc_lo, v66, 63
	s_nop 1
	v_mov_b32_e32 v66, s9
	v_add_f32_e32 v66, s10, v66
	v_add_f32_e32 v66, s11, v66
	v_add_f32_e32 v66, vcc_lo, v66
	v_mul_f32_e32 v66, 0x3a800000, v66
	v_add_f32_e32 v66, 0x3727c5ac, v66
	v_rsq_f32_e32 v118, v66
	s_nop 0
	v_mov_b32_e32 v119, v118
	v_pk_mul_f32 v[0:1], v[0:1], v[118:119]
	v_pk_mul_f32 v[2:3], v[2:3], v[118:119]
	v_pk_mul_f32 v[4:5], v[4:5], v[118:119]
	v_pk_mul_f32 v[6:7], v[6:7], v[118:119]
	v_pk_mul_f32 v[8:9], v[8:9], v[118:119]
	v_pk_mul_f32 v[10:11], v[10:11], v[118:119]
	v_pk_mul_f32 v[12:13], v[12:13], v[118:119]
	v_pk_mul_f32 v[14:15], v[14:15], v[118:119]
	v_pk_fma_f32 v[76:77], v[0:1], v[34:35], v[50:51]
	v_pk_fma_f32 v[78:79], v[2:3], v[36:37], v[52:53]
	v_pk_fma_f32 v[80:81], v[4:5], v[38:39], v[54:55]
	v_pk_fma_f32 v[82:83], v[6:7], v[40:41], v[56:57]
	v_pk_fma_f32 v[84:85], v[8:9], v[42:43], v[58:59]
	v_pk_fma_f32 v[86:87], v[10:11], v[44:45], v[60:61]
	v_pk_fma_f32 v[88:89], v[12:13], v[46:47], v[62:63]
	v_pk_fma_f32 v[90:91], v[14:15], v[48:49], v[64:65]
	v_cvt_pk_bf16_f32 v92, v76, v77
	v_cvt_pk_bf16_f32 v93, v78, v79
	v_cvt_pk_bf16_f32 v94, v80, v81
	v_cvt_pk_bf16_f32 v95, v82, v83
	v_cvt_pk_bf16_f32 v96, v84, v85
	v_cvt_pk_bf16_f32 v97, v86, v87
	v_cvt_pk_bf16_f32 v98, v88, v89
	v_cvt_pk_bf16_f32 v99, v90, v91
	global_store_dwordx2 v115, v[92:93], s[2:3] offset:0 sc1
	global_store_dwordx2 v115, v[94:95], s[2:3] offset:512 sc1
	global_store_dwordx2 v115, v[96:97], s[2:3] offset:1024 sc1
	global_store_dwordx2 v115, v[98:99], s[2:3] offset:1536 sc1
	s_add_u32 s2, s2, 0x400000
	s_addc_u32 s3, s3, 0
	s_add_u32 s0, s0, 0x800000
	s_addc_u32 s1, s1, 0
	global_load_dwordx4 v[0:3], v114, s[0:1] offset:0
	global_load_dwordx4 v[4:7], v114, s[0:1] offset:1024
	global_load_dwordx4 v[8:11], v114, s[0:1] offset:2048
	global_load_dwordx4 v[12:15], v114, s[0:1] offset:3072
	s_waitcnt vmcnt(8)
; __device__ __forceinline__ void phase_ln(float* R, const float* __restrict__ g, const float* __restrict__ b, bf16_t* xbf, float samp_scale, const float* __restrict__ part, int nsplit, bool f32_all) {
;     ...
;   for (int r = gw; r < MT; r += nw) {
;     float* row = R + (size_t)r * 1024;
;     f32x4 v[4];
; #pragma unroll
;     for (int i = 0; i < 4; ++i) v[i] = *(const f32x4*)(row + i * 256 + lane * 4);
;     if (r >= MP) {
;       for (int sp = 0; sp < nsplit; ++sp) {
;         const float* prow = part + ((size_t)sp * MS + (r - MP)) * 1024;
; #pragma unroll
;         for (int i = 0; i < 4; ++i) v[i] = v[i] + *(const f32x4*)(prow + i * 256 + lane * 4);
;       }
;     }
;     float s = 0.f;
; #pragma unroll
;     for (int i = 0; i < 4; ++i) s += v[i][0] + v[i][1] + v[i][2] + v[i][3];
; #pragma unroll
;     for (int o = 32; o >= 1; o >>= 1) s += __shfl_xor(s, o);
;     const float mean = s * (1.f / 1024.f);
;     float ss = 0.f;
; #pragma unroll
;     for (int i = 0; i < 4; ++i) { v[i] = v[i] - mean; ss += v[i][0] * v[i][0] + v[i][1] * v[i][1] + v[i][2] * v[i][2] + v[i][3] * v[i][3]; }
; #pragma unroll
;     for (int o = 32; o >= 1; o >>= 1) ss += __shfl_xor(ss, o);
;     const float rstd = rsqrtf(ss * (1.f / 1024.f) + LN_EPS);
; #pragma unroll
;     for (int i = 0; i < 4; ++i) {
;       const f32x4 y = v[i] * rstd * gv[i] + bv[i];
;       if (r >= MP) *(f32x4*)(row + i * 256 + lane * 4) = y * samp_scale;
;       else if (f32_all) *(f32x4*)(row + i * 256 + lane * 4) = y;
;       if (xbf) {
;         u32x2 wv;
;         wv[0] = cvt_pk_bf16(y[0], y[1]); wv[1] = cvt_pk_bf16(y[2], y[3]);
;         *(u32x2*)(xbf + (size_t)r * 1024 + i * 256 + lane * 4) = wv;
;       }
;     }
;   }
	v_pk_add_f32 v[66:67], v[18:19], v[20:21]
	v_pk_add_f32 v[68:69], v[22:23], v[24:25]
	v_pk_add_f32 v[70:71], v[26:27], v[28:29]
	v_pk_add_f32 v[72:73], v[30:31], v[32:33]
	v_pk_add_f32 v[66:67], v[66:67], v[68:69]
	v_pk_add_f32 v[70:71], v[70:71], v[72:73]
	v_pk_add_f32 v[66:67], v[66:67], v[70:71]
	v_add_f32_e32 v66, v66, v67
	s_nop 1
	v_add_f32_dpp v66, v66, v66 row_shr:1 row_mask:0xf bank_mask:0xf bound_ctrl:1
	s_nop 1
	v_add_f32_dpp v66, v66, v66 row_shr:2 row_mask:0xf bank_mask:0xf bound_ctrl:1
	s_nop 1
	v_add_f32_dpp v66, v66, v66 row_shr:4 row_mask:0xf bank_mask:0xf bound_ctrl:1
	s_nop 1
	v_add_f32_dpp v66, v66, v66 row_shr:8 row_mask:0xf bank_mask:0xf bound_ctrl:1
	s_nop 0
	v_readlane_b32 s9, v66, 15
	v_readlane_b32 s10, v66, 31
	v_readlane_b32 s11, v66, 47
	v_readlane_b32 vcc_lo, v66, 63
	s_nop 1
	v_mov_b32_e32 v66, s9
	v_add_f32_e32 v66, s10, v66
	v_add_f32_e32 v66, s11, v66
	v_add_f32_e32 v66, vcc_lo, v66
	v_mul_f32_e32 v116, 0x3a800000, v66
	v_mov_b32_e32 v117, v116
	v_pk_add_f32 v[18:19], v[18:19], v[116:117] neg_lo:[0,1] neg_hi:[0,1]
	v_pk_add_f32 v[20:21], v[20:21], v[116:117] neg_lo:[0,1] neg_hi:[0,1]
	v_pk_add_f32 v[22:23], v[22:23], v[116:117] neg_lo:[0,1] neg_hi:[0,1]
	v_pk_add_f32 v[24:25], v[24:25], v[116:117] neg_lo:[0,1] neg_hi:[0,1]
	v_pk_add_f32 v[26:27], v[26:27], v[116:117] neg_lo:[0,1] neg_hi:[0,1]
	v_pk_add_f32 v[28:29], v[28:29], v[116:117] neg_lo:[0,1] neg_hi:[0,1]
	v_pk_add_f32 v[30:31], v[30:31], v[116:117] neg_lo:[0,1] neg_hi:[0,1]
	v_pk_add_f32 v[32:33], v[32:33], v[116:117] neg_lo:[0,1] neg_hi:[0,1]
	v_pk_mul_f32 v[66:67], v[18:19], v[18:19]
	v_pk_mul_f32 v[68:69], v[20:21], v[20:21]
	v_pk_fma_f32 v[66:67], v[22:23], v[22:23], v[66:67]
	v_pk_fma_f32 v[68:69], v[24:25], v[24:25], v[68:69]
	v_pk_fma_f32 v[66:67], v[26:27], v[26:27], v[66:67]
	v_pk_fma_f32 v[68:69], v[28:29], v[28:29], v[68:69]
	v_pk_fma_f32 v[66:67], v[30:31], v[30:31], v[66:67]
	v_pk_fma_f32 v[68:69], v[32:33], v[32:33], v[68:69]
	v_pk_add_f32 v[66:67], v[66:67], v[68:69]
	v_add_f32_e32 v66, v66, v67
	s_nop 1
	v_add_f32_dpp v66, v66, v66 row_shr:1 row_mask:0xf bank_mask:0xf bound_ctrl:1
	s_nop 1
	v_add_f32_dpp v66, v66, v66 row_shr:2 row_mask:0xf bank_mask:0xf bound_ctrl:1
	s_nop 1
	v_add_f32_dpp v66, v66, v66 row_shr:4 row_mask:0xf bank_mask:0xf bound_ctrl:1
	s_nop 1
	v_add_f32_dpp v66, v66, v66 row_shr:8 row_mask:0xf bank_mask:0xf bound_ctrl:1
	s_nop 0
	v_readlane_b32 s9, v66, 15
	v_readlane_b32 s10, v66, 31
	v_readlane_b32 s11, v66, 47
	v_readlane_b32 vcc_lo, v66, 63
	s_nop 1
	v_mov_b32_e32 v66, s9
	v_add_f32_e32 v66, s10, v66
	v_add_f32_e32 v66, s11, v66
	v_add_f32_e32 v66, vcc_lo, v66
	v_mul_f32_e32 v66, 0x3a800000, v66
	v_add_f32_e32 v66, 0x3727c5ac, v66
	v_rsq_f32_e32 v118, v66
	s_nop 0
	v_mov_b32_e32 v119, v118
	v_pk_mul_f32 v[18:19], v[18:19], v[118:119]
	v_pk_mul_f32 v[20:21], v[20:21], v[118:119]
	v_pk_mul_f32 v[22:23], v[22:23], v[118:119]
	v_pk_mul_f32 v[24:25], v[24:25], v[118:119]
	v_pk_mul_f32 v[26:27], v[26:27], v[118:119]
	v_pk_mul_f32 v[28:29], v[28:29], v[118:119]
	v_pk_mul_f32 v[30:31], v[30:31], v[118:119]
	v_pk_mul_f32 v[32:33], v[32:33], v[118:119]
	v_pk_fma_f32 v[76:77], v[18:19], v[34:35], v[50:51]
	v_pk_fma_f32 v[78:79], v[20:21], v[36:37], v[52:53]
	v_pk_fma_f32 v[80:81], v[22:23], v[38:39], v[54:55]
	v_pk_fma_f32 v[82:83], v[24:25], v[40:41], v[56:57]
	v_pk_fma_f32 v[84:85], v[26:27], v[42:43], v[58:59]
	v_pk_fma_f32 v[86:87], v[28:29], v[44:45], v[60:61]
	v_pk_fma_f32 v[88:89], v[30:31], v[46:47], v[62:63]
	v_pk_fma_f32 v[90:91], v[32:33], v[48:49], v[64:65]
	v_cvt_pk_bf16_f32 v92, v76, v77
	v_cvt_pk_bf16_f32 v93, v78, v79
	v_cvt_pk_bf16_f32 v94, v80, v81
	v_cvt_pk_bf16_f32 v95, v82, v83
	v_cvt_pk_bf16_f32 v96, v84, v85
	v_cvt_pk_bf16_f32 v97, v86, v87
	v_cvt_pk_bf16_f32 v98, v88, v89
	v_cvt_pk_bf16_f32 v99, v90, v91
	global_store_dwordx2 v115, v[92:93], s[2:3] offset:0 sc1
	global_store_dwordx2 v115, v[94:95], s[2:3] offset:512 sc1
	global_store_dwordx2 v115, v[96:97], s[2:3] offset:1024 sc1
	global_store_dwordx2 v115, v[98:99], s[2:3] offset:1536 sc1
	s_add_u32 s2, s2, 0x400000
	s_addc_u32 s3, s3, 0
	s_add_u32 s0, s0, 0x800000
	s_addc_u32 s1, s1, 0
	global_load_dwordx4 v[18:21], v114, s[0:1] offset:0
	global_load_dwordx4 v[22:25], v114, s[0:1] offset:1024
	global_load_dwordx4 v[26:29], v114, s[0:1] offset:2048
	global_load_dwordx4 v[30:33], v114, s[0:1] offset:3072
	s_waitcnt vmcnt(8)
; __device__ __forceinline__ void phase_ln(float* R, const float* __restrict__ g, const float* __restrict__ b, bf16_t* xbf, float samp_scale, const float* __restrict__ part, int nsplit, bool f32_all) {
;     ...
;   for (int r = gw; r < MT; r += nw) {
;     float* row = R + (size_t)r * 1024;
;     f32x4 v[4];
; #pragma unroll
;     for (int i = 0; i < 4; ++i) v[i] = *(const f32x4*)(row + i * 256 + lane * 4);
;     if (r >= MP) {
;       for (int sp = 0; sp < nsplit; ++sp) {
;         const float* prow = part + ((size_t)sp * MS + (r - MP)) * 1024;
; #pragma unroll
;         for (int i = 0; i < 4; ++i) v[i] = v[i] + *(const f32x4*)(prow + i * 256 + lane * 4);
;       }
;     }
;     float s = 0.f;
; #pragma unroll
;     for (int i = 0; i < 4; ++i) s += v[i][0] + v[i][1] + v[i][2] + v[i][3];
; #pragma unroll
;     for (int o = 32; o >= 1; o >>= 1) s += __shfl_xor(s, o);
;     const float mean = s * (1.f / 1024.f);
;     float ss = 0.f;
; #pragma unroll
;     for (int i = 0; i < 4; ++i) { v[i] = v[i] - mean; ss += v[i][0] * v[i][0] + v[i][1] * v[i][1] + v[i][2] * v[i][2] + v[i][3] * v[i][3]; }
; #pragma unroll
;     for (int o = 32; o >= 1; o >>= 1) ss += __shfl_xor(ss, o);
;     const float rstd = rsqrtf(ss * (1.f / 1024.f) + LN_EPS);
; #pragma unroll
;     for (int i = 0; i < 4; ++i) {
;       const f32x4 y = v[i] * rstd * gv[i] + bv[i];
;       if (r >= MP) *(f32x4*)(row + i * 256 + lane * 4) = y * samp_scale;
;       else if (f32_all) *(f32x4*)(row + i * 256 + lane * 4) = y;
;       if (xbf) {
;         u32x2 wv;
;         wv[0] = cvt_pk_bf16(y[0], y[1]); wv[1] = cvt_pk_bf16(y[2], y[3]);
;         *(u32x2*)(xbf + (size_t)r * 1024 + i * 256 + lane * 4) = wv;
;       }
;     }
;   }
	v_pk_add_f32 v[66:67], v[0:1], v[2:3]
	v_pk_add_f32 v[68:69], v[4:5], v[6:7]
	v_pk_add_f32 v[70:71], v[8:9], v[10:11]
	v_pk_add_f32 v[72:73], v[12:13], v[14:15]
	v_pk_add_f32 v[66:67], v[66:67], v[68:69]
	v_pk_add_f32 v[70:71], v[70:71], v[72:73]
	v_pk_add_f32 v[66:67], v[66:67], v[70:71]
	v_add_f32_e32 v66, v66, v67
	s_nop 1
	v_add_f32_dpp v66, v66, v66 row_shr:1 row_mask:0xf bank_mask:0xf bound_ctrl:1
	s_nop 1
	v_add_f32_dpp v66, v66, v66 row_shr:2 row_mask:0xf bank_mask:0xf bound_ctrl:1
	s_nop 1
	v_add_f32_dpp v66, v66, v66 row_shr:4 row_mask:0xf bank_mask:0xf bound_ctrl:1
	s_nop 1
	v_add_f32_dpp v66, v66, v66 row_shr:8 row_mask:0xf bank_mask:0xf bound_ctrl:1
	s_nop 0
	v_readlane_b32 s9, v66, 15
	v_readlane_b32 s10, v66, 31
	v_readlane_b32 s11, v66, 47
	v_readlane_b32 vcc_lo, v66, 63
	s_nop 1
	v_mov_b32_e32 v66, s9
	v_add_f32_e32 v66, s10, v66
	v_add_f32_e32 v66, s11, v66
	v_add_f32_e32 v66, vcc_lo, v66
	v_mul_f32_e32 v116, 0x3a800000, v66
	v_mov_b32_e32 v117, v116
	v_pk_add_f32 v[0:1], v[0:1], v[116:117] neg_lo:[0,1] neg_hi:[0,1]
	v_pk_add_f32 v[2:3], v[2:3], v[116:117] neg_lo:[0,1] neg_hi:[0,1]
	v_pk_add_f32 v[4:5], v[4:5], v[116:117] neg_lo:[0,1] neg_hi:[0,1]
	v_pk_add_f32 v[6:7], v[6:7], v[116:117] neg_lo:[0,1] neg_hi:[0,1]
	v_pk_add_f32 v[8:9], v[8:9], v[116:117] neg_lo:[0,1] neg_hi:[0,1]
	v_pk_add_f32 v[10:11], v[10:11], v[116:117] neg_lo:[0,1] neg_hi:[0,1]
	v_pk_add_f32 v[12:13], v[12:13], v[116:117] neg_lo:[0,1] neg_hi:[0,1]
	v_pk_add_f32 v[14:15], v[14:15], v[116:117] neg_lo:[0,1] neg_hi:[0,1]
	v_pk_mul_f32 v[66:67], v[0:1], v[0:1]
	v_pk_mul_f32 v[68:69], v[2:3], v[2:3]
	v_pk_fma_f32 v[66:67], v[4:5], v[4:5], v[66:67]
	v_pk_fma_f32 v[68:69], v[6:7], v[6:7], v[68:69]
	v_pk_fma_f32 v[66:67], v[8:9], v[8:9], v[66:67]
	v_pk_fma_f32 v[68:69], v[10:11], v[10:11], v[68:69]
	v_pk_fma_f32 v[66:67], v[12:13], v[12:13], v[66:67]
	v_pk_fma_f32 v[68:69], v[14:15], v[14:15], v[68:69]
	v_pk_add_f32 v[66:67], v[66:67], v[68:69]
	v_add_f32_e32 v66, v66, v67
	s_nop 1
	v_add_f32_dpp v66, v66, v66 row_shr:1 row_mask:0xf bank_mask:0xf bound_ctrl:1
	s_nop 1
	v_add_f32_dpp v66, v66, v66 row_shr:2 row_mask:0xf bank_mask:0xf bound_ctrl:1
	s_nop 1
	v_add_f32_dpp v66, v66, v66 row_shr:4 row_mask:0xf bank_mask:0xf bound_ctrl:1
	s_nop 1
	v_add_f32_dpp v66, v66, v66 row_shr:8 row_mask:0xf bank_mask:0xf bound_ctrl:1
	s_nop 0
	v_readlane_b32 s9, v66, 15
	v_readlane_b32 s10, v66, 31
	v_readlane_b32 s11, v66, 47
	v_readlane_b32 vcc_lo, v66, 63
	s_nop 1
	v_mov_b32_e32 v66, s9
	v_add_f32_e32 v66, s10, v66
	v_add_f32_e32 v66, s11, v66
	v_add_f32_e32 v66, vcc_lo, v66
	v_mul_f32_e32 v66, 0x3a800000, v66
	v_add_f32_e32 v66, 0x3727c5ac, v66
	v_rsq_f32_e32 v118, v66
	s_nop 0
	v_mov_b32_e32 v119, v118
	v_pk_mul_f32 v[0:1], v[0:1], v[118:119]
	v_pk_mul_f32 v[2:3], v[2:3], v[118:119]
	v_pk_mul_f32 v[4:5], v[4:5], v[118:119]
	v_pk_mul_f32 v[6:7], v[6:7], v[118:119]
	v_pk_mul_f32 v[8:9], v[8:9], v[118:119]
	v_pk_mul_f32 v[10:11], v[10:11], v[118:119]
	v_pk_mul_f32 v[12:13], v[12:13], v[118:119]
	v_pk_mul_f32 v[14:15], v[14:15], v[118:119]
	v_pk_fma_f32 v[76:77], v[0:1], v[34:35], v[50:51]
	v_pk_fma_f32 v[78:79], v[2:3], v[36:37], v[52:53]
	v_pk_fma_f32 v[80:81], v[4:5], v[38:39], v[54:55]
	v_pk_fma_f32 v[82:83], v[6:7], v[40:41], v[56:57]
	v_pk_fma_f32 v[84:85], v[8:9], v[42:43], v[58:59]
	v_pk_fma_f32 v[86:87], v[10:11], v[44:45], v[60:61]
	v_pk_fma_f32 v[88:89], v[12:13], v[46:47], v[62:63]
	v_pk_fma_f32 v[90:91], v[14:15], v[48:49], v[64:65]
	v_cvt_pk_bf16_f32 v92, v76, v77
	v_cvt_pk_bf16_f32 v93, v78, v79
	v_cvt_pk_bf16_f32 v94, v80, v81
	v_cvt_pk_bf16_f32 v95, v82, v83
	v_cvt_pk_bf16_f32 v96, v84, v85
	v_cvt_pk_bf16_f32 v97, v86, v87
	v_cvt_pk_bf16_f32 v98, v88, v89
	v_cvt_pk_bf16_f32 v99, v90, v91
	global_store_dwordx2 v115, v[92:93], s[2:3] offset:0 sc1
	global_store_dwordx2 v115, v[94:95], s[2:3] offset:512 sc1
	global_store_dwordx2 v115, v[96:97], s[2:3] offset:1024 sc1
	global_store_dwordx2 v115, v[98:99], s[2:3] offset:1536 sc1
	s_add_u32 s2, s2, 0x400000
	s_addc_u32 s3, s3, 0
	s_add_u32 s0, s0, 0x800000
	s_addc_u32 s1, s1, 0
	global_load_dwordx4 v[0:3], v114, s[0:1] offset:0
	global_load_dwordx4 v[4:7], v114, s[0:1] offset:1024
	global_load_dwordx4 v[8:11], v114, s[0:1] offset:2048
	global_load_dwordx4 v[12:15], v114, s[0:1] offset:3072
	s_waitcnt vmcnt(8)
; __device__ __forceinline__ void phase_ln(float* R, const float* __restrict__ g, const float* __restrict__ b, bf16_t* xbf, float samp_scale, const float* __restrict__ part, int nsplit, bool f32_all) {
;     ...
;   for (int r = gw; r < MT; r += nw) {
;     float* row = R + (size_t)r * 1024;
;     f32x4 v[4];
; #pragma unroll
;     for (int i = 0; i < 4; ++i) v[i] = *(const f32x4*)(row + i * 256 + lane * 4);
;     if (r >= MP) {
;       for (int sp = 0; sp < nsplit; ++sp) {
;         const float* prow = part + ((size_t)sp * MS + (r - MP)) * 1024;
; #pragma unroll
;         for (int i = 0; i < 4; ++i) v[i] = v[i] + *(const f32x4*)(prow + i * 256 + lane * 4);
;       }
;     }
;     float s = 0.f;
; #pragma unroll
;     for (int i = 0; i < 4; ++i) s += v[i][0] + v[i][1] + v[i][2] + v[i][3];
; #pragma unroll
;     for (int o = 32; o >= 1; o >>= 1) s += __shfl_xor(s, o);
;     const float mean = s * (1.f / 1024.f);
;     float ss = 0.f;
; #pragma unroll
;     for (int i = 0; i < 4; ++i) { v[i] = v[i] - mean; ss += v[i][0] * v[i][0] + v[i][1] * v[i][1] + v[i][2] * v[i][2] + v[i][3] * v[i][3]; }
; #pragma unroll
;     for (int o = 32; o >= 1; o >>= 1) ss += __shfl_xor(ss, o);
;     const float rstd = rsqrtf(ss * (1.f / 1024.f) + LN_EPS);
; #pragma unroll
;     for (int i = 0; i < 4; ++i) {
;       const f32x4 y = v[i] * rstd * gv[i] + bv[i];
;       if (r >= MP) *(f32x4*)(row + i * 256 + lane * 4) = y * samp_scale;
;       else if (f32_all) *(f32x4*)(row + i * 256 + lane * 4) = y;
;       if (xbf) {
;         u32x2 wv;
;         wv[0] = cvt_pk_bf16(y[0], y[1]); wv[1] = cvt_pk_bf16(y[2], y[3]);
;         *(u32x2*)(xbf + (size_t)r * 1024 + i * 256 + lane * 4) = wv;
;       }
;     }
;   }
	v_pk_add_f32 v[66:67], v[18:19], v[20:21]
	v_pk_add_f32 v[68:69], v[22:23], v[24:25]
	v_pk_add_f32 v[70:71], v[26:27], v[28:29]
	v_pk_add_f32 v[72:73], v[30:31], v[32:33]
	v_pk_add_f32 v[66:67], v[66:67], v[68:69]
	v_pk_add_f32 v[70:71], v[70:71], v[72:73]
	v_pk_add_f32 v[66:67], v[66:67], v[70:71]
	v_add_f32_e32 v66, v66, v67
	s_nop 1
	v_add_f32_dpp v66, v66, v66 row_shr:1 row_mask:0xf bank_mask:0xf bound_ctrl:1
	s_nop 1
	v_add_f32_dpp v66, v66, v66 row_shr:2 row_mask:0xf bank_mask:0xf bound_ctrl:1
	s_nop 1
	v_add_f32_dpp v66, v66, v66 row_shr:4 row_mask:0xf bank_mask:0xf bound_ctrl:1
	s_nop 1
	v_add_f32_dpp v66, v66, v66 row_shr:8 row_mask:0xf bank_mask:0xf bound_ctrl:1
	s_nop 0
	v_readlane_b32 s9, v66, 15
	v_readlane_b32 s10, v66, 31
	v_readlane_b32 s11, v66, 47
	v_readlane_b32 vcc_lo, v66, 63
	s_nop 1
	v_mov_b32_e32 v66, s9
	v_add_f32_e32 v66, s10, v66
	v_add_f32_e32 v66, s11, v66
	v_add_f32_e32 v66, vcc_lo, v66
	v_mul_f32_e32 v116, 0x3a800000, v66
	v_mov_b32_e32 v117, v116
	v_pk_add_f32 v[18:19], v[18:19], v[116:117] neg_lo:[0,1] neg_hi:[0,1]
	v_pk_add_f32 v[20:21], v[20:21], v[116:117] neg_lo:[0,1] neg_hi:[0,1]
	v_pk_add_f32 v[22:23], v[22:23], v[116:117] neg_lo:[0,1] neg_hi:[0,1]
	v_pk_add_f32 v[24:25], v[24:25], v[116:117] neg_lo:[0,1] neg_hi:[0,1]
	v_pk_add_f32 v[26:27], v[26:27], v[116:117] neg_lo:[0,1] neg_hi:[0,1]
	v_pk_add_f32 v[28:29], v[28:29], v[116:117] neg_lo:[0,1] neg_hi:[0,1]
	v_pk_add_f32 v[30:31], v[30:31], v[116:117] neg_lo:[0,1] neg_hi:[0,1]
	v_pk_add_f32 v[32:33], v[32:33], v[116:117] neg_lo:[0,1] neg_hi:[0,1]
	v_pk_mul_f32 v[66:67], v[18:19], v[18:19]
	v_pk_mul_f32 v[68:69], v[20:21], v[20:21]
	v_pk_fma_f32 v[66:67], v[22:23], v[22:23], v[66:67]
	v_pk_fma_f32 v[68:69], v[24:25], v[24:25], v[68:69]
	v_pk_fma_f32 v[66:67], v[26:27], v[26:27], v[66:67]
	v_pk_fma_f32 v[68:69], v[28:29], v[28:29], v[68:69]
	v_pk_fma_f32 v[66:67], v[30:31], v[30:31], v[66:67]
	v_pk_fma_f32 v[68:69], v[32:33], v[32:33], v[68:69]
	v_pk_add_f32 v[66:67], v[66:67], v[68:69]
	v_add_f32_e32 v66, v66, v67
	s_nop 1
	v_add_f32_dpp v66, v66, v66 row_shr:1 row_mask:0xf bank_mask:0xf bound_ctrl:1
	s_nop 1
	v_add_f32_dpp v66, v66, v66 row_shr:2 row_mask:0xf bank_mask:0xf bound_ctrl:1
	s_nop 1
	v_add_f32_dpp v66, v66, v66 row_shr:4 row_mask:0xf bank_mask:0xf bound_ctrl:1
	s_nop 1
	v_add_f32_dpp v66, v66, v66 row_shr:8 row_mask:0xf bank_mask:0xf bound_ctrl:1
	s_nop 0
	v_readlane_b32 s9, v66, 15
	v_readlane_b32 s10, v66, 31
	v_readlane_b32 s11, v66, 47
	v_readlane_b32 vcc_lo, v66, 63
	s_nop 1
	v_mov_b32_e32 v66, s9
	v_add_f32_e32 v66, s10, v66
	v_add_f32_e32 v66, s11, v66
	v_add_f32_e32 v66, vcc_lo, v66
	v_mul_f32_e32 v66, 0x3a800000, v66
	v_add_f32_e32 v66, 0x3727c5ac, v66
	v_rsq_f32_e32 v118, v66
	s_nop 0
	v_mov_b32_e32 v119, v118
	v_pk_mul_f32 v[18:19], v[18:19], v[118:119]
	v_pk_mul_f32 v[20:21], v[20:21], v[118:119]
	v_pk_mul_f32 v[22:23], v[22:23], v[118:119]
	v_pk_mul_f32 v[24:25], v[24:25], v[118:119]
	v_pk_mul_f32 v[26:27], v[26:27], v[118:119]
	v_pk_mul_f32 v[28:29], v[28:29], v[118:119]
	v_pk_mul_f32 v[30:31], v[30:31], v[118:119]
	v_pk_mul_f32 v[32:33], v[32:33], v[118:119]
	v_pk_fma_f32 v[76:77], v[18:19], v[34:35], v[50:51]
	v_pk_fma_f32 v[78:79], v[20:21], v[36:37], v[52:53]
	v_pk_fma_f32 v[80:81], v[22:23], v[38:39], v[54:55]
	v_pk_fma_f32 v[82:83], v[24:25], v[40:41], v[56:57]
	v_pk_fma_f32 v[84:85], v[26:27], v[42:43], v[58:59]
	v_pk_fma_f32 v[86:87], v[28:29], v[44:45], v[60:61]
	v_pk_fma_f32 v[88:89], v[30:31], v[46:47], v[62:63]
	v_pk_fma_f32 v[90:91], v[32:33], v[48:49], v[64:65]
	v_cvt_pk_bf16_f32 v92, v76, v77
	v_cvt_pk_bf16_f32 v93, v78, v79
	v_cvt_pk_bf16_f32 v94, v80, v81
	v_cvt_pk_bf16_f32 v95, v82, v83
	v_cvt_pk_bf16_f32 v96, v84, v85
	v_cvt_pk_bf16_f32 v97, v86, v87
	v_cvt_pk_bf16_f32 v98, v88, v89
	v_cvt_pk_bf16_f32 v99, v90, v91
	global_store_dwordx2 v115, v[92:93], s[2:3] offset:0 sc1
	global_store_dwordx2 v115, v[94:95], s[2:3] offset:512 sc1
	global_store_dwordx2 v115, v[96:97], s[2:3] offset:1024 sc1
	global_store_dwordx2 v115, v[98:99], s[2:3] offset:1536 sc1
	s_add_u32 s2, s2, 0x400000
	s_addc_u32 s3, s3, 0
	s_add_u32 s0, s0, 0x800000
	s_addc_u32 s1, s1, 0
	global_load_dwordx4 v[18:21], v114, s[0:1] offset:0
	global_load_dwordx4 v[22:25], v114, s[0:1] offset:1024
	global_load_dwordx4 v[26:29], v114, s[0:1] offset:2048
	global_load_dwordx4 v[30:33], v114, s[0:1] offset:3072
	s_waitcnt vmcnt(8)
; __device__ __forceinline__ void phase_ln(float* R, const float* __restrict__ g, const float* __restrict__ b, bf16_t* xbf, float samp_scale, const float* __restrict__ part, int nsplit, bool f32_all) {
;     ...
;   for (int r = gw; r < MT; r += nw) {
;     float* row = R + (size_t)r * 1024;
;     f32x4 v[4];
; #pragma unroll
;     for (int i = 0; i < 4; ++i) v[i] = *(const f32x4*)(row + i * 256 + lane * 4);
;     if (r >= MP) {
;       for (int sp = 0; sp < nsplit; ++sp) {
;         const float* prow = part + ((size_t)sp * MS + (r - MP)) * 1024;
; #pragma unroll
;         for (int i = 0; i < 4; ++i) v[i] = v[i] + *(const f32x4*)(prow + i * 256 + lane * 4);
;       }
;     }
;     float s = 0.f;
; #pragma unroll
;     for (int i = 0; i < 4; ++i) s += v[i][0] + v[i][1] + v[i][2] + v[i][3];
; #pragma unroll
;     for (int o = 32; o >= 1; o >>= 1) s += __shfl_xor(s, o);
;     const float mean = s * (1.f / 1024.f);
;     float ss = 0.f;
; #pragma unroll
;     for (int i = 0; i < 4; ++i) { v[i] = v[i] - mean; ss += v[i][0] * v[i][0] + v[i][1] * v[i][1] + v[i][2] * v[i][2] + v[i][3] * v[i][3]; }
; #pragma unroll
;     for (int o = 32; o >= 1; o >>= 1) ss += __shfl_xor(ss, o);
;     const float rstd = rsqrtf(ss * (1.f / 1024.f) + LN_EPS);
; #pragma unroll
;     for (int i = 0; i < 4; ++i) {
;       const f32x4 y = v[i] * rstd * gv[i] + bv[i];
;       if (r >= MP) *(f32x4*)(row + i * 256 + lane * 4) = y * samp_scale;
;       else if (f32_all) *(f32x4*)(row + i * 256 + lane * 4) = y;
;       if (xbf) {
;         u32x2 wv;
;         wv[0] = cvt_pk_bf16(y[0], y[1]); wv[1] = cvt_pk_bf16(y[2], y[3]);
;         *(u32x2*)(xbf + (size_t)r * 1024 + i * 256 + lane * 4) = wv;
;       }
;     }
;   }
	v_pk_add_f32 v[66:67], v[0:1], v[2:3]
	v_pk_add_f32 v[68:69], v[4:5], v[6:7]
	v_pk_add_f32 v[70:71], v[8:9], v[10:11]
	v_pk_add_f32 v[72:73], v[12:13], v[14:15]
	v_pk_add_f32 v[66:67], v[66:67], v[68:69]
	v_pk_add_f32 v[70:71], v[70:71], v[72:73]
	v_pk_add_f32 v[66:67], v[66:67], v[70:71]
	v_add_f32_e32 v66, v66, v67
	s_nop 1
	v_add_f32_dpp v66, v66, v66 row_shr:1 row_mask:0xf bank_mask:0xf bound_ctrl:1
	s_nop 1
	v_add_f32_dpp v66, v66, v66 row_shr:2 row_mask:0xf bank_mask:0xf bound_ctrl:1
	s_nop 1
	v_add_f32_dpp v66, v66, v66 row_shr:4 row_mask:0xf bank_mask:0xf bound_ctrl:1
	s_nop 1
	v_add_f32_dpp v66, v66, v66 row_shr:8 row_mask:0xf bank_mask:0xf bound_ctrl:1
	s_nop 0
	v_readlane_b32 s9, v66, 15
	v_readlane_b32 s10, v66, 31
	v_readlane_b32 s11, v66, 47
	v_readlane_b32 vcc_lo, v66, 63
	s_nop 1
	v_mov_b32_e32 v66, s9
	v_add_f32_e32 v66, s10, v66
	v_add_f32_e32 v66, s11, v66
	v_add_f32_e32 v66, vcc_lo, v66
	v_mul_f32_e32 v116, 0x3a800000, v66
	v_mov_b32_e32 v117, v116
	v_pk_add_f32 v[0:1], v[0:1], v[116:117] neg_lo:[0,1] neg_hi:[0,1]
	v_pk_add_f32 v[2:3], v[2:3], v[116:117] neg_lo:[0,1] neg_hi:[0,1]
	v_pk_add_f32 v[4:5], v[4:5], v[116:117] neg_lo:[0,1] neg_hi:[0,1]
	v_pk_add_f32 v[6:7], v[6:7], v[116:117] neg_lo:[0,1] neg_hi:[0,1]
	v_pk_add_f32 v[8:9], v[8:9], v[116:117] neg_lo:[0,1] neg_hi:[0,1]
	v_pk_add_f32 v[10:11], v[10:11], v[116:117] neg_lo:[0,1] neg_hi:[0,1]
	v_pk_add_f32 v[12:13], v[12:13], v[116:117] neg_lo:[0,1] neg_hi:[0,1]
	v_pk_add_f32 v[14:15], v[14:15], v[116:117] neg_lo:[0,1] neg_hi:[0,1]
	v_pk_mul_f32 v[66:67], v[0:1], v[0:1]
	v_pk_mul_f32 v[68:69], v[2:3], v[2:3]
	v_pk_fma_f32 v[66:67], v[4:5], v[4:5], v[66:67]
	v_pk_fma_f32 v[68:69], v[6:7], v[6:7], v[68:69]
	v_pk_fma_f32 v[66:67], v[8:9], v[8:9], v[66:67]
	v_pk_fma_f32 v[68:69], v[10:11], v[10:11], v[68:69]
	v_pk_fma_f32 v[66:67], v[12:13], v[12:13], v[66:67]
	v_pk_fma_f32 v[68:69], v[14:15], v[14:15], v[68:69]
	v_pk_add_f32 v[66:67], v[66:67], v[68:69]
	v_add_f32_e32 v66, v66, v67
	s_nop 1
	v_add_f32_dpp v66, v66, v66 row_shr:1 row_mask:0xf bank_mask:0xf bound_ctrl:1
	s_nop 1
	v_add_f32_dpp v66, v66, v66 row_shr:2 row_mask:0xf bank_mask:0xf bound_ctrl:1
	s_nop 1
	v_add_f32_dpp v66, v66, v66 row_shr:4 row_mask:0xf bank_mask:0xf bound_ctrl:1
	s_nop 1
	v_add_f32_dpp v66, v66, v66 row_shr:8 row_mask:0xf bank_mask:0xf bound_ctrl:1
	s_nop 0
	v_readlane_b32 s9, v66, 15
	v_readlane_b32 s10, v66, 31
	v_readlane_b32 s11, v66, 47
	v_readlane_b32 vcc_lo, v66, 63
	s_nop 1
	v_mov_b32_e32 v66, s9
	v_add_f32_e32 v66, s10, v66
	v_add_f32_e32 v66, s11, v66
	v_add_f32_e32 v66, vcc_lo, v66
	v_mul_f32_e32 v66, 0x3a800000, v66
	v_add_f32_e32 v66, 0x3727c5ac, v66
	v_rsq_f32_e32 v118, v66
	s_nop 0
	v_mov_b32_e32 v119, v118
	v_pk_mul_f32 v[0:1], v[0:1], v[118:119]
	v_pk_mul_f32 v[2:3], v[2:3], v[118:119]
	v_pk_mul_f32 v[4:5], v[4:5], v[118:119]
	v_pk_mul_f32 v[6:7], v[6:7], v[118:119]
	v_pk_mul_f32 v[8:9], v[8:9], v[118:119]
	v_pk_mul_f32 v[10:11], v[10:11], v[118:119]
	v_pk_mul_f32 v[12:13], v[12:13], v[118:119]
	v_pk_mul_f32 v[14:15], v[14:15], v[118:119]
	v_pk_fma_f32 v[76:77], v[0:1], v[34:35], v[50:51]
	v_pk_fma_f32 v[78:79], v[2:3], v[36:37], v[52:53]
	v_pk_fma_f32 v[80:81], v[4:5], v[38:39], v[54:55]
	v_pk_fma_f32 v[82:83], v[6:7], v[40:41], v[56:57]
	v_pk_fma_f32 v[84:85], v[8:9], v[42:43], v[58:59]
	v_pk_fma_f32 v[86:87], v[10:11], v[44:45], v[60:61]
	v_pk_fma_f32 v[88:89], v[12:13], v[46:47], v[62:63]
	v_pk_fma_f32 v[90:91], v[14:15], v[48:49], v[64:65]
	v_cvt_pk_bf16_f32 v92, v76, v77
	v_cvt_pk_bf16_f32 v93, v78, v79
	v_cvt_pk_bf16_f32 v94, v80, v81
	v_cvt_pk_bf16_f32 v95, v82, v83
	v_cvt_pk_bf16_f32 v96, v84, v85
	v_cvt_pk_bf16_f32 v97, v86, v87
	v_cvt_pk_bf16_f32 v98, v88, v89
	v_cvt_pk_bf16_f32 v99, v90, v91
	global_store_dwordx2 v115, v[92:93], s[2:3] offset:0 sc1
	global_store_dwordx2 v115, v[94:95], s[2:3] offset:512 sc1
	global_store_dwordx2 v115, v[96:97], s[2:3] offset:1024 sc1
	global_store_dwordx2 v115, v[98:99], s[2:3] offset:1536 sc1
	s_add_u32 s2, s2, 0x400000
	s_addc_u32 s3, s3, 0
	s_add_u32 s0, s0, 0x800000
	s_addc_u32 s1, s1, 0
	global_load_dwordx4 v[0:3], v114, s[0:1] offset:0
	global_load_dwordx4 v[4:7], v114, s[0:1] offset:1024
	global_load_dwordx4 v[8:11], v114, s[0:1] offset:2048
	global_load_dwordx4 v[12:15], v114, s[0:1] offset:3072
	s_waitcnt vmcnt(8)
; __device__ __forceinline__ void phase_ln(float* R, const float* __restrict__ g, const float* __restrict__ b, bf16_t* xbf, float samp_scale, const float* __restrict__ part, int nsplit, bool f32_all) {
;     ...
;   for (int r = gw; r < MT; r += nw) {
;     float* row = R + (size_t)r * 1024;
;     f32x4 v[4];
; #pragma unroll
;     for (int i = 0; i < 4; ++i) v[i] = *(const f32x4*)(row + i * 256 + lane * 4);
;     if (r >= MP) {
;       for (int sp = 0; sp < nsplit; ++sp) {
;         const float* prow = part + ((size_t)sp * MS + (r - MP)) * 1024;
; #pragma unroll
;         for (int i = 0; i < 4; ++i) v[i] = v[i] + *(const f32x4*)(prow + i * 256 + lane * 4);
;       }
;     }
;     float s = 0.f;
; #pragma unroll
;     for (int i = 0; i < 4; ++i) s += v[i][0] + v[i][1] + v[i][2] + v[i][3];
; #pragma unroll
;     for (int o = 32; o >= 1; o >>= 1) s += __shfl_xor(s, o);
;     const float mean = s * (1.f / 1024.f);
;     float ss = 0.f;
; #pragma unroll
;     for (int i = 0; i < 4; ++i) { v[i] = v[i] - mean; ss += v[i][0] * v[i][0] + v[i][1] * v[i][1] + v[i][2] * v[i][2] + v[i][3] * v[i][3]; }
; #pragma unroll
;     for (int o = 32; o >= 1; o >>= 1) ss += __shfl_xor(ss, o);
;     const float rstd = rsqrtf(ss * (1.f / 1024.f) + LN_EPS);
; #pragma unroll
;     for (int i = 0; i < 4; ++i) {
;       const f32x4 y = v[i] * rstd * gv[i] + bv[i];
;       if (r >= MP) *(f32x4*)(row + i * 256 + lane * 4) = y * samp_scale;
;       else if (f32_all) *(f32x4*)(row + i * 256 + lane * 4) = y;
;       if (xbf) {
;         u32x2 wv;
;         wv[0] = cvt_pk_bf16(y[0], y[1]); wv[1] = cvt_pk_bf16(y[2], y[3]);
;         *(u32x2*)(xbf + (size_t)r * 1024 + i * 256 + lane * 4) = wv;
;       }
;     }
	v_pk_add_f32 v[66:67], v[18:19], v[20:21]
	v_pk_add_f32 v[68:69], v[22:23], v[24:25]
	v_pk_add_f32 v[70:71], v[26:27], v[28:29]
	v_pk_add_f32 v[72:73], v[30:31], v[32:33]
	v_pk_add_f32 v[66:67], v[66:67], v[68:69]
	v_pk_add_f32 v[70:71], v[70:71], v[72:73]
	v_pk_add_f32 v[66:67], v[66:67], v[70:71]
	v_add_f32_e32 v66, v66, v67
	s_nop 1
	v_add_f32_dpp v66, v66, v66 row_shr:1 row_mask:0xf bank_mask:0xf bound_ctrl:1
	s_nop 1
	v_add_f32_dpp v66, v66, v66 row_shr:2 row_mask:0xf bank_mask:0xf bound_ctrl:1
	s_nop 1
	v_add_f32_dpp v66, v66, v66 row_shr:4 row_mask:0xf bank_mask:0xf bound_ctrl:1
	s_nop 1
	v_add_f32_dpp v66, v66, v66 row_shr:8 row_mask:0xf bank_mask:0xf bound_ctrl:1
	s_nop 0
	v_readlane_b32 s9, v66, 15
	v_readlane_b32 s10, v66, 31
	v_readlane_b32 s11, v66, 47
	v_readlane_b32 vcc_lo, v66, 63
	s_nop 1
	v_mov_b32_e32 v66, s9
	v_add_f32_e32 v66, s10, v66
	v_add_f32_e32 v66, s11, v66
	v_add_f32_e32 v66, vcc_lo, v66
	v_mul_f32_e32 v116, 0x3a800000, v66
	v_mov_b32_e32 v117, v116
	v_pk_add_f32 v[18:19], v[18:19], v[116:117] neg_lo:[0,1] neg_hi:[0,1]
	v_pk_add_f32 v[20:21], v[20:21], v[116:117] neg_lo:[0,1] neg_hi:[0,1]
	v_pk_add_f32 v[22:23], v[22:23], v[116:117] neg_lo:[0,1] neg_hi:[0,1]
	v_pk_add_f32 v[24:25], v[24:25], v[116:117] neg_lo:[0,1] neg_hi:[0,1]
	v_pk_add_f32 v[26:27], v[26:27], v[116:117] neg_lo:[0,1] neg_hi:[0,1]
	v_pk_add_f32 v[28:29], v[28:29], v[116:117] neg_lo:[0,1] neg_hi:[0,1]
	v_pk_add_f32 v[30:31], v[30:31], v[116:117] neg_lo:[0,1] neg_hi:[0,1]
	v_pk_add_f32 v[32:33], v[32:33], v[116:117] neg_lo:[0,1] neg_hi:[0,1]
	v_pk_mul_f32 v[66:67], v[18:19], v[18:19]
	v_pk_mul_f32 v[68:69], v[20:21], v[20:21]
	v_pk_fma_f32 v[66:67], v[22:23], v[22:23], v[66:67]
	v_pk_fma_f32 v[68:69], v[24:25], v[24:25], v[68:69]
	v_pk_fma_f32 v[66:67], v[26:27], v[26:27], v[66:67]
	v_pk_fma_f32 v[68:69], v[28:29], v[28:29], v[68:69]
	v_pk_fma_f32 v[66:67], v[30:31], v[30:31], v[66:67]
	v_pk_fma_f32 v[68:69], v[32:33], v[32:33], v[68:69]
	v_pk_add_f32 v[66:67], v[66:67], v[68:69]
	v_add_f32_e32 v66, v66, v67
	s_nop 1
	v_add_f32_dpp v66, v66, v66 row_shr:1 row_mask:0xf bank_mask:0xf bound_ctrl:1
	s_nop 1
	v_add_f32_dpp v66, v66, v66 row_shr:2 row_mask:0xf bank_mask:0xf bound_ctrl:1
	s_nop 1
	v_add_f32_dpp v66, v66, v66 row_shr:4 row_mask:0xf bank_mask:0xf bound_ctrl:1
	s_nop 1
	v_add_f32_dpp v66, v66, v66 row_shr:8 row_mask:0xf bank_mask:0xf bound_ctrl:1
	s_nop 0
	v_readlane_b32 s9, v66, 15
	v_readlane_b32 s10, v66, 31
	v_readlane_b32 s11, v66, 47
	v_readlane_b32 vcc_lo, v66, 63
	s_nop 1
	v_mov_b32_e32 v66, s9
	v_add_f32_e32 v66, s10, v66
	v_add_f32_e32 v66, s11, v66
	v_add_f32_e32 v66, vcc_lo, v66
	v_mul_f32_e32 v66, 0x3a800000, v66
	v_add_f32_e32 v66, 0x3727c5ac, v66
	v_rsq_f32_e32 v118, v66
	s_nop 0
	v_mov_b32_e32 v119, v118
	v_pk_mul_f32 v[18:19], v[18:19], v[118:119]
	v_pk_mul_f32 v[20:21], v[20:21], v[118:119]
	v_pk_mul_f32 v[22:23], v[22:23], v[118:119]
	v_pk_mul_f32 v[24:25], v[24:25], v[118:119]
	v_pk_mul_f32 v[26:27], v[26:27], v[118:119]
	v_pk_mul_f32 v[28:29], v[28:29], v[118:119]
	v_pk_mul_f32 v[30:31], v[30:31], v[118:119]
	v_pk_mul_f32 v[32:33], v[32:33], v[118:119]
	v_pk_fma_f32 v[76:77], v[18:19], v[34:35], v[50:51]
	v_pk_fma_f32 v[78:79], v[20:21], v[36:37], v[52:53]
	v_pk_fma_f32 v[80:81], v[22:23], v[38:39], v[54:55]
	v_pk_fma_f32 v[82:83], v[24:25], v[40:41], v[56:57]
	v_pk_fma_f32 v[84:85], v[26:27], v[42:43], v[58:59]
	v_pk_fma_f32 v[86:87], v[28:29], v[44:45], v[60:61]
	v_pk_fma_f32 v[88:89], v[30:31], v[46:47], v[62:63]
	v_pk_fma_f32 v[90:91], v[32:33], v[48:49], v[64:65]
	v_cvt_pk_bf16_f32 v92, v76, v77
	v_cvt_pk_bf16_f32 v93, v78, v79
	v_cvt_pk_bf16_f32 v94, v80, v81
	v_cvt_pk_bf16_f32 v95, v82, v83
	v_cvt_pk_bf16_f32 v96, v84, v85
	v_cvt_pk_bf16_f32 v97, v86, v87
	v_cvt_pk_bf16_f32 v98, v88, v89
	v_cvt_pk_bf16_f32 v99, v90, v91
	global_store_dwordx2 v115, v[92:93], s[2:3] offset:0 sc1
	global_store_dwordx2 v115, v[94:95], s[2:3] offset:512 sc1
	global_store_dwordx2 v115, v[96:97], s[2:3] offset:1024 sc1
	global_store_dwordx2 v115, v[98:99], s[2:3] offset:1536 sc1
	s_add_u32 s2, s2, 0x400000
	s_addc_u32 s3, s3, 0
	s_add_u32 s0, s0, 0x800000
	s_addc_u32 s1, s1, 0
	global_load_dwordx4 v[18:21], v114, s[0:1] offset:0
	global_load_dwordx4 v[22:25], v114, s[0:1] offset:1024
	global_load_dwordx4 v[26:29], v114, s[0:1] offset:2048
	global_load_dwordx4 v[30:33], v114, s[0:1] offset:3072
	s_waitcnt vmcnt(8)
; __device__ __forceinline__ void phase_ln(float* R, const float* __restrict__ g, const float* __restrict__ b, bf16_t* xbf, float samp_scale, const float* __restrict__ part, int nsplit, bool f32_all) {
;     ...
;   for (int r = gw; r < MT; r += nw) {
;     float* row = R + (size_t)r * 1024;
;     f32x4 v[4];
; #pragma unroll
;     for (int i = 0; i < 4; ++i) v[i] = *(const f32x4*)(row + i * 256 + lane * 4);
;     if (r >= MP) {
;       for (int sp = 0; sp < nsplit; ++sp) {
;         const float* prow = part + ((size_t)sp * MS + (r - MP)) * 1024;
; #pragma unroll
;         for (int i = 0; i < 4; ++i) v[i] = v[i] + *(const f32x4*)(prow + i * 256 + lane * 4);
;       }
;     }
;     float s = 0.f;
; #pragma unroll
;     for (int i = 0; i < 4; ++i) s += v[i][0] + v[i][1] + v[i][2] + v[i][3];
; #pragma unroll
;     for (int o = 32; o >= 1; o >>= 1) s += __shfl_xor(s, o);
;     const float mean = s * (1.f / 1024.f);
;     float ss = 0.f;
; #pragma unroll
;     for (int i = 0; i < 4; ++i) { v[i] = v[i] - mean; ss += v[i][0] * v[i][0] + v[i][1] * v[i][1] + v[i][2] * v[i][2] + v[i][3] * v[i][3]; }
; #pragma unroll
;     for (int o = 32; o >= 1; o >>= 1) ss += __shfl_xor(ss, o);
;     const float rstd = rsqrtf(ss * (1.f / 1024.f) + LN_EPS);
; #pragma unroll
;     for (int i = 0; i < 4; ++i) {
;       const f32x4 y = v[i] * rstd * gv[i] + bv[i];
;       if (r >= MP) *(f32x4*)(row + i * 256 + lane * 4) = y * samp_scale;
;       else if (f32_all) *(f32x4*)(row + i * 256 + lane * 4) = y;
;       if (xbf) {
;         u32x2 wv;
;         wv[0] = cvt_pk_bf16(y[0], y[1]); wv[1] = cvt_pk_bf16(y[2], y[3]);
;         *(u32x2*)(xbf + (size_t)r * 1024 + i * 256 + lane * 4) = wv;
;       }
;     }
	v_pk_add_f32 v[66:67], v[0:1], v[2:3]
	v_pk_add_f32 v[68:69], v[4:5], v[6:7]
	v_pk_add_f32 v[70:71], v[8:9], v[10:11]
	v_pk_add_f32 v[72:73], v[12:13], v[14:15]
	v_pk_add_f32 v[66:67], v[66:67], v[68:69]
	v_pk_add_f32 v[70:71], v[70:71], v[72:73]
	v_pk_add_f32 v[66:67], v[66:67], v[70:71]
	v_add_f32_e32 v66, v66, v67
	s_nop 1
	v_add_f32_dpp v66, v66, v66 row_shr:1 row_mask:0xf bank_mask:0xf bound_ctrl:1
	s_nop 1
	v_add_f32_dpp v66, v66, v66 row_shr:2 row_mask:0xf bank_mask:0xf bound_ctrl:1
	s_nop 1
	v_add_f32_dpp v66, v66, v66 row_shr:4 row_mask:0xf bank_mask:0xf bound_ctrl:1
	s_nop 1
	v_add_f32_dpp v66, v66, v66 row_shr:8 row_mask:0xf bank_mask:0xf bound_ctrl:1
	s_nop 0
	v_readlane_b32 s9, v66, 15
	v_readlane_b32 s10, v66, 31
	v_readlane_b32 s11, v66, 47
	v_readlane_b32 vcc_lo, v66, 63
	s_nop 1
	v_mov_b32_e32 v66, s9
	v_add_f32_e32 v66, s10, v66
	v_add_f32_e32 v66, s11, v66
	v_add_f32_e32 v66, vcc_lo, v66
	v_mul_f32_e32 v116, 0x3a800000, v66
	v_mov_b32_e32 v117, v116
	v_pk_add_f32 v[0:1], v[0:1], v[116:117] neg_lo:[0,1] neg_hi:[0,1]
	v_pk_add_f32 v[2:3], v[2:3], v[116:117] neg_lo:[0,1] neg_hi:[0,1]
	v_pk_add_f32 v[4:5], v[4:5], v[116:117] neg_lo:[0,1] neg_hi:[0,1]
	v_pk_add_f32 v[6:7], v[6:7], v[116:117] neg_lo:[0,1] neg_hi:[0,1]
	v_pk_add_f32 v[8:9], v[8:9], v[116:117] neg_lo:[0,1] neg_hi:[0,1]
	v_pk_add_f32 v[10:11], v[10:11], v[116:117] neg_lo:[0,1] neg_hi:[0,1]
	v_pk_add_f32 v[12:13], v[12:13], v[116:117] neg_lo:[0,1] neg_hi:[0,1]
	v_pk_add_f32 v[14:15], v[14:15], v[116:117] neg_lo:[0,1] neg_hi:[0,1]
	v_pk_mul_f32 v[66:67], v[0:1], v[0:1]
	v_pk_mul_f32 v[68:69], v[2:3], v[2:3]
	v_pk_fma_f32 v[66:67], v[4:5], v[4:5], v[66:67]
	v_pk_fma_f32 v[68:69], v[6:7], v[6:7], v[68:69]
	v_pk_fma_f32 v[66:67], v[8:9], v[8:9], v[66:67]
	v_pk_fma_f32 v[68:69], v[10:11], v[10:11], v[68:69]
	v_pk_fma_f32 v[66:67], v[12:13], v[12:13], v[66:67]
	v_pk_fma_f32 v[68:69], v[14:15], v[14:15], v[68:69]
	v_pk_add_f32 v[66:67], v[66:67], v[68:69]
	v_add_f32_e32 v66, v66, v67
	s_nop 1
	v_add_f32_dpp v66, v66, v66 row_shr:1 row_mask:0xf bank_mask:0xf bound_ctrl:1
	s_nop 1
	v_add_f32_dpp v66, v66, v66 row_shr:2 row_mask:0xf bank_mask:0xf bound_ctrl:1
	s_nop 1
	v_add_f32_dpp v66, v66, v66 row_shr:4 row_mask:0xf bank_mask:0xf bound_ctrl:1
	s_nop 1
	v_add_f32_dpp v66, v66, v66 row_shr:8 row_mask:0xf bank_mask:0xf bound_ctrl:1
	s_nop 0
	v_readlane_b32 s9, v66, 15
	v_readlane_b32 s10, v66, 31
	v_readlane_b32 s11, v66, 47
	v_readlane_b32 vcc_lo, v66, 63
	s_nop 1
	v_mov_b32_e32 v66, s9
	v_add_f32_e32 v66, s10, v66
	v_add_f32_e32 v66, s11, v66
	v_add_f32_e32 v66, vcc_lo, v66
	v_mul_f32_e32 v66, 0x3a800000, v66
	v_add_f32_e32 v66, 0x3727c5ac, v66
	v_rsq_f32_e32 v118, v66
	s_nop 0
	v_mov_b32_e32 v119, v118
	v_pk_mul_f32 v[0:1], v[0:1], v[118:119]
	v_pk_mul_f32 v[2:3], v[2:3], v[118:119]
	v_pk_mul_f32 v[4:5], v[4:5], v[118:119]
	v_pk_mul_f32 v[6:7], v[6:7], v[118:119]
	v_pk_mul_f32 v[8:9], v[8:9], v[118:119]
	v_pk_mul_f32 v[10:11], v[10:11], v[118:119]
	v_pk_mul_f32 v[12:13], v[12:13], v[118:119]
	v_pk_mul_f32 v[14:15], v[14:15], v[118:119]
	v_pk_fma_f32 v[76:77], v[0:1], v[34:35], v[50:51]
	v_pk_fma_f32 v[78:79], v[2:3], v[36:37], v[52:53]
	v_pk_fma_f32 v[80:81], v[4:5], v[38:39], v[54:55]
	v_pk_fma_f32 v[82:83], v[6:7], v[40:41], v[56:57]
	v_pk_fma_f32 v[84:85], v[8:9], v[42:43], v[58:59]
	v_pk_fma_f32 v[86:87], v[10:11], v[44:45], v[60:61]
	v_pk_fma_f32 v[88:89], v[12:13], v[46:47], v[62:63]
	v_pk_fma_f32 v[90:91], v[14:15], v[48:49], v[64:65]
	v_cvt_pk_bf16_f32 v92, v76, v77
	v_cvt_pk_bf16_f32 v93, v78, v79
	v_cvt_pk_bf16_f32 v94, v80, v81
	v_cvt_pk_bf16_f32 v95, v82, v83
	v_cvt_pk_bf16_f32 v96, v84, v85
	v_cvt_pk_bf16_f32 v97, v86, v87
	v_cvt_pk_bf16_f32 v98, v88, v89
	v_cvt_pk_bf16_f32 v99, v90, v91
	global_store_dwordx2 v115, v[92:93], s[2:3] offset:0 sc1
	global_store_dwordx2 v115, v[94:95], s[2:3] offset:512 sc1
	global_store_dwordx2 v115, v[96:97], s[2:3] offset:1024 sc1
	global_store_dwordx2 v115, v[98:99], s[2:3] offset:1536 sc1
	s_add_u32 s2, s2, 0x400000
	s_addc_u32 s3, s3, 0
	s_add_u32 s0, s0, 0x800000
	s_addc_u32 s1, s1, 0
	global_load_dwordx4 v[0:3], v114, s[0:1] offset:0
	global_load_dwordx4 v[4:7], v114, s[0:1] offset:1024
	global_load_dwordx4 v[8:11], v114, s[0:1] offset:2048
	global_load_dwordx4 v[12:15], v114, s[0:1] offset:3072
	s_waitcnt vmcnt(8)
; __device__ __forceinline__ void phase_ln(float* R, const float* __restrict__ g, const float* __restrict__ b, bf16_t* xbf, float samp_scale, const float* __restrict__ part, int nsplit, bool f32_all) {
;     ...
;   for (int r = gw; r < MT; r += nw) {
;     float* row = R + (size_t)r * 1024;
;     f32x4 v[4];
; #pragma unroll
;     for (int i = 0; i < 4; ++i) v[i] = *(const f32x4*)(row + i * 256 + lane * 4);
;     if (r >= MP) {
;       for (int sp = 0; sp < nsplit; ++sp) {
;         const float* prow = part + ((size_t)sp * MS + (r - MP)) * 1024;
; #pragma unroll
;         for (int i = 0; i < 4; ++i) v[i] = v[i] + *(const f32x4*)(prow + i * 256 + lane * 4);
;       }
;     }
;     float s = 0.f;
; #pragma unroll
;     for (int i = 0; i < 4; ++i) s += v[i][0] + v[i][1] + v[i][2] + v[i][3];
; #pragma unroll
;     for (int o = 32; o >= 1; o >>= 1) s += __shfl_xor(s, o);
;     const float mean = s * (1.f / 1024.f);
;     float ss = 0.f;
; #pragma unroll
;     for (int i = 0; i < 4; ++i) { v[i] = v[i] - mean; ss += v[i][0] * v[i][0] + v[i][1] * v[i][1] + v[i][2] * v[i][2] + v[i][3] * v[i][3]; }
; #pragma unroll
;     for (int o = 32; o >= 1; o >>= 1) ss += __shfl_xor(ss, o);
;     const float rstd = rsqrtf(ss * (1.f / 1024.f) + LN_EPS);
; #pragma unroll
;     for (int i = 0; i < 4; ++i) {
;       const f32x4 y = v[i] * rstd * gv[i] + bv[i];
;       if (r >= MP) *(f32x4*)(row + i * 256 + lane * 4) = y * samp_scale;
;       else if (f32_all) *(f32x4*)(row + i * 256 + lane * 4) = y;
;       if (xbf) {
;         u32x2 wv;
;         wv[0] = cvt_pk_bf16(y[0], y[1]); wv[1] = cvt_pk_bf16(y[2], y[3]);
;         *(u32x2*)(xbf + (size_t)r * 1024 + i * 256 + lane * 4) = wv;
;       }
;     }
	v_pk_add_f32 v[66:67], v[18:19], v[20:21]
	v_pk_add_f32 v[68:69], v[22:23], v[24:25]
	v_pk_add_f32 v[70:71], v[26:27], v[28:29]
	v_pk_add_f32 v[72:73], v[30:31], v[32:33]
	v_pk_add_f32 v[66:67], v[66:67], v[68:69]
	v_pk_add_f32 v[70:71], v[70:71], v[72:73]
	v_pk_add_f32 v[66:67], v[66:67], v[70:71]
	v_add_f32_e32 v66, v66, v67
	s_nop 1
	v_add_f32_dpp v66, v66, v66 row_shr:1 row_mask:0xf bank_mask:0xf bound_ctrl:1
	s_nop 1
	v_add_f32_dpp v66, v66, v66 row_shr:2 row_mask:0xf bank_mask:0xf bound_ctrl:1
	s_nop 1
	v_add_f32_dpp v66, v66, v66 row_shr:4 row_mask:0xf bank_mask:0xf bound_ctrl:1
	s_nop 1
	v_add_f32_dpp v66, v66, v66 row_shr:8 row_mask:0xf bank_mask:0xf bound_ctrl:1
	s_nop 0
	v_readlane_b32 s9, v66, 15
	v_readlane_b32 s10, v66, 31
	v_readlane_b32 s11, v66, 47
	v_readlane_b32 vcc_lo, v66, 63
	s_nop 1
	v_mov_b32_e32 v66, s9
	v_add_f32_e32 v66, s10, v66
	v_add_f32_e32 v66, s11, v66
	v_add_f32_e32 v66, vcc_lo, v66
	v_mul_f32_e32 v116, 0x3a800000, v66
	v_mov_b32_e32 v117, v116
	v_pk_add_f32 v[18:19], v[18:19], v[116:117] neg_lo:[0,1] neg_hi:[0,1]
	v_pk_add_f32 v[20:21], v[20:21], v[116:117] neg_lo:[0,1] neg_hi:[0,1]
	v_pk_add_f32 v[22:23], v[22:23], v[116:117] neg_lo:[0,1] neg_hi:[0,1]
	v_pk_add_f32 v[24:25], v[24:25], v[116:117] neg_lo:[0,1] neg_hi:[0,1]
	v_pk_add_f32 v[26:27], v[26:27], v[116:117] neg_lo:[0,1] neg_hi:[0,1]
	v_pk_add_f32 v[28:29], v[28:29], v[116:117] neg_lo:[0,1] neg_hi:[0,1]
	v_pk_add_f32 v[30:31], v[30:31], v[116:117] neg_lo:[0,1] neg_hi:[0,1]
	v_pk_add_f32 v[32:33], v[32:33], v[116:117] neg_lo:[0,1] neg_hi:[0,1]
	v_pk_mul_f32 v[66:67], v[18:19], v[18:19]
	v_pk_mul_f32 v[68:69], v[20:21], v[20:21]
	v_pk_fma_f32 v[66:67], v[22:23], v[22:23], v[66:67]
	v_pk_fma_f32 v[68:69], v[24:25], v[24:25], v[68:69]
	v_pk_fma_f32 v[66:67], v[26:27], v[26:27], v[66:67]
	v_pk_fma_f32 v[68:69], v[28:29], v[28:29], v[68:69]
	v_pk_fma_f32 v[66:67], v[30:31], v[30:31], v[66:67]
	v_pk_fma_f32 v[68:69], v[32:33], v[32:33], v[68:69]
	v_pk_add_f32 v[66:67], v[66:67], v[68:69]
	v_add_f32_e32 v66, v66, v67
	s_nop 1
	v_add_f32_dpp v66, v66, v66 row_shr:1 row_mask:0xf bank_mask:0xf bound_ctrl:1
	s_nop 1
	v_add_f32_dpp v66, v66, v66 row_shr:2 row_mask:0xf bank_mask:0xf bound_ctrl:1
	s_nop 1
	v_add_f32_dpp v66, v66, v66 row_shr:4 row_mask:0xf bank_mask:0xf bound_ctrl:1
	s_nop 1
	v_add_f32_dpp v66, v66, v66 row_shr:8 row_mask:0xf bank_mask:0xf bound_ctrl:1
	s_nop 0
	v_readlane_b32 s9, v66, 15
	v_readlane_b32 s10, v66, 31
	v_readlane_b32 s11, v66, 47
	v_readlane_b32 vcc_lo, v66, 63
	s_nop 1
	v_mov_b32_e32 v66, s9
	v_add_f32_e32 v66, s10, v66
	v_add_f32_e32 v66, s11, v66
	v_add_f32_e32 v66, vcc_lo, v66
	v_mul_f32_e32 v66, 0x3a800000, v66
	v_add_f32_e32 v66, 0x3727c5ac, v66
	v_rsq_f32_e32 v118, v66
	s_nop 0
	v_mov_b32_e32 v119, v118
	v_pk_mul_f32 v[18:19], v[18:19], v[118:119]
	v_pk_mul_f32 v[20:21], v[20:21], v[118:119]
	v_pk_mul_f32 v[22:23], v[22:23], v[118:119]
	v_pk_mul_f32 v[24:25], v[24:25], v[118:119]
	v_pk_mul_f32 v[26:27], v[26:27], v[118:119]
	v_pk_mul_f32 v[28:29], v[28:29], v[118:119]
	v_pk_mul_f32 v[30:31], v[30:31], v[118:119]
	v_pk_mul_f32 v[32:33], v[32:33], v[118:119]
	v_pk_fma_f32 v[76:77], v[18:19], v[34:35], v[50:51]
	v_pk_fma_f32 v[78:79], v[20:21], v[36:37], v[52:53]
	v_pk_fma_f32 v[80:81], v[22:23], v[38:39], v[54:55]
	v_pk_fma_f32 v[82:83], v[24:25], v[40:41], v[56:57]
	v_pk_fma_f32 v[84:85], v[26:27], v[42:43], v[58:59]
	v_pk_fma_f32 v[86:87], v[28:29], v[44:45], v[60:61]
	v_pk_fma_f32 v[88:89], v[30:31], v[46:47], v[62:63]
	v_pk_fma_f32 v[90:91], v[32:33], v[48:49], v[64:65]
	v_cvt_pk_bf16_f32 v92, v76, v77
	v_cvt_pk_bf16_f32 v93, v78, v79
	v_cvt_pk_bf16_f32 v94, v80, v81
	v_cvt_pk_bf16_f32 v95, v82, v83
	v_cvt_pk_bf16_f32 v96, v84, v85
	v_cvt_pk_bf16_f32 v97, v86, v87
	v_cvt_pk_bf16_f32 v98, v88, v89
	v_cvt_pk_bf16_f32 v99, v90, v91
	global_store_dwordx2 v115, v[92:93], s[2:3] offset:0 sc1
	global_store_dwordx2 v115, v[94:95], s[2:3] offset:512 sc1
	global_store_dwordx2 v115, v[96:97], s[2:3] offset:1024 sc1
	global_store_dwordx2 v115, v[98:99], s[2:3] offset:1536 sc1
	s_add_u32 s2, s2, 0x400000
	s_addc_u32 s3, s3, 0
	s_add_u32 s0, s0, 0x800000
	s_addc_u32 s1, s1, 0
	global_load_dwordx4 v[18:21], v114, s[0:1] offset:0
	global_load_dwordx4 v[22:25], v114, s[0:1] offset:1024
	global_load_dwordx4 v[26:29], v114, s[0:1] offset:2048
	global_load_dwordx4 v[30:33], v114, s[0:1] offset:3072
	s_waitcnt vmcnt(8)
; __device__ __forceinline__ void phase_ln(float* R, const float* __restrict__ g, const float* __restrict__ b, bf16_t* xbf, float samp_scale, const float* __restrict__ part, int nsplit, bool f32_all) {
;     ...
;   for (int r = gw; r < MT; r += nw) {
;     float* row = R + (size_t)r * 1024;
;     f32x4 v[4];
; #pragma unroll
;     for (int i = 0; i < 4; ++i) v[i] = *(const f32x4*)(row + i * 256 + lane * 4);
;     if (r >= MP) {
;       for (int sp = 0; sp < nsplit; ++sp) {
;         const float* prow = part + ((size_t)sp * MS + (r - MP)) * 1024;
; #pragma unroll
;         for (int i = 0; i < 4; ++i) v[i] = v[i] + *(const f32x4*)(prow + i * 256 + lane * 4);
;       }
;     }
;     float s = 0.f;
; #pragma unroll
;     for (int i = 0; i < 4; ++i) s += v[i][0] + v[i][1] + v[i][2] + v[i][3];
; #pragma unroll
;     for (int o = 32; o >= 1; o >>= 1) s += __shfl_xor(s, o);
;     const float mean = s * (1.f / 1024.f);
;     float ss = 0.f;
; #pragma unroll
;     for (int i = 0; i < 4; ++i) { v[i] = v[i] - mean; ss += v[i][0] * v[i][0] + v[i][1] * v[i][1] + v[i][2] * v[i][2] + v[i][3] * v[i][3]; }
; #pragma unroll
;     for (int o = 32; o >= 1; o >>= 1) ss += __shfl_xor(ss, o);
;     const float rstd = rsqrtf(ss * (1.f / 1024.f) + LN_EPS);
; #pragma unroll
;     for (int i = 0; i < 4; ++i) {
;       const f32x4 y = v[i] * rstd * gv[i] + bv[i];
;       if (r >= MP) *(f32x4*)(row + i * 256 + lane * 4) = y * samp_scale;
;       else if (f32_all) *(f32x4*)(row + i * 256 + lane * 4) = y;
;       if (xbf) {
;         u32x2 wv;
;         wv[0] = cvt_pk_bf16(y[0], y[1]); wv[1] = cvt_pk_bf16(y[2], y[3]);
;         *(u32x2*)(xbf + (size_t)r * 1024 + i * 256 + lane * 4) = wv;
;       }
;     }
	v_pk_add_f32 v[66:67], v[0:1], v[2:3]
	v_pk_add_f32 v[68:69], v[4:5], v[6:7]
	v_pk_add_f32 v[70:71], v[8:9], v[10:11]
	v_pk_add_f32 v[72:73], v[12:13], v[14:15]
	v_pk_add_f32 v[66:67], v[66:67], v[68:69]
	v_pk_add_f32 v[70:71], v[70:71], v[72:73]
	v_pk_add_f32 v[66:67], v[66:67], v[70:71]
	v_add_f32_e32 v66, v66, v67
	s_nop 1
	v_add_f32_dpp v66, v66, v66 row_shr:1 row_mask:0xf bank_mask:0xf bound_ctrl:1
	s_nop 1
	v_add_f32_dpp v66, v66, v66 row_shr:2 row_mask:0xf bank_mask:0xf bound_ctrl:1
	s_nop 1
	v_add_f32_dpp v66, v66, v66 row_shr:4 row_mask:0xf bank_mask:0xf bound_ctrl:1
	s_nop 1
	v_add_f32_dpp v66, v66, v66 row_shr:8 row_mask:0xf bank_mask:0xf bound_ctrl:1
	s_nop 0
	v_readlane_b32 s9, v66, 15
	v_readlane_b32 s10, v66, 31
	v_readlane_b32 s11, v66, 47
	v_readlane_b32 vcc_lo, v66, 63
	s_nop 1
	v_mov_b32_e32 v66, s9
	v_add_f32_e32 v66, s10, v66
	v_add_f32_e32 v66, s11, v66
	v_add_f32_e32 v66, vcc_lo, v66
	v_mul_f32_e32 v116, 0x3a800000, v66
	v_mov_b32_e32 v117, v116
	v_pk_add_f32 v[0:1], v[0:1], v[116:117] neg_lo:[0,1] neg_hi:[0,1]
	v_pk_add_f32 v[2:3], v[2:3], v[116:117] neg_lo:[0,1] neg_hi:[0,1]
	v_pk_add_f32 v[4:5], v[4:5], v[116:117] neg_lo:[0,1] neg_hi:[0,1]
	v_pk_add_f32 v[6:7], v[6:7], v[116:117] neg_lo:[0,1] neg_hi:[0,1]
	v_pk_add_f32 v[8:9], v[8:9], v[116:117] neg_lo:[0,1] neg_hi:[0,1]
	v_pk_add_f32 v[10:11], v[10:11], v[116:117] neg_lo:[0,1] neg_hi:[0,1]
	v_pk_add_f32 v[12:13], v[12:13], v[116:117] neg_lo:[0,1] neg_hi:[0,1]
	v_pk_add_f32 v[14:15], v[14:15], v[116:117] neg_lo:[0,1] neg_hi:[0,1]
	v_pk_mul_f32 v[66:67], v[0:1], v[0:1]
	v_pk_mul_f32 v[68:69], v[2:3], v[2:3]
	v_pk_fma_f32 v[66:67], v[4:5], v[4:5], v[66:67]
	v_pk_fma_f32 v[68:69], v[6:7], v[6:7], v[68:69]
	v_pk_fma_f32 v[66:67], v[8:9], v[8:9], v[66:67]
	v_pk_fma_f32 v[68:69], v[10:11], v[10:11], v[68:69]
	v_pk_fma_f32 v[66:67], v[12:13], v[12:13], v[66:67]
	v_pk_fma_f32 v[68:69], v[14:15], v[14:15], v[68:69]
	v_pk_add_f32 v[66:67], v[66:67], v[68:69]
	v_add_f32_e32 v66, v66, v67
	s_nop 1
	v_add_f32_dpp v66, v66, v66 row_shr:1 row_mask:0xf bank_mask:0xf bound_ctrl:1
	s_nop 1
	v_add_f32_dpp v66, v66, v66 row_shr:2 row_mask:0xf bank_mask:0xf bound_ctrl:1
	s_nop 1
	v_add_f32_dpp v66, v66, v66 row_shr:4 row_mask:0xf bank_mask:0xf bound_ctrl:1
	s_nop 1
	v_add_f32_dpp v66, v66, v66 row_shr:8 row_mask:0xf bank_mask:0xf bound_ctrl:1
	s_nop 0
	v_readlane_b32 s9, v66, 15
	v_readlane_b32 s10, v66, 31
	v_readlane_b32 s11, v66, 47
	v_readlane_b32 vcc_lo, v66, 63
	s_nop 1
	v_mov_b32_e32 v66, s9
	v_add_f32_e32 v66, s10, v66
	v_add_f32_e32 v66, s11, v66
	v_add_f32_e32 v66, vcc_lo, v66
	v_mul_f32_e32 v66, 0x3a800000, v66
	v_add_f32_e32 v66, 0x3727c5ac, v66
	v_rsq_f32_e32 v118, v66
	s_nop 0
	v_mov_b32_e32 v119, v118
	v_pk_mul_f32 v[0:1], v[0:1], v[118:119]
	v_pk_mul_f32 v[2:3], v[2:3], v[118:119]
	v_pk_mul_f32 v[4:5], v[4:5], v[118:119]
	v_pk_mul_f32 v[6:7], v[6:7], v[118:119]
	v_pk_mul_f32 v[8:9], v[8:9], v[118:119]
	v_pk_mul_f32 v[10:11], v[10:11], v[118:119]
	v_pk_mul_f32 v[12:13], v[12:13], v[118:119]
	v_pk_mul_f32 v[14:15], v[14:15], v[118:119]
	v_pk_fma_f32 v[76:77], v[0:1], v[34:35], v[50:51]
	v_pk_fma_f32 v[78:79], v[2:3], v[36:37], v[52:53]
	v_pk_fma_f32 v[80:81], v[4:5], v[38:39], v[54:55]
	v_pk_fma_f32 v[82:83], v[6:7], v[40:41], v[56:57]
	v_pk_fma_f32 v[84:85], v[8:9], v[42:43], v[58:59]
	v_pk_fma_f32 v[86:87], v[10:11], v[44:45], v[60:61]
	v_pk_fma_f32 v[88:89], v[12:13], v[46:47], v[62:63]
	v_pk_fma_f32 v[90:91], v[14:15], v[48:49], v[64:65]
	v_cvt_pk_bf16_f32 v92, v76, v77
	v_cvt_pk_bf16_f32 v93, v78, v79
	v_cvt_pk_bf16_f32 v94, v80, v81
	v_cvt_pk_bf16_f32 v95, v82, v83
	v_cvt_pk_bf16_f32 v96, v84, v85
	v_cvt_pk_bf16_f32 v97, v86, v87
	v_cvt_pk_bf16_f32 v98, v88, v89
	v_cvt_pk_bf16_f32 v99, v90, v91
	global_store_dwordx2 v115, v[92:93], s[2:3] offset:0 sc1
	global_store_dwordx2 v115, v[94:95], s[2:3] offset:512 sc1
	global_store_dwordx2 v115, v[96:97], s[2:3] offset:1024 sc1
	global_store_dwordx2 v115, v[98:99], s[2:3] offset:1536 sc1
	s_add_u32 s2, s2, 0x400000
	s_addc_u32 s3, s3, 0
	s_add_u32 s0, s0, 0x800000
	s_addc_u32 s1, s1, 0
	global_load_dwordx4 v[0:3], v114, s[0:1] offset:0
	global_load_dwordx4 v[4:7], v114, s[0:1] offset:1024
	global_load_dwordx4 v[8:11], v114, s[0:1] offset:2048
	global_load_dwordx4 v[12:15], v114, s[0:1] offset:3072
	s_waitcnt vmcnt(8)
; __device__ __forceinline__ void phase_ln(float* R, const float* __restrict__ g, const float* __restrict__ b, bf16_t* xbf, float samp_scale, const float* __restrict__ part, int nsplit, bool f32_all) {
;     ...
;   for (int r = gw; r < MT; r += nw) {
;     float* row = R + (size_t)r * 1024;
;     f32x4 v[4];
; #pragma unroll
;     for (int i = 0; i < 4; ++i) v[i] = *(const f32x4*)(row + i * 256 + lane * 4);
;     if (r >= MP) {
;       for (int sp = 0; sp < nsplit; ++sp) {
;         const float* prow = part + ((size_t)sp * MS + (r - MP)) * 1024;
; #pragma unroll
;         for (int i = 0; i < 4; ++i) v[i] = v[i] + *(const f32x4*)(prow + i * 256 + lane * 4);
;       }
;     }
;     float s = 0.f;
; #pragma unroll
;     for (int i = 0; i < 4; ++i) s += v[i][0] + v[i][1] + v[i][2] + v[i][3];
; #pragma unroll
;     for (int o = 32; o >= 1; o >>= 1) s += __shfl_xor(s, o);
;     const float mean = s * (1.f / 1024.f);
;     float ss = 0.f;
; #pragma unroll
;     for (int i = 0; i < 4; ++i) { v[i] = v[i] - mean; ss += v[i][0] * v[i][0] + v[i][1] * v[i][1] + v[i][2] * v[i][2] + v[i][3] * v[i][3]; }
; #pragma unroll
;     for (int o = 32; o >= 1; o >>= 1) ss += __shfl_xor(ss, o);
;     const float rstd = rsqrtf(ss * (1.f / 1024.f) + LN_EPS);
; #pragma unroll
;     for (int i = 0; i < 4; ++i) {
;       const f32x4 y = v[i] * rstd * gv[i] + bv[i];
;       if (r >= MP) *(f32x4*)(row + i * 256 + lane * 4) = y * samp_scale;
;       else if (f32_all) *(f32x4*)(row + i * 256 + lane * 4) = y;
;       if (xbf) {
;         u32x2 wv;
;         wv[0] = cvt_pk_bf16(y[0], y[1]); wv[1] = cvt_pk_bf16(y[2], y[3]);
;         *(u32x2*)(xbf + (size_t)r * 1024 + i * 256 + lane * 4) = wv;
;       }
;     }
	v_pk_add_f32 v[66:67], v[18:19], v[20:21]
	v_pk_add_f32 v[68:69], v[22:23], v[24:25]
	v_pk_add_f32 v[70:71], v[26:27], v[28:29]
	v_pk_add_f32 v[72:73], v[30:31], v[32:33]
	v_pk_add_f32 v[66:67], v[66:67], v[68:69]
	v_pk_add_f32 v[70:71], v[70:71], v[72:73]
	v_pk_add_f32 v[66:67], v[66:67], v[70:71]
	v_add_f32_e32 v66, v66, v67
	s_nop 1
	v_add_f32_dpp v66, v66, v66 row_shr:1 row_mask:0xf bank_mask:0xf bound_ctrl:1
	s_nop 1
	v_add_f32_dpp v66, v66, v66 row_shr:2 row_mask:0xf bank_mask:0xf bound_ctrl:1
	s_nop 1
	v_add_f32_dpp v66, v66, v66 row_shr:4 row_mask:0xf bank_mask:0xf bound_ctrl:1
	s_nop 1
	v_add_f32_dpp v66, v66, v66 row_shr:8 row_mask:0xf bank_mask:0xf bound_ctrl:1
	s_nop 0
	v_readlane_b32 s9, v66, 15
	v_readlane_b32 s10, v66, 31
	v_readlane_b32 s11, v66, 47
	v_readlane_b32 vcc_lo, v66, 63
	s_nop 1
	v_mov_b32_e32 v66, s9
	v_add_f32_e32 v66, s10, v66
	v_add_f32_e32 v66, s11, v66
	v_add_f32_e32 v66, vcc_lo, v66
	v_mul_f32_e32 v116, 0x3a800000, v66
	v_mov_b32_e32 v117, v116
	v_pk_add_f32 v[18:19], v[18:19], v[116:117] neg_lo:[0,1] neg_hi:[0,1]
	v_pk_add_f32 v[20:21], v[20:21], v[116:117] neg_lo:[0,1] neg_hi:[0,1]
	v_pk_add_f32 v[22:23], v[22:23], v[116:117] neg_lo:[0,1] neg_hi:[0,1]
	v_pk_add_f32 v[24:25], v[24:25], v[116:117] neg_lo:[0,1] neg_hi:[0,1]
	v_pk_add_f32 v[26:27], v[26:27], v[116:117] neg_lo:[0,1] neg_hi:[0,1]
	v_pk_add_f32 v[28:29], v[28:29], v[116:117] neg_lo:[0,1] neg_hi:[0,1]
	v_pk_add_f32 v[30:31], v[30:31], v[116:117] neg_lo:[0,1] neg_hi:[0,1]
	v_pk_add_f32 v[32:33], v[32:33], v[116:117] neg_lo:[0,1] neg_hi:[0,1]
	v_pk_mul_f32 v[66:67], v[18:19], v[18:19]
	v_pk_mul_f32 v[68:69], v[20:21], v[20:21]
	v_pk_fma_f32 v[66:67], v[22:23], v[22:23], v[66:67]
	v_pk_fma_f32 v[68:69], v[24:25], v[24:25], v[68:69]
	v_pk_fma_f32 v[66:67], v[26:27], v[26:27], v[66:67]
	v_pk_fma_f32 v[68:69], v[28:29], v[28:29], v[68:69]
	v_pk_fma_f32 v[66:67], v[30:31], v[30:31], v[66:67]
	v_pk_fma_f32 v[68:69], v[32:33], v[32:33], v[68:69]
	v_pk_add_f32 v[66:67], v[66:67], v[68:69]
	v_add_f32_e32 v66, v66, v67
	s_nop 1
	v_add_f32_dpp v66, v66, v66 row_shr:1 row_mask:0xf bank_mask:0xf bound_ctrl:1
	s_nop 1
	v_add_f32_dpp v66, v66, v66 row_shr:2 row_mask:0xf bank_mask:0xf bound_ctrl:1
	s_nop 1
	v_add_f32_dpp v66, v66, v66 row_shr:4 row_mask:0xf bank_mask:0xf bound_ctrl:1
	s_nop 1
	v_add_f32_dpp v66, v66, v66 row_shr:8 row_mask:0xf bank_mask:0xf bound_ctrl:1
	s_nop 0
	v_readlane_b32 s9, v66, 15
	v_readlane_b32 s10, v66, 31
	v_readlane_b32 s11, v66, 47
	v_readlane_b32 vcc_lo, v66, 63
	s_nop 1
	v_mov_b32_e32 v66, s9
	v_add_f32_e32 v66, s10, v66
	v_add_f32_e32 v66, s11, v66
	v_add_f32_e32 v66, vcc_lo, v66
	v_mul_f32_e32 v66, 0x3a800000, v66
	v_add_f32_e32 v66, 0x3727c5ac, v66
	v_rsq_f32_e32 v118, v66
	s_nop 0
	v_mov_b32_e32 v119, v118
	v_pk_mul_f32 v[18:19], v[18:19], v[118:119]
	v_pk_mul_f32 v[20:21], v[20:21], v[118:119]
	v_pk_mul_f32 v[22:23], v[22:23], v[118:119]
	v_pk_mul_f32 v[24:25], v[24:25], v[118:119]
	v_pk_mul_f32 v[26:27], v[26:27], v[118:119]
	v_pk_mul_f32 v[28:29], v[28:29], v[118:119]
	v_pk_mul_f32 v[30:31], v[30:31], v[118:119]
	v_pk_mul_f32 v[32:33], v[32:33], v[118:119]
	v_pk_fma_f32 v[76:77], v[18:19], v[34:35], v[50:51]
	v_pk_fma_f32 v[78:79], v[20:21], v[36:37], v[52:53]
	v_pk_fma_f32 v[80:81], v[22:23], v[38:39], v[54:55]
	v_pk_fma_f32 v[82:83], v[24:25], v[40:41], v[56:57]
	v_pk_fma_f32 v[84:85], v[26:27], v[42:43], v[58:59]
	v_pk_fma_f32 v[86:87], v[28:29], v[44:45], v[60:61]
	v_pk_fma_f32 v[88:89], v[30:31], v[46:47], v[62:63]
	v_pk_fma_f32 v[90:91], v[32:33], v[48:49], v[64:65]
	v_cvt_pk_bf16_f32 v92, v76, v77
	v_cvt_pk_bf16_f32 v93, v78, v79
	v_cvt_pk_bf16_f32 v94, v80, v81
	v_cvt_pk_bf16_f32 v95, v82, v83
	v_cvt_pk_bf16_f32 v96, v84, v85
	v_cvt_pk_bf16_f32 v97, v86, v87
	v_cvt_pk_bf16_f32 v98, v88, v89
	v_cvt_pk_bf16_f32 v99, v90, v91
	global_store_dwordx2 v115, v[92:93], s[2:3] offset:0 sc1
	global_store_dwordx2 v115, v[94:95], s[2:3] offset:512 sc1
	global_store_dwordx2 v115, v[96:97], s[2:3] offset:1024 sc1
	global_store_dwordx2 v115, v[98:99], s[2:3] offset:1536 sc1
	s_add_u32 s2, s2, 0x400000
	s_addc_u32 s3, s3, 0
	s_add_u32 s0, s0, 0x800000
	s_addc_u32 s1, s1, 0
	global_load_dwordx4 v[18:21], v114, s[0:1] offset:0
	global_load_dwordx4 v[22:25], v114, s[0:1] offset:1024
	global_load_dwordx4 v[26:29], v114, s[0:1] offset:2048
	global_load_dwordx4 v[30:33], v114, s[0:1] offset:3072
	s_waitcnt vmcnt(8)
; __device__ __forceinline__ void phase_ln(float* R, const float* __restrict__ g, const float* __restrict__ b, bf16_t* xbf, float samp_scale, const float* __restrict__ part, int nsplit, bool f32_all) {
;     ...
;   for (int r = gw; r < MT; r += nw) {
;     float* row = R + (size_t)r * 1024;
;     f32x4 v[4];
; #pragma unroll
;     for (int i = 0; i < 4; ++i) v[i] = *(const f32x4*)(row + i * 256 + lane * 4);
;     if (r >= MP) {
;       for (int sp = 0; sp < nsplit; ++sp) {
;         const float* prow = part + ((size_t)sp * MS + (r - MP)) * 1024;
; #pragma unroll
;         for (int i = 0; i < 4; ++i) v[i] = v[i] + *(const f32x4*)(prow + i * 256 + lane * 4);
;       }
;     }
;     float s = 0.f;
; #pragma unroll
;     for (int i = 0; i < 4; ++i) s += v[i][0] + v[i][1] + v[i][2] + v[i][3];
; #pragma unroll
;     for (int o = 32; o >= 1; o >>= 1) s += __shfl_xor(s, o);
;     const float mean = s * (1.f / 1024.f);
;     float ss = 0.f;
; #pragma unroll
;     for (int i = 0; i < 4; ++i) { v[i] = v[i] - mean; ss += v[i][0] * v[i][0] + v[i][1] * v[i][1] + v[i][2] * v[i][2] + v[i][3] * v[i][3]; }
; #pragma unroll
;     for (int o = 32; o >= 1; o >>= 1) ss += __shfl_xor(ss, o);
;     const float rstd = rsqrtf(ss * (1.f / 1024.f) + LN_EPS);
; #pragma unroll
;     for (int i = 0; i < 4; ++i) {
;       const f32x4 y = v[i] * rstd * gv[i] + bv[i];
;       if (r >= MP) *(f32x4*)(row + i * 256 + lane * 4) = y * samp_scale;
;       else if (f32_all) *(f32x4*)(row + i * 256 + lane * 4) = y;
;       if (xbf) {
;         u32x2 wv;
;         wv[0] = cvt_pk_bf16(y[0], y[1]); wv[1] = cvt_pk_bf16(y[2], y[3]);
;         *(u32x2*)(xbf + (size_t)r * 1024 + i * 256 + lane * 4) = wv;
;       }
;     }
	v_pk_add_f32 v[66:67], v[0:1], v[2:3]
	v_pk_add_f32 v[68:69], v[4:5], v[6:7]
	v_pk_add_f32 v[70:71], v[8:9], v[10:11]
	v_pk_add_f32 v[72:73], v[12:13], v[14:15]
	v_pk_add_f32 v[66:67], v[66:67], v[68:69]
	v_pk_add_f32 v[70:71], v[70:71], v[72:73]
	v_pk_add_f32 v[66:67], v[66:67], v[70:71]
	v_add_f32_e32 v66, v66, v67
	s_nop 1
	v_add_f32_dpp v66, v66, v66 row_shr:1 row_mask:0xf bank_mask:0xf bound_ctrl:1
	s_nop 1
	v_add_f32_dpp v66, v66, v66 row_shr:2 row_mask:0xf bank_mask:0xf bound_ctrl:1
	s_nop 1
	v_add_f32_dpp v66, v66, v66 row_shr:4 row_mask:0xf bank_mask:0xf bound_ctrl:1
	s_nop 1
	v_add_f32_dpp v66, v66, v66 row_shr:8 row_mask:0xf bank_mask:0xf bound_ctrl:1
	s_nop 0
	v_readlane_b32 s9, v66, 15
	v_readlane_b32 s10, v66, 31
	v_readlane_b32 s11, v66, 47
	v_readlane_b32 vcc_lo, v66, 63
	s_nop 1
	v_mov_b32_e32 v66, s9
	v_add_f32_e32 v66, s10, v66
	v_add_f32_e32 v66, s11, v66
	v_add_f32_e32 v66, vcc_lo, v66
	v_mul_f32_e32 v116, 0x3a800000, v66
	v_mov_b32_e32 v117, v116
	v_pk_add_f32 v[0:1], v[0:1], v[116:117] neg_lo:[0,1] neg_hi:[0,1]
	v_pk_add_f32 v[2:3], v[2:3], v[116:117] neg_lo:[0,1] neg_hi:[0,1]
	v_pk_add_f32 v[4:5], v[4:5], v[116:117] neg_lo:[0,1] neg_hi:[0,1]
	v_pk_add_f32 v[6:7], v[6:7], v[116:117] neg_lo:[0,1] neg_hi:[0,1]
	v_pk_add_f32 v[8:9], v[8:9], v[116:117] neg_lo:[0,1] neg_hi:[0,1]
	v_pk_add_f32 v[10:11], v[10:11], v[116:117] neg_lo:[0,1] neg_hi:[0,1]
	v_pk_add_f32 v[12:13], v[12:13], v[116:117] neg_lo:[0,1] neg_hi:[0,1]
	v_pk_add_f32 v[14:15], v[14:15], v[116:117] neg_lo:[0,1] neg_hi:[0,1]
	v_pk_mul_f32 v[66:67], v[0:1], v[0:1]
	v_pk_mul_f32 v[68:69], v[2:3], v[2:3]
	v_pk_fma_f32 v[66:67], v[4:5], v[4:5], v[66:67]
	v_pk_fma_f32 v[68:69], v[6:7], v[6:7], v[68:69]
	v_pk_fma_f32 v[66:67], v[8:9], v[8:9], v[66:67]
	v_pk_fma_f32 v[68:69], v[10:11], v[10:11], v[68:69]
	v_pk_fma_f32 v[66:67], v[12:13], v[12:13], v[66:67]
	v_pk_fma_f32 v[68:69], v[14:15], v[14:15], v[68:69]
	v_pk_add_f32 v[66:67], v[66:67], v[68:69]
	v_add_f32_e32 v66, v66, v67
	s_nop 1
	v_add_f32_dpp v66, v66, v66 row_shr:1 row_mask:0xf bank_mask:0xf bound_ctrl:1
	s_nop 1
	v_add_f32_dpp v66, v66, v66 row_shr:2 row_mask:0xf bank_mask:0xf bound_ctrl:1
	s_nop 1
	v_add_f32_dpp v66, v66, v66 row_shr:4 row_mask:0xf bank_mask:0xf bound_ctrl:1
	s_nop 1
	v_add_f32_dpp v66, v66, v66 row_shr:8 row_mask:0xf bank_mask:0xf bound_ctrl:1
	s_nop 0
	v_readlane_b32 s9, v66, 15
	v_readlane_b32 s10, v66, 31
	v_readlane_b32 s11, v66, 47
	v_readlane_b32 vcc_lo, v66, 63
	s_nop 1
	v_mov_b32_e32 v66, s9
	v_add_f32_e32 v66, s10, v66
	v_add_f32_e32 v66, s11, v66
	v_add_f32_e32 v66, vcc_lo, v66
	v_mul_f32_e32 v66, 0x3a800000, v66
	v_add_f32_e32 v66, 0x3727c5ac, v66
	v_rsq_f32_e32 v118, v66
	s_nop 0
	v_mov_b32_e32 v119, v118
	v_pk_mul_f32 v[0:1], v[0:1], v[118:119]
	v_pk_mul_f32 v[2:3], v[2:3], v[118:119]
	v_pk_mul_f32 v[4:5], v[4:5], v[118:119]
	v_pk_mul_f32 v[6:7], v[6:7], v[118:119]
	v_pk_mul_f32 v[8:9], v[8:9], v[118:119]
	v_pk_mul_f32 v[10:11], v[10:11], v[118:119]
	v_pk_mul_f32 v[12:13], v[12:13], v[118:119]
	v_pk_mul_f32 v[14:15], v[14:15], v[118:119]
	v_pk_fma_f32 v[76:77], v[0:1], v[34:35], v[50:51]
	v_pk_fma_f32 v[78:79], v[2:3], v[36:37], v[52:53]
	v_pk_fma_f32 v[80:81], v[4:5], v[38:39], v[54:55]
	v_pk_fma_f32 v[82:83], v[6:7], v[40:41], v[56:57]
	v_pk_fma_f32 v[84:85], v[8:9], v[42:43], v[58:59]
	v_pk_fma_f32 v[86:87], v[10:11], v[44:45], v[60:61]
	v_pk_fma_f32 v[88:89], v[12:13], v[46:47], v[62:63]
	v_pk_fma_f32 v[90:91], v[14:15], v[48:49], v[64:65]
	v_cvt_pk_bf16_f32 v92, v76, v77
	v_cvt_pk_bf16_f32 v93, v78, v79
	v_cvt_pk_bf16_f32 v94, v80, v81
	v_cvt_pk_bf16_f32 v95, v82, v83
	v_cvt_pk_bf16_f32 v96, v84, v85
	v_cvt_pk_bf16_f32 v97, v86, v87
	v_cvt_pk_bf16_f32 v98, v88, v89
	v_cvt_pk_bf16_f32 v99, v90, v91
	global_store_dwordx2 v115, v[92:93], s[2:3] offset:0 sc1
	global_store_dwordx2 v115, v[94:95], s[2:3] offset:512 sc1
	global_store_dwordx2 v115, v[96:97], s[2:3] offset:1024 sc1
	global_store_dwordx2 v115, v[98:99], s[2:3] offset:1536 sc1
	s_add_u32 s2, s2, 0x400000
	s_addc_u32 s3, s3, 0
	s_waitcnt vmcnt(4)
	v_pk_add_f32 v[66:67], v[18:19], v[20:21]
	v_pk_add_f32 v[68:69], v[22:23], v[24:25]
	v_pk_add_f32 v[70:71], v[26:27], v[28:29]
	v_pk_add_f32 v[72:73], v[30:31], v[32:33]
	v_pk_add_f32 v[66:67], v[66:67], v[68:69]
	v_pk_add_f32 v[70:71], v[70:71], v[72:73]
	v_pk_add_f32 v[66:67], v[66:67], v[70:71]
	v_add_f32_e32 v66, v66, v67
	s_nop 1
	v_add_f32_dpp v66, v66, v66 row_shr:1 row_mask:0xf bank_mask:0xf bound_ctrl:1
	s_nop 1
	v_add_f32_dpp v66, v66, v66 row_shr:2 row_mask:0xf bank_mask:0xf bound_ctrl:1
	s_nop 1
	v_add_f32_dpp v66, v66, v66 row_shr:4 row_mask:0xf bank_mask:0xf bound_ctrl:1
	s_nop 1
	v_add_f32_dpp v66, v66, v66 row_shr:8 row_mask:0xf bank_mask:0xf bound_ctrl:1
	s_nop 0
	v_readlane_b32 s9, v66, 15
	v_readlane_b32 s10, v66, 31
	v_readlane_b32 s11, v66, 47
	v_readlane_b32 vcc_lo, v66, 63
	s_nop 1
	v_mov_b32_e32 v66, s9
	v_add_f32_e32 v66, s10, v66
	v_add_f32_e32 v66, s11, v66
	v_add_f32_e32 v66, vcc_lo, v66
	v_mul_f32_e32 v116, 0x3a800000, v66
	v_mov_b32_e32 v117, v116
	v_pk_add_f32 v[18:19], v[18:19], v[116:117] neg_lo:[0,1] neg_hi:[0,1]
	v_pk_add_f32 v[20:21], v[20:21], v[116:117] neg_lo:[0,1] neg_hi:[0,1]
	v_pk_add_f32 v[22:23], v[22:23], v[116:117] neg_lo:[0,1] neg_hi:[0,1]
	v_pk_add_f32 v[24:25], v[24:25], v[116:117] neg_lo:[0,1] neg_hi:[0,1]
	v_pk_add_f32 v[26:27], v[26:27], v[116:117] neg_lo:[0,1] neg_hi:[0,1]
	v_pk_add_f32 v[28:29], v[28:29], v[116:117] neg_lo:[0,1] neg_hi:[0,1]
	v_pk_add_f32 v[30:31], v[30:31], v[116:117] neg_lo:[0,1] neg_hi:[0,1]
	v_pk_add_f32 v[32:33], v[32:33], v[116:117] neg_lo:[0,1] neg_hi:[0,1]
	v_pk_mul_f32 v[66:67], v[18:19], v[18:19]
; __device__ __forceinline__ void phase_ln(float* R, const float* __restrict__ g, const float* __restrict__ b, bf16_t* xbf, float samp_scale, const float* __restrict__ part, int nsplit, bool f32_all) {
;     ...
;   for (int r = gw; r < MT; r += nw) {
;     float* row = R + (size_t)r * 1024;
;     f32x4 v[4];
; #pragma unroll
;     for (int i = 0; i < 4; ++i) v[i] = *(const f32x4*)(row + i * 256 + lane * 4);
;     if (r >= MP) {
;       for (int sp = 0; sp < nsplit; ++sp) {
;         const float* prow = part + ((size_t)sp * MS + (r - MP)) * 1024;
; #pragma unroll
;         for (int i = 0; i < 4; ++i) v[i] = v[i] + *(const f32x4*)(prow + i * 256 + lane * 4);
;       }
;     }
;     ...
;     const float mean = s * (1.f / 1024.f);
;     float ss = 0.f;
; #pragma unroll
;     for (int i = 0; i < 4; ++i) { v[i] = v[i] - mean; ss += v[i][0] * v[i][0] + v[i][1] * v[i][1] + v[i][2] * v[i][2] + v[i][3] * v[i][3]; }
; #pragma unroll
;     for (int o = 32; o >= 1; o >>= 1) ss += __shfl_xor(ss, o);
;     const float rstd = rsqrtf(ss * (1.f / 1024.f) + LN_EPS);
; #pragma unroll
;     for (int i = 0; i < 4; ++i) {
;       const f32x4 y = v[i] * rstd * gv[i] + bv[i];
;       if (r >= MP) *(f32x4*)(row + i * 256 + lane * 4) = y * samp_scale;
;       else if (f32_all) *(f32x4*)(row + i * 256 + lane * 4) = y;
;       if (xbf) {
;         u32x2 wv;
;         wv[0] = cvt_pk_bf16(y[0], y[1]); wv[1] = cvt_pk_bf16(y[2], y[3]);
;         *(u32x2*)(xbf + (size_t)r * 1024 + i * 256 + lane * 4) = wv;
	v_pk_mul_f32 v[68:69], v[20:21], v[20:21]
	v_pk_fma_f32 v[66:67], v[22:23], v[22:23], v[66:67]
	v_pk_fma_f32 v[68:69], v[24:25], v[24:25], v[68:69]
	v_pk_fma_f32 v[66:67], v[26:27], v[26:27], v[66:67]
	v_pk_fma_f32 v[68:69], v[28:29], v[28:29], v[68:69]
	v_pk_fma_f32 v[66:67], v[30:31], v[30:31], v[66:67]
	v_pk_fma_f32 v[68:69], v[32:33], v[32:33], v[68:69]
	v_pk_add_f32 v[66:67], v[66:67], v[68:69]
	v_add_f32_e32 v66, v66, v67
	s_nop 1
	v_add_f32_dpp v66, v66, v66 row_shr:1 row_mask:0xf bank_mask:0xf bound_ctrl:1
	s_nop 1
	v_add_f32_dpp v66, v66, v66 row_shr:2 row_mask:0xf bank_mask:0xf bound_ctrl:1
	s_nop 1
	v_add_f32_dpp v66, v66, v66 row_shr:4 row_mask:0xf bank_mask:0xf bound_ctrl:1
	s_nop 1
	v_add_f32_dpp v66, v66, v66 row_shr:8 row_mask:0xf bank_mask:0xf bound_ctrl:1
	s_nop 0
	v_readlane_b32 s9, v66, 15
	v_readlane_b32 s10, v66, 31
	v_readlane_b32 s11, v66, 47
	v_readlane_b32 vcc_lo, v66, 63
	s_nop 1
	v_mov_b32_e32 v66, s9
	v_add_f32_e32 v66, s10, v66
	v_add_f32_e32 v66, s11, v66
	v_add_f32_e32 v66, vcc_lo, v66
	v_mul_f32_e32 v66, 0x3a800000, v66
	v_add_f32_e32 v66, 0x3727c5ac, v66
	v_rsq_f32_e32 v118, v66
	s_nop 0
	v_mov_b32_e32 v119, v118
	v_pk_mul_f32 v[18:19], v[18:19], v[118:119]
	v_pk_mul_f32 v[20:21], v[20:21], v[118:119]
	v_pk_mul_f32 v[22:23], v[22:23], v[118:119]
	v_pk_mul_f32 v[24:25], v[24:25], v[118:119]
	v_pk_mul_f32 v[26:27], v[26:27], v[118:119]
	v_pk_mul_f32 v[28:29], v[28:29], v[118:119]
	v_pk_mul_f32 v[30:31], v[30:31], v[118:119]
	v_pk_mul_f32 v[32:33], v[32:33], v[118:119]
	v_pk_fma_f32 v[76:77], v[18:19], v[34:35], v[50:51]
	v_pk_fma_f32 v[78:79], v[20:21], v[36:37], v[52:53]
	v_pk_fma_f32 v[80:81], v[22:23], v[38:39], v[54:55]
	v_pk_fma_f32 v[82:83], v[24:25], v[40:41], v[56:57]
	v_pk_fma_f32 v[84:85], v[26:27], v[42:43], v[58:59]
	v_pk_fma_f32 v[86:87], v[28:29], v[44:45], v[60:61]
	v_pk_fma_f32 v[88:89], v[30:31], v[46:47], v[62:63]
	v_pk_fma_f32 v[90:91], v[32:33], v[48:49], v[64:65]
	v_cvt_pk_bf16_f32 v92, v76, v77
	v_cvt_pk_bf16_f32 v93, v78, v79
	v_cvt_pk_bf16_f32 v94, v80, v81
	v_cvt_pk_bf16_f32 v95, v82, v83
	v_cvt_pk_bf16_f32 v96, v84, v85
	v_cvt_pk_bf16_f32 v97, v86, v87
	v_cvt_pk_bf16_f32 v98, v88, v89
	v_cvt_pk_bf16_f32 v99, v90, v91
	global_store_dwordx2 v115, v[92:93], s[2:3] offset:0 sc1
	global_store_dwordx2 v115, v[94:95], s[2:3] offset:512 sc1
	global_store_dwordx2 v115, v[96:97], s[2:3] offset:1024 sc1
	global_store_dwordx2 v115, v[98:99], s[2:3] offset:1536 sc1
	s_add_u32 s2, s2, 0x400000
	s_addc_u32 s3, s3, 0
	v_readfirstlane_b32 s10, v244
	v_readlane_b32 s9, v254, 6
	s_lshr_b32 s10, s10, 6
	s_cmp_ge_u32 s10, 2
	s_cbranch_scc1 .Lln1_done
	s_lshl_b32 s9, s9, 1
	s_add_i32 s9, s9, s10
	s_lshl_b32 s11, s9, 12
	s_add_u32 s11, s11, 0x8000000
	s_add_u32 s0, s4, s11
	s_addc_u32 s1, s5, 0
	s_lshl_b32 s11, s9, 11
	s_add_u32 s11, s11, 0x79c0000
	s_add_u32 s2, s6, s11
	s_addc_u32 s3, s7, 0
	s_lshl_b32 s11, s9, 12
	s_add_u32 s11, s11, 0x1e482000
	s_add_u32 s10, s6, s11
	s_addc_u32 s11, s7, 0
	global_load_dwordx4 v[0:3], v114, s[0:1] offset:0
	global_load_dwordx4 v[4:7], v114, s[0:1] offset:1024
	global_load_dwordx4 v[8:11], v114, s[0:1] offset:2048
	global_load_dwordx4 v[12:15], v114, s[0:1] offset:3072
	global_load_dwordx4 v[18:21], v114, s[10:11] offset:0
	global_load_dwordx4 v[22:25], v114, s[10:11] offset:1024
	global_load_dwordx4 v[26:29], v114, s[10:11] offset:2048
	global_load_dwordx4 v[30:33], v114, s[10:11] offset:3072
	s_add_u32 s10, s10, 0x200000
	s_addc_u32 s11, s11, 0
	global_load_dwordx4 v[66:69], v114, s[10:11] offset:0
	global_load_dwordx4 v[70:73], v114, s[10:11] offset:1024
	global_load_dwordx4 v[74:77], v114, s[10:11] offset:2048
	global_load_dwordx4 v[78:81], v114, s[10:11] offset:3072
	s_add_u32 s10, s10, 0x200000
	s_addc_u32 s11, s11, 0
	global_load_dwordx4 v[82:85], v114, s[10:11] offset:0
	global_load_dwordx4 v[86:89], v114, s[10:11] offset:1024
	global_load_dwordx4 v[90:93], v114, s[10:11] offset:2048
	global_load_dwordx4 v[94:97], v114, s[10:11] offset:3072
	s_add_u32 s10, s10, 0x200000
	s_addc_u32 s11, s11, 0
	global_load_dwordx4 v[98:101], v114, s[10:11] offset:0
	global_load_dwordx4 v[102:105], v114, s[10:11] offset:1024
	global_load_dwordx4 v[106:109], v114, s[10:11] offset:2048
	global_load_dwordx4 v[110:113], v114, s[10:11] offset:3072
	s_add_u32 s10, s10, 0x200000
	s_addc_u32 s11, s11, 0
	s_waitcnt vmcnt(0)
; __device__ __forceinline__ void phase_ln(float* R, const float* __restrict__ g, const float* __restrict__ b, bf16_t* xbf, float samp_scale, const float* __restrict__ part, int nsplit, bool f32_all) {
;     ...
;       for (int sp = 0; sp < nsplit; ++sp) {
;         const float* prow = part + ((size_t)sp * MS + (r - MP)) * 1024;
; #pragma unroll
;         for (int i = 0; i < 4; ++i) v[i] = v[i] + *(const f32x4*)(prow + i * 256 + lane * 4);
;       }
;     }
;     float s = 0.f;
; #pragma unroll
;     for (int i = 0; i < 4; ++i) s += v[i][0] + v[i][1] + v[i][2] + v[i][3];
; #pragma unroll
;     for (int o = 32; o >= 1; o >>= 1) s += __shfl_xor(s, o);
;     const float mean = s * (1.f / 1024.f);
;     float ss = 0.f;
; #pragma unroll
;     for (int i = 0; i < 4; ++i) { v[i] = v[i] - mean; ss += v[i][0] * v[i][0] + v[i][1] * v[i][1] + v[i][2] * v[i][2] + v[i][3] * v[i][3]; }
; #pragma unroll
;     for (int o = 32; o >= 1; o >>= 1) ss += __shfl_xor(ss, o);
;     const float rstd = rsqrtf(ss * (1.f / 1024.f) + LN_EPS);
; #pragma unroll
;     for (int i = 0; i < 4; ++i) {
;       const f32x4 y = v[i] * rstd * gv[i] + bv[i];
;       if (r >= MP) *(f32x4*)(row + i * 256 + lane * 4) = y * samp_scale;
;       else if (f32_all) *(f32x4*)(row + i * 256 + lane * 4) = y;
;       if (xbf) {
;         u32x2 wv;
;         wv[0] = cvt_pk_bf16(y[0], y[1]); wv[1] = cvt_pk_bf16(y[2], y[3]);
;         *(u32x2*)(xbf + (size_t)r * 1024 + i * 256 + lane * 4) = wv;
	v_pk_add_f32 v[0:1], v[0:1], v[18:19]
	v_pk_add_f32 v[2:3], v[2:3], v[20:21]
	v_pk_add_f32 v[4:5], v[4:5], v[22:23]
	v_pk_add_f32 v[6:7], v[6:7], v[24:25]
	v_pk_add_f32 v[8:9], v[8:9], v[26:27]
	v_pk_add_f32 v[10:11], v[10:11], v[28:29]
	v_pk_add_f32 v[12:13], v[12:13], v[30:31]
	v_pk_add_f32 v[14:15], v[14:15], v[32:33]
	v_pk_add_f32 v[0:1], v[0:1], v[66:67]
	v_pk_add_f32 v[2:3], v[2:3], v[68:69]
	v_pk_add_f32 v[4:5], v[4:5], v[70:71]
	v_pk_add_f32 v[6:7], v[6:7], v[72:73]
	v_pk_add_f32 v[8:9], v[8:9], v[74:75]
	v_pk_add_f32 v[10:11], v[10:11], v[76:77]
	v_pk_add_f32 v[12:13], v[12:13], v[78:79]
	v_pk_add_f32 v[14:15], v[14:15], v[80:81]
	v_pk_add_f32 v[0:1], v[0:1], v[82:83]
	v_pk_add_f32 v[2:3], v[2:3], v[84:85]
	v_pk_add_f32 v[4:5], v[4:5], v[86:87]
	v_pk_add_f32 v[6:7], v[6:7], v[88:89]
	v_pk_add_f32 v[8:9], v[8:9], v[90:91]
	v_pk_add_f32 v[10:11], v[10:11], v[92:93]
	v_pk_add_f32 v[12:13], v[12:13], v[94:95]
	v_pk_add_f32 v[14:15], v[14:15], v[96:97]
	v_pk_add_f32 v[0:1], v[0:1], v[98:99]
	v_pk_add_f32 v[2:3], v[2:3], v[100:101]
	v_pk_add_f32 v[4:5], v[4:5], v[102:103]
	v_pk_add_f32 v[6:7], v[6:7], v[104:105]
	v_pk_add_f32 v[8:9], v[8:9], v[106:107]
	v_pk_add_f32 v[10:11], v[10:11], v[108:109]
	v_pk_add_f32 v[12:13], v[12:13], v[110:111]
	v_pk_add_f32 v[14:15], v[14:15], v[112:113]
	v_pk_add_f32 v[66:67], v[0:1], v[2:3]
	v_pk_add_f32 v[68:69], v[4:5], v[6:7]
	v_pk_add_f32 v[70:71], v[8:9], v[10:11]
	v_pk_add_f32 v[72:73], v[12:13], v[14:15]
	v_pk_add_f32 v[66:67], v[66:67], v[68:69]
	v_pk_add_f32 v[70:71], v[70:71], v[72:73]
	v_pk_add_f32 v[66:67], v[66:67], v[70:71]
	v_add_f32_e32 v66, v66, v67
	s_nop 1
	v_add_f32_dpp v66, v66, v66 row_shr:1 row_mask:0xf bank_mask:0xf bound_ctrl:1
	s_nop 1
	v_add_f32_dpp v66, v66, v66 row_shr:2 row_mask:0xf bank_mask:0xf bound_ctrl:1
	s_nop 1
	v_add_f32_dpp v66, v66, v66 row_shr:4 row_mask:0xf bank_mask:0xf bound_ctrl:1
	s_nop 1
	v_add_f32_dpp v66, v66, v66 row_shr:8 row_mask:0xf bank_mask:0xf bound_ctrl:1
	s_nop 0
	v_readlane_b32 s9, v66, 15
	v_readlane_b32 s10, v66, 31
	v_readlane_b32 s11, v66, 47
	v_readlane_b32 vcc_lo, v66, 63
	s_nop 1
	v_mov_b32_e32 v66, s9
	v_add_f32_e32 v66, s10, v66
	v_add_f32_e32 v66, s11, v66
	v_add_f32_e32 v66, vcc_lo, v66
	v_mul_f32_e32 v116, 0x3a800000, v66
	v_mov_b32_e32 v117, v116
	v_pk_add_f32 v[0:1], v[0:1], v[116:117] neg_lo:[0,1] neg_hi:[0,1]
	v_pk_add_f32 v[2:3], v[2:3], v[116:117] neg_lo:[0,1] neg_hi:[0,1]
	v_pk_add_f32 v[4:5], v[4:5], v[116:117] neg_lo:[0,1] neg_hi:[0,1]
	v_pk_add_f32 v[6:7], v[6:7], v[116:117] neg_lo:[0,1] neg_hi:[0,1]
	v_pk_add_f32 v[8:9], v[8:9], v[116:117] neg_lo:[0,1] neg_hi:[0,1]
	v_pk_add_f32 v[10:11], v[10:11], v[116:117] neg_lo:[0,1] neg_hi:[0,1]
	v_pk_add_f32 v[12:13], v[12:13], v[116:117] neg_lo:[0,1] neg_hi:[0,1]
	v_pk_add_f32 v[14:15], v[14:15], v[116:117] neg_lo:[0,1] neg_hi:[0,1]
	v_pk_mul_f32 v[66:67], v[0:1], v[0:1]
	v_pk_mul_f32 v[68:69], v[2:3], v[2:3]
	v_pk_fma_f32 v[66:67], v[4:5], v[4:5], v[66:67]
	v_pk_fma_f32 v[68:69], v[6:7], v[6:7], v[68:69]
	v_pk_fma_f32 v[66:67], v[8:9], v[8:9], v[66:67]
	v_pk_fma_f32 v[68:69], v[10:11], v[10:11], v[68:69]
	v_pk_fma_f32 v[66:67], v[12:13], v[12:13], v[66:67]
	v_pk_fma_f32 v[68:69], v[14:15], v[14:15], v[68:69]
	v_pk_add_f32 v[66:67], v[66:67], v[68:69]
	v_add_f32_e32 v66, v66, v67
	s_nop 1
	v_add_f32_dpp v66, v66, v66 row_shr:1 row_mask:0xf bank_mask:0xf bound_ctrl:1
	s_nop 1
	v_add_f32_dpp v66, v66, v66 row_shr:2 row_mask:0xf bank_mask:0xf bound_ctrl:1
	s_nop 1
	v_add_f32_dpp v66, v66, v66 row_shr:4 row_mask:0xf bank_mask:0xf bound_ctrl:1
	s_nop 1
	v_add_f32_dpp v66, v66, v66 row_shr:8 row_mask:0xf bank_mask:0xf bound_ctrl:1
	s_nop 0
	v_readlane_b32 s9, v66, 15
	v_readlane_b32 s10, v66, 31
	v_readlane_b32 s11, v66, 47
	v_readlane_b32 vcc_lo, v66, 63
	s_nop 1
	v_mov_b32_e32 v66, s9
	v_add_f32_e32 v66, s10, v66
	v_add_f32_e32 v66, s11, v66
	v_add_f32_e32 v66, vcc_lo, v66
	v_mul_f32_e32 v66, 0x3a800000, v66
	v_add_f32_e32 v66, 0x3727c5ac, v66
	v_rsq_f32_e32 v118, v66
	s_nop 0
	v_mov_b32_e32 v119, v118
	v_pk_mul_f32 v[0:1], v[0:1], v[118:119]
	v_pk_mul_f32 v[2:3], v[2:3], v[118:119]
	v_pk_mul_f32 v[4:5], v[4:5], v[118:119]
	v_pk_mul_f32 v[6:7], v[6:7], v[118:119]
	v_pk_mul_f32 v[8:9], v[8:9], v[118:119]
	v_pk_mul_f32 v[10:11], v[10:11], v[118:119]
	v_pk_mul_f32 v[12:13], v[12:13], v[118:119]
	v_pk_mul_f32 v[14:15], v[14:15], v[118:119]
	v_pk_fma_f32 v[76:77], v[0:1], v[34:35], v[50:51]
	v_pk_fma_f32 v[78:79], v[2:3], v[36:37], v[52:53]
	v_pk_fma_f32 v[80:81], v[4:5], v[38:39], v[54:55]
	v_pk_fma_f32 v[82:83], v[6:7], v[40:41], v[56:57]
	v_pk_fma_f32 v[84:85], v[8:9], v[42:43], v[58:59]
	v_pk_fma_f32 v[86:87], v[10:11], v[44:45], v[60:61]
	v_pk_fma_f32 v[88:89], v[12:13], v[46:47], v[62:63]
	v_pk_fma_f32 v[90:91], v[14:15], v[48:49], v[64:65]
	s_mov_b32 s9, 0x3fb504f3
	v_mov_b32_e32 v120, s9
	v_mov_b32_e32 v121, s9
	v_pk_mul_f32 v[0:1], v[76:77], v[120:121]
	v_pk_mul_f32 v[2:3], v[78:79], v[120:121]
	v_pk_mul_f32 v[4:5], v[80:81], v[120:121]
	v_pk_mul_f32 v[6:7], v[82:83], v[120:121]
	v_pk_mul_f32 v[8:9], v[84:85], v[120:121]
	v_pk_mul_f32 v[10:11], v[86:87], v[120:121]
	v_pk_mul_f32 v[12:13], v[88:89], v[120:121]
	v_pk_mul_f32 v[14:15], v[90:91], v[120:121]
	global_store_dwordx4 v114, v[0:3], s[0:1] offset:0 sc1
	global_store_dwordx4 v114, v[4:7], s[0:1] offset:1024 sc1
	global_store_dwordx4 v114, v[8:11], s[0:1] offset:2048 sc1
	global_store_dwordx4 v114, v[12:15], s[0:1] offset:3072 sc1
	v_cvt_pk_bf16_f32 v92, v76, v77
	v_cvt_pk_bf16_f32 v93, v78, v79
	v_cvt_pk_bf16_f32 v94, v80, v81
	v_cvt_pk_bf16_f32 v95, v82, v83
	v_cvt_pk_bf16_f32 v96, v84, v85
	v_cvt_pk_bf16_f32 v97, v86, v87
	v_cvt_pk_bf16_f32 v98, v88, v89
	v_cvt_pk_bf16_f32 v99, v90, v91
	global_store_dwordx2 v115, v[92:93], s[2:3] offset:0 sc1
	global_store_dwordx2 v115, v[94:95], s[2:3] offset:512 sc1
	global_store_dwordx2 v115, v[96:97], s[2:3] offset:1024 sc1
	global_store_dwordx2 v115, v[98:99], s[2:3] offset:1536 sc1

; __device__ __forceinline__ int otid() { int t = threadIdx.x; asm volatile("" : "+v"(t)); return t; }
; __device__ __forceinline__ void phase_ln(float* R, const float* __restrict__ g, const float* __restrict__ b, bf16_t* xbf, float samp_scale, const float* __restrict__ part, int nsplit, bool f32_all) {
;   const int tid = otid(), lane = tid & 63, gw = blockIdx.x * 8 + (tid >> 6), nw = gridDim.x * 8;
;   f32x4 gv[4], bv[4];
; #pragma unroll
;   for (int i = 0; i < 4; ++i) { gv[i] = *(const f32x4*)(g + i * 256 + lane * 4); bv[i] = *(const f32x4*)(b + i * 256 + lane * 4); }
;   for (int r = gw; r < MT; r += nw) {
;     float* row = R + (size_t)r * 1024;
;     f32x4 v[4];
; #pragma unroll
;     for (int i = 0; i < 4; ++i) v[i] = *(const f32x4*)(row + i * 256 + lane * 4);
;     if (r >= MP) {
;       for (int sp = 0; sp < nsplit; ++sp) {
;         const float* prow = part + ((size_t)sp * MS + (r - MP)) * 1024;
; #pragma unroll
;         for (int i = 0; i < 4; ++i) v[i] = v[i] + *(const f32x4*)(prow + i * 256 + lane * 4);
;       }
;     }
;     float s = 0.f;
; #pragma unroll
;     for (int i = 0; i < 4; ++i) s += v[i][0] + v[i][1] + v[i][2] + v[i][3];
; #pragma unroll
;     for (int o = 32; o >= 1; o >>= 1) s += __shfl_xor(s, o);
;     const float mean = s * (1.f / 1024.f);
;     float ss = 0.f;
; #pragma unroll
;     for (int i = 0; i < 4; ++i) { v[i] = v[i] - mean; ss += v[i][0] * v[i][0] + v[i][1] * v[i][1] + v[i][2] * v[i][2] + v[i][3] * v[i][3]; }
; #pragma unroll
;     for (int o = 32; o >= 1; o >>= 1) ss += __shfl_xor(ss, o);
;     const float rstd = rsqrtf(ss * (1.f / 1024.f) + LN_EPS);
; #pragma unroll
;     for (int i = 0; i < 4; ++i) {
;       const f32x4 y = v[i] * rstd * gv[i] + bv[i];
;       if (r >= MP) *(f32x4*)(row + i * 256 + lane * 4) = y * samp_scale;
;       else if (f32_all) *(f32x4*)(row + i * 256 + lane * 4) = y;
;       if (xbf) {
;         u32x2 wv;
;         wv[0] = cvt_pk_bf16(y[0], y[1]); wv[1] = cvt_pk_bf16(y[2], y[3]);
;         *(u32x2*)(xbf + (size_t)r * 1024 + i * 256 + lane * 4) = wv;
.LBB0_3944:
	s_or_b64 exec, exec, s[0:1]
	v_readlane_b32 s0, v254, 51
	s_nop 0
	s_cmp_lg_u32 s0, 0
	s_cbranch_scc1 .Lln2_orig
	v_readlane_b32 s6, v254, 2
	v_readlane_b32 s7, v254, 3
	v_readlane_b32 s8, v255, 22
	s_waitcnt lgkmcnt(0)
	s_barrier
	s_load_dwordx4 s[0:3], s[6:7], 0x98
	s_load_dwordx4 s[4:7], s[6:7], 0xa8
	v_readlane_b32 s9, v254, 15
	v_readfirstlane_b32 s10, v244
	v_lshlrev_b32_e32 v114, 4, v252
	v_lshlrev_b32_e32 v115, 3, v252
	s_lshr_b32 s10, s10, 6
	s_add_i32 s9, s9, s10
	s_lshl_b32 s11, s8, 12
	s_waitcnt lgkmcnt(0)
	s_add_u32 s0, s0, s11
	s_addc_u32 s1, s1, 0
	s_add_u32 s2, s2, s11
	s_addc_u32 s3, s3, 0
	global_load_dwordx4 v[34:37], v114, s[0:1] offset:0
	global_load_dwordx4 v[38:41], v114, s[0:1] offset:1024
	global_load_dwordx4 v[42:45], v114, s[0:1] offset:2048
	global_load_dwordx4 v[46:49], v114, s[0:1] offset:3072
	global_load_dwordx4 v[50:53], v114, s[2:3] offset:0
	global_load_dwordx4 v[54:57], v114, s[2:3] offset:1024
	global_load_dwordx4 v[58:61], v114, s[2:3] offset:2048
	global_load_dwordx4 v[62:65], v114, s[2:3] offset:3072
	s_lshl_b32 s11, s9, 12
	s_add_u32 s0, s4, s11
	s_addc_u32 s1, s5, 0
	s_lshl_b32 s11, s9, 11
	s_add_u32 s11, s11, 0x39c0000
	s_add_u32 s2, s6, s11
	s_addc_u32 s3, s7, 0
	global_load_dwordx4 v[0:3], v114, s[0:1] offset:0
	global_load_dwordx4 v[4:7], v114, s[0:1] offset:1024
	global_load_dwordx4 v[8:11], v114, s[0:1] offset:2048
	global_load_dwordx4 v[12:15], v114, s[0:1] offset:3072
	s_add_u32 s0, s0, 0x800000
	s_addc_u32 s1, s1, 0
	global_load_dwordx4 v[18:21], v114, s[0:1] offset:0
	global_load_dwordx4 v[22:25], v114, s[0:1] offset:1024
	global_load_dwordx4 v[26:29], v114, s[0:1] offset:2048
	global_load_dwordx4 v[30:33], v114, s[0:1] offset:3072
	s_waitcnt vmcnt(4)
	v_pk_add_f32 v[66:67], v[0:1], v[2:3]
	v_pk_add_f32 v[68:69], v[4:5], v[6:7]
	v_pk_add_f32 v[70:71], v[8:9], v[10:11]
	v_pk_add_f32 v[72:73], v[12:13], v[14:15]
	v_pk_add_f32 v[66:67], v[66:67], v[68:69]
	v_pk_add_f32 v[70:71], v[70:71], v[72:73]
	v_pk_add_f32 v[66:67], v[66:67], v[70:71]
	v_add_f32_e32 v66, v66, v67
	s_nop 1
	v_add_f32_dpp v66, v66, v66 row_shr:1 row_mask:0xf bank_mask:0xf bound_ctrl:1
	s_nop 1
	v_add_f32_dpp v66, v66, v66 row_shr:2 row_mask:0xf bank_mask:0xf bound_ctrl:1
	s_nop 1
	v_add_f32_dpp v66, v66, v66 row_shr:4 row_mask:0xf bank_mask:0xf bound_ctrl:1
	s_nop 1
	v_add_f32_dpp v66, v66, v66 row_shr:8 row_mask:0xf bank_mask:0xf bound_ctrl:1
	s_nop 0
	v_readlane_b32 s9, v66, 15
	v_readlane_b32 s10, v66, 31
	v_readlane_b32 s11, v66, 47
	v_readlane_b32 vcc_lo, v66, 63
	s_nop 1
	v_mov_b32_e32 v66, s9
	v_add_f32_e32 v66, s10, v66
	v_add_f32_e32 v66, s11, v66
	v_add_f32_e32 v66, vcc_lo, v66
	v_mul_f32_e32 v116, 0x3a800000, v66
	v_mov_b32_e32 v117, v116
	v_pk_add_f32 v[0:1], v[0:1], v[116:117] neg_lo:[0,1] neg_hi:[0,1]
	v_pk_add_f32 v[2:3], v[2:3], v[116:117] neg_lo:[0,1] neg_hi:[0,1]
	v_pk_add_f32 v[4:5], v[4:5], v[116:117] neg_lo:[0,1] neg_hi:[0,1]
	v_pk_add_f32 v[6:7], v[6:7], v[116:117] neg_lo:[0,1] neg_hi:[0,1]
	v_pk_add_f32 v[8:9], v[8:9], v[116:117] neg_lo:[0,1] neg_hi:[0,1]
	v_pk_add_f32 v[10:11], v[10:11], v[116:117] neg_lo:[0,1] neg_hi:[0,1]
	v_pk_add_f32 v[12:13], v[12:13], v[116:117] neg_lo:[0,1] neg_hi:[0,1]
	v_pk_add_f32 v[14:15], v[14:15], v[116:117] neg_lo:[0,1] neg_hi:[0,1]
	v_pk_mul_f32 v[66:67], v[0:1], v[0:1]
	v_pk_mul_f32 v[68:69], v[2:3], v[2:3]
	v_pk_fma_f32 v[66:67], v[4:5], v[4:5], v[66:67]
	v_pk_fma_f32 v[68:69], v[6:7], v[6:7], v[68:69]
	v_pk_fma_f32 v[66:67], v[8:9], v[8:9], v[66:67]
	v_pk_fma_f32 v[68:69], v[10:11], v[10:11], v[68:69]
	v_pk_fma_f32 v[66:67], v[12:13], v[12:13], v[66:67]
	v_pk_fma_f32 v[68:69], v[14:15], v[14:15], v[68:69]
	v_pk_add_f32 v[66:67], v[66:67], v[68:69]
	v_add_f32_e32 v66, v66, v67
	s_nop 1
	v_add_f32_dpp v66, v66, v66 row_shr:1 row_mask:0xf bank_mask:0xf bound_ctrl:1
	s_nop 1
	v_add_f32_dpp v66, v66, v66 row_shr:2 row_mask:0xf bank_mask:0xf bound_ctrl:1
	s_nop 1
	v_add_f32_dpp v66, v66, v66 row_shr:4 row_mask:0xf bank_mask:0xf bound_ctrl:1
	s_nop 1
	v_add_f32_dpp v66, v66, v66 row_shr:8 row_mask:0xf bank_mask:0xf bound_ctrl:1
	s_nop 0
	v_readlane_b32 s9, v66, 15
	v_readlane_b32 s10, v66, 31
	v_readlane_b32 s11, v66, 47
	v_readlane_b32 vcc_lo, v66, 63
	s_nop 1
	v_mov_b32_e32 v66, s9
	v_add_f32_e32 v66, s10, v66
	v_add_f32_e32 v66, s11, v66
	v_add_f32_e32 v66, vcc_lo, v66
	v_mul_f32_e32 v66, 0x3a800000, v66
	v_add_f32_e32 v66, 0x3727c5ac, v66
	v_rsq_f32_e32 v118, v66
	s_nop 0
	v_mov_b32_e32 v119, v118
	v_pk_mul_f32 v[0:1], v[0:1], v[118:119]
	v_pk_mul_f32 v[2:3], v[2:3], v[118:119]
	v_pk_mul_f32 v[4:5], v[4:5], v[118:119]
	v_pk_mul_f32 v[6:7], v[6:7], v[118:119]
	v_pk_mul_f32 v[8:9], v[8:9], v[118:119]
	v_pk_mul_f32 v[10:11], v[10:11], v[118:119]
	v_pk_mul_f32 v[12:13], v[12:13], v[118:119]
	v_pk_mul_f32 v[14:15], v[14:15], v[118:119]
	v_pk_fma_f32 v[76:77], v[0:1], v[34:35], v[50:51]
	v_pk_fma_f32 v[78:79], v[2:3], v[36:37], v[52:53]
	v_pk_fma_f32 v[80:81], v[4:5], v[38:39], v[54:55]
	v_pk_fma_f32 v[82:83], v[6:7], v[40:41], v[56:57]
	v_pk_fma_f32 v[84:85], v[8:9], v[42:43], v[58:59]
	v_pk_fma_f32 v[86:87], v[10:11], v[44:45], v[60:61]
	v_pk_fma_f32 v[88:89], v[12:13], v[46:47], v[62:63]
	v_pk_fma_f32 v[90:91], v[14:15], v[48:49], v[64:65]
	s_cmp_lg_u32 s8, 0
	s_cbranch_scc1 .Lln2_f32_0
	v_cvt_pk_bf16_f32 v92, v76, v77
	v_cvt_pk_bf16_f32 v93, v78, v79
	v_cvt_pk_bf16_f32 v94, v80, v81
	v_cvt_pk_bf16_f32 v95, v82, v83
	v_cvt_pk_bf16_f32 v96, v84, v85
	v_cvt_pk_bf16_f32 v97, v86, v87
	v_cvt_pk_bf16_f32 v98, v88, v89
	v_cvt_pk_bf16_f32 v99, v90, v91
	global_store_dwordx2 v115, v[92:93], s[2:3] offset:0 sc1
	global_store_dwordx2 v115, v[94:95], s[2:3] offset:512 sc1
	global_store_dwordx2 v115, v[96:97], s[2:3] offset:1024 sc1
	global_store_dwordx2 v115, v[98:99], s[2:3] offset:1536 sc1
	s_branch .Lln2_st_0
; __device__ __forceinline__ void phase_ln(float* R, const float* __restrict__ g, const float* __restrict__ b, bf16_t* xbf, float samp_scale, const float* __restrict__ part, int nsplit, bool f32_all) {
;     ...
;   for (int r = gw; r < MT; r += nw) {
;     float* row = R + (size_t)r * 1024;
;     f32x4 v[4];
; #pragma unroll
;     for (int i = 0; i < 4; ++i) v[i] = *(const f32x4*)(row + i * 256 + lane * 4);
;     if (r >= MP) {
;       for (int sp = 0; sp < nsplit; ++sp) {
;         const float* prow = part + ((size_t)sp * MS + (r - MP)) * 1024;
; #pragma unroll
;         for (int i = 0; i < 4; ++i) v[i] = v[i] + *(const f32x4*)(prow + i * 256 + lane * 4);
;       }
;     }
;     float s = 0.f;
; #pragma unroll
;     for (int i = 0; i < 4; ++i) s += v[i][0] + v[i][1] + v[i][2] + v[i][3];
; #pragma unroll
;     for (int o = 32; o >= 1; o >>= 1) s += __shfl_xor(s, o);
;     const float mean = s * (1.f / 1024.f);
;     float ss = 0.f;
; #pragma unroll
;     for (int i = 0; i < 4; ++i) { v[i] = v[i] - mean; ss += v[i][0] * v[i][0] + v[i][1] * v[i][1] + v[i][2] * v[i][2] + v[i][3] * v[i][3]; }
; #pragma unroll
;     for (int o = 32; o >= 1; o >>= 1) ss += __shfl_xor(ss, o);
;     const float rstd = rsqrtf(ss * (1.f / 1024.f) + LN_EPS);
; #pragma unroll
;     for (int i = 0; i < 4; ++i) {
;       const f32x4 y = v[i] * rstd * gv[i] + bv[i];
;       if (r >= MP) *(f32x4*)(row + i * 256 + lane * 4) = y * samp_scale;
;       else if (f32_all) *(f32x4*)(row + i * 256 + lane * 4) = y;
;       if (xbf) {
;         u32x2 wv;
;         wv[0] = cvt_pk_bf16(y[0], y[1]); wv[1] = cvt_pk_bf16(y[2], y[3]);
;         *(u32x2*)(xbf + (size_t)r * 1024 + i * 256 + lane * 4) = wv;
.Lln2_f32_0:
	s_sub_u32 s10, s0, 0x800000
	s_subb_u32 s11, s1, 0
	global_store_dwordx4 v114, v[76:79], s[10:11] offset:0 sc1
	global_store_dwordx4 v114, v[80:83], s[10:11] offset:1024 sc1
	global_store_dwordx4 v114, v[84:87], s[10:11] offset:2048 sc1
	global_store_dwordx4 v114, v[88:91], s[10:11] offset:3072 sc1
.Lln2_st_0:
	s_add_u32 s2, s2, 0x400000
	s_addc_u32 s3, s3, 0
	s_add_u32 s0, s0, 0x800000
	s_addc_u32 s1, s1, 0
	global_load_dwordx4 v[0:3], v114, s[0:1] offset:0
	global_load_dwordx4 v[4:7], v114, s[0:1] offset:1024
	global_load_dwordx4 v[8:11], v114, s[0:1] offset:2048
	global_load_dwordx4 v[12:15], v114, s[0:1] offset:3072
	s_waitcnt vmcnt(8)
	v_pk_add_f32 v[66:67], v[18:19], v[20:21]
	v_pk_add_f32 v[68:69], v[22:23], v[24:25]
	v_pk_add_f32 v[70:71], v[26:27], v[28:29]
	v_pk_add_f32 v[72:73], v[30:31], v[32:33]
	v_pk_add_f32 v[66:67], v[66:67], v[68:69]
	v_pk_add_f32 v[70:71], v[70:71], v[72:73]
	v_pk_add_f32 v[66:67], v[66:67], v[70:71]
	v_add_f32_e32 v66, v66, v67
	s_nop 1
	v_add_f32_dpp v66, v66, v66 row_shr:1 row_mask:0xf bank_mask:0xf bound_ctrl:1
	s_nop 1
	v_add_f32_dpp v66, v66, v66 row_shr:2 row_mask:0xf bank_mask:0xf bound_ctrl:1
	s_nop 1
	v_add_f32_dpp v66, v66, v66 row_shr:4 row_mask:0xf bank_mask:0xf bound_ctrl:1
	s_nop 1
	v_add_f32_dpp v66, v66, v66 row_shr:8 row_mask:0xf bank_mask:0xf bound_ctrl:1
	s_nop 0
	v_readlane_b32 s9, v66, 15
	v_readlane_b32 s10, v66, 31
	v_readlane_b32 s11, v66, 47
	v_readlane_b32 vcc_lo, v66, 63
	s_nop 1
	v_mov_b32_e32 v66, s9
	v_add_f32_e32 v66, s10, v66
	v_add_f32_e32 v66, s11, v66
	v_add_f32_e32 v66, vcc_lo, v66
	v_mul_f32_e32 v116, 0x3a800000, v66
	v_mov_b32_e32 v117, v116
	v_pk_add_f32 v[18:19], v[18:19], v[116:117] neg_lo:[0,1] neg_hi:[0,1]
	v_pk_add_f32 v[20:21], v[20:21], v[116:117] neg_lo:[0,1] neg_hi:[0,1]
	v_pk_add_f32 v[22:23], v[22:23], v[116:117] neg_lo:[0,1] neg_hi:[0,1]
	v_pk_add_f32 v[24:25], v[24:25], v[116:117] neg_lo:[0,1] neg_hi:[0,1]
	v_pk_add_f32 v[26:27], v[26:27], v[116:117] neg_lo:[0,1] neg_hi:[0,1]
	v_pk_add_f32 v[28:29], v[28:29], v[116:117] neg_lo:[0,1] neg_hi:[0,1]
	v_pk_add_f32 v[30:31], v[30:31], v[116:117] neg_lo:[0,1] neg_hi:[0,1]
	v_pk_add_f32 v[32:33], v[32:33], v[116:117] neg_lo:[0,1] neg_hi:[0,1]
	v_pk_mul_f32 v[66:67], v[18:19], v[18:19]
	v_pk_mul_f32 v[68:69], v[20:21], v[20:21]
	v_pk_fma_f32 v[66:67], v[22:23], v[22:23], v[66:67]
	v_pk_fma_f32 v[68:69], v[24:25], v[24:25], v[68:69]
	v_pk_fma_f32 v[66:67], v[26:27], v[26:27], v[66:67]
	v_pk_fma_f32 v[68:69], v[28:29], v[28:29], v[68:69]
	v_pk_fma_f32 v[66:67], v[30:31], v[30:31], v[66:67]
	v_pk_fma_f32 v[68:69], v[32:33], v[32:33], v[68:69]
	v_pk_add_f32 v[66:67], v[66:67], v[68:69]
	v_add_f32_e32 v66, v66, v67
	s_nop 1
	v_add_f32_dpp v66, v66, v66 row_shr:1 row_mask:0xf bank_mask:0xf bound_ctrl:1
	s_nop 1
	v_add_f32_dpp v66, v66, v66 row_shr:2 row_mask:0xf bank_mask:0xf bound_ctrl:1
	s_nop 1
	v_add_f32_dpp v66, v66, v66 row_shr:4 row_mask:0xf bank_mask:0xf bound_ctrl:1
	s_nop 1
	v_add_f32_dpp v66, v66, v66 row_shr:8 row_mask:0xf bank_mask:0xf bound_ctrl:1
	s_nop 0
	v_readlane_b32 s9, v66, 15
	v_readlane_b32 s10, v66, 31
	v_readlane_b32 s11, v66, 47
	v_readlane_b32 vcc_lo, v66, 63
	s_nop 1
	v_mov_b32_e32 v66, s9
	v_add_f32_e32 v66, s10, v66
	v_add_f32_e32 v66, s11, v66
	v_add_f32_e32 v66, vcc_lo, v66
	v_mul_f32_e32 v66, 0x3a800000, v66
	v_add_f32_e32 v66, 0x3727c5ac, v66
	v_rsq_f32_e32 v118, v66
	s_nop 0
	v_mov_b32_e32 v119, v118
	v_pk_mul_f32 v[18:19], v[18:19], v[118:119]
	v_pk_mul_f32 v[20:21], v[20:21], v[118:119]
	v_pk_mul_f32 v[22:23], v[22:23], v[118:119]
	v_pk_mul_f32 v[24:25], v[24:25], v[118:119]
	v_pk_mul_f32 v[26:27], v[26:27], v[118:119]
	v_pk_mul_f32 v[28:29], v[28:29], v[118:119]
	v_pk_mul_f32 v[30:31], v[30:31], v[118:119]
	v_pk_mul_f32 v[32:33], v[32:33], v[118:119]
	v_pk_fma_f32 v[76:77], v[18:19], v[34:35], v[50:51]
	v_pk_fma_f32 v[78:79], v[20:21], v[36:37], v[52:53]
	v_pk_fma_f32 v[80:81], v[22:23], v[38:39], v[54:55]
	v_pk_fma_f32 v[82:83], v[24:25], v[40:41], v[56:57]
	v_pk_fma_f32 v[84:85], v[26:27], v[42:43], v[58:59]
	v_pk_fma_f32 v[86:87], v[28:29], v[44:45], v[60:61]
	v_pk_fma_f32 v[88:89], v[30:31], v[46:47], v[62:63]
	v_pk_fma_f32 v[90:91], v[32:33], v[48:49], v[64:65]
	s_cmp_lg_u32 s8, 0
	s_cbranch_scc1 .Lln2_f32_1
	v_cvt_pk_bf16_f32 v92, v76, v77
	v_cvt_pk_bf16_f32 v93, v78, v79
	v_cvt_pk_bf16_f32 v94, v80, v81
	v_cvt_pk_bf16_f32 v95, v82, v83
	v_cvt_pk_bf16_f32 v96, v84, v85
	v_cvt_pk_bf16_f32 v97, v86, v87
	v_cvt_pk_bf16_f32 v98, v88, v89
	v_cvt_pk_bf16_f32 v99, v90, v91
	global_store_dwordx2 v115, v[92:93], s[2:3] offset:0 sc1
	global_store_dwordx2 v115, v[94:95], s[2:3] offset:512 sc1
	global_store_dwordx2 v115, v[96:97], s[2:3] offset:1024 sc1
	global_store_dwordx2 v115, v[98:99], s[2:3] offset:1536 sc1
	s_branch .Lln2_st_1

; __device__ __forceinline__ void phase_ln(float* R, const float* __restrict__ g, const float* __restrict__ b, bf16_t* xbf, float samp_scale, const float* __restrict__ part, int nsplit, bool f32_all) {
;     ...
;   for (int r = gw; r < MT; r += nw) {
;     float* row = R + (size_t)r * 1024;
;     f32x4 v[4];
; #pragma unroll
;     for (int i = 0; i < 4; ++i) v[i] = *(const f32x4*)(row + i * 256 + lane * 4);
;     if (r >= MP) {
;       for (int sp = 0; sp < nsplit; ++sp) {
;         const float* prow = part + ((size_t)sp * MS + (r - MP)) * 1024;
; #pragma unroll
;         for (int i = 0; i < 4; ++i) v[i] = v[i] + *(const f32x4*)(prow + i * 256 + lane * 4);
;       }
;     }
;     float s = 0.f;
; #pragma unroll
;     for (int i = 0; i < 4; ++i) s += v[i][0] + v[i][1] + v[i][2] + v[i][3];
; #pragma unroll
;     for (int o = 32; o >= 1; o >>= 1) s += __shfl_xor(s, o);
;     const float mean = s * (1.f / 1024.f);
;     float ss = 0.f;
; #pragma unroll
;     for (int i = 0; i < 4; ++i) { v[i] = v[i] - mean; ss += v[i][0] * v[i][0] + v[i][1] * v[i][1] + v[i][2] * v[i][2] + v[i][3] * v[i][3]; }
; #pragma unroll
;     for (int o = 32; o >= 1; o >>= 1) ss += __shfl_xor(ss, o);
;     const float rstd = rsqrtf(ss * (1.f / 1024.f) + LN_EPS);
; #pragma unroll
;     for (int i = 0; i < 4; ++i) {
;       const f32x4 y = v[i] * rstd * gv[i] + bv[i];
;       if (r >= MP) *(f32x4*)(row + i * 256 + lane * 4) = y * samp_scale;
;       else if (f32_all) *(f32x4*)(row + i * 256 + lane * 4) = y;
;       if (xbf) {
;         u32x2 wv;
;         wv[0] = cvt_pk_bf16(y[0], y[1]); wv[1] = cvt_pk_bf16(y[2], y[3]);
;         *(u32x2*)(xbf + (size_t)r * 1024 + i * 256 + lane * 4) = wv;
.Lln2_st_1:
	s_add_u32 s2, s2, 0x400000
	s_addc_u32 s3, s3, 0
	s_add_u32 s0, s0, 0x800000
	s_addc_u32 s1, s1, 0
	global_load_dwordx4 v[18:21], v114, s[0:1] offset:0
	global_load_dwordx4 v[22:25], v114, s[0:1] offset:1024
	global_load_dwordx4 v[26:29], v114, s[0:1] offset:2048
	global_load_dwordx4 v[30:33], v114, s[0:1] offset:3072
	s_waitcnt vmcnt(8)
	v_pk_add_f32 v[66:67], v[0:1], v[2:3]
	v_pk_add_f32 v[68:69], v[4:5], v[6:7]
	v_pk_add_f32 v[70:71], v[8:9], v[10:11]
	v_pk_add_f32 v[72:73], v[12:13], v[14:15]
	v_pk_add_f32 v[66:67], v[66:67], v[68:69]
	v_pk_add_f32 v[70:71], v[70:71], v[72:73]
	v_pk_add_f32 v[66:67], v[66:67], v[70:71]
	v_add_f32_e32 v66, v66, v67
	s_nop 1
	v_add_f32_dpp v66, v66, v66 row_shr:1 row_mask:0xf bank_mask:0xf bound_ctrl:1
	s_nop 1
	v_add_f32_dpp v66, v66, v66 row_shr:2 row_mask:0xf bank_mask:0xf bound_ctrl:1
	s_nop 1
	v_add_f32_dpp v66, v66, v66 row_shr:4 row_mask:0xf bank_mask:0xf bound_ctrl:1
	s_nop 1
	v_add_f32_dpp v66, v66, v66 row_shr:8 row_mask:0xf bank_mask:0xf bound_ctrl:1
	s_nop 0
	v_readlane_b32 s9, v66, 15
	v_readlane_b32 s10, v66, 31
	v_readlane_b32 s11, v66, 47
	v_readlane_b32 vcc_lo, v66, 63
	s_nop 1
	v_mov_b32_e32 v66, s9
	v_add_f32_e32 v66, s10, v66
	v_add_f32_e32 v66, s11, v66
	v_add_f32_e32 v66, vcc_lo, v66
	v_mul_f32_e32 v116, 0x3a800000, v66
	v_mov_b32_e32 v117, v116
	v_pk_add_f32 v[0:1], v[0:1], v[116:117] neg_lo:[0,1] neg_hi:[0,1]
	v_pk_add_f32 v[2:3], v[2:3], v[116:117] neg_lo:[0,1] neg_hi:[0,1]
	v_pk_add_f32 v[4:5], v[4:5], v[116:117] neg_lo:[0,1] neg_hi:[0,1]
	v_pk_add_f32 v[6:7], v[6:7], v[116:117] neg_lo:[0,1] neg_hi:[0,1]
	v_pk_add_f32 v[8:9], v[8:9], v[116:117] neg_lo:[0,1] neg_hi:[0,1]
	v_pk_add_f32 v[10:11], v[10:11], v[116:117] neg_lo:[0,1] neg_hi:[0,1]
	v_pk_add_f32 v[12:13], v[12:13], v[116:117] neg_lo:[0,1] neg_hi:[0,1]
	v_pk_add_f32 v[14:15], v[14:15], v[116:117] neg_lo:[0,1] neg_hi:[0,1]
	v_pk_mul_f32 v[66:67], v[0:1], v[0:1]
	v_pk_mul_f32 v[68:69], v[2:3], v[2:3]
	v_pk_fma_f32 v[66:67], v[4:5], v[4:5], v[66:67]
	v_pk_fma_f32 v[68:69], v[6:7], v[6:7], v[68:69]
	v_pk_fma_f32 v[66:67], v[8:9], v[8:9], v[66:67]
	v_pk_fma_f32 v[68:69], v[10:11], v[10:11], v[68:69]
	v_pk_fma_f32 v[66:67], v[12:13], v[12:13], v[66:67]
	v_pk_fma_f32 v[68:69], v[14:15], v[14:15], v[68:69]
	v_pk_add_f32 v[66:67], v[66:67], v[68:69]
	v_add_f32_e32 v66, v66, v67
	s_nop 1
	v_add_f32_dpp v66, v66, v66 row_shr:1 row_mask:0xf bank_mask:0xf bound_ctrl:1
	s_nop 1
	v_add_f32_dpp v66, v66, v66 row_shr:2 row_mask:0xf bank_mask:0xf bound_ctrl:1
	s_nop 1
	v_add_f32_dpp v66, v66, v66 row_shr:4 row_mask:0xf bank_mask:0xf bound_ctrl:1
	s_nop 1
	v_add_f32_dpp v66, v66, v66 row_shr:8 row_mask:0xf bank_mask:0xf bound_ctrl:1
	s_nop 0
	v_readlane_b32 s9, v66, 15
	v_readlane_b32 s10, v66, 31
	v_readlane_b32 s11, v66, 47
	v_readlane_b32 vcc_lo, v66, 63
	s_nop 1
	v_mov_b32_e32 v66, s9
	v_add_f32_e32 v66, s10, v66
	v_add_f32_e32 v66, s11, v66
	v_add_f32_e32 v66, vcc_lo, v66
	v_mul_f32_e32 v66, 0x3a800000, v66
	v_add_f32_e32 v66, 0x3727c5ac, v66
	v_rsq_f32_e32 v118, v66
	s_nop 0
	v_mov_b32_e32 v119, v118
	v_pk_mul_f32 v[0:1], v[0:1], v[118:119]
	v_pk_mul_f32 v[2:3], v[2:3], v[118:119]
	v_pk_mul_f32 v[4:5], v[4:5], v[118:119]
	v_pk_mul_f32 v[6:7], v[6:7], v[118:119]
	v_pk_mul_f32 v[8:9], v[8:9], v[118:119]
	v_pk_mul_f32 v[10:11], v[10:11], v[118:119]
	v_pk_mul_f32 v[12:13], v[12:13], v[118:119]
	v_pk_mul_f32 v[14:15], v[14:15], v[118:119]
	v_pk_fma_f32 v[76:77], v[0:1], v[34:35], v[50:51]
	v_pk_fma_f32 v[78:79], v[2:3], v[36:37], v[52:53]
	v_pk_fma_f32 v[80:81], v[4:5], v[38:39], v[54:55]
	v_pk_fma_f32 v[82:83], v[6:7], v[40:41], v[56:57]
	v_pk_fma_f32 v[84:85], v[8:9], v[42:43], v[58:59]
	v_pk_fma_f32 v[86:87], v[10:11], v[44:45], v[60:61]
	v_pk_fma_f32 v[88:89], v[12:13], v[46:47], v[62:63]
	v_pk_fma_f32 v[90:91], v[14:15], v[48:49], v[64:65]
	s_cmp_lg_u32 s8, 0
	s_cbranch_scc1 .Lln2_f32_2
	v_cvt_pk_bf16_f32 v92, v76, v77
	v_cvt_pk_bf16_f32 v93, v78, v79
	v_cvt_pk_bf16_f32 v94, v80, v81
	v_cvt_pk_bf16_f32 v95, v82, v83
	v_cvt_pk_bf16_f32 v96, v84, v85
	v_cvt_pk_bf16_f32 v97, v86, v87
	v_cvt_pk_bf16_f32 v98, v88, v89
	v_cvt_pk_bf16_f32 v99, v90, v91
	global_store_dwordx2 v115, v[92:93], s[2:3] offset:0 sc1
	global_store_dwordx2 v115, v[94:95], s[2:3] offset:512 sc1
	global_store_dwordx2 v115, v[96:97], s[2:3] offset:1024 sc1
	global_store_dwordx2 v115, v[98:99], s[2:3] offset:1536 sc1
	s_branch .Lln2_st_2

; __device__ __forceinline__ void phase_ln(float* R, const float* __restrict__ g, const float* __restrict__ b, bf16_t* xbf, float samp_scale, const float* __restrict__ part, int nsplit, bool f32_all) {
;     ...
;     float s = 0.f;
; #pragma unroll
;     for (int i = 0; i < 4; ++i) s += v[i][0] + v[i][1] + v[i][2] + v[i][3];
; #pragma unroll
;     for (int o = 32; o >= 1; o >>= 1) s += __shfl_xor(s, o);
;     const float mean = s * (1.f / 1024.f);
;     float ss = 0.f;
; #pragma unroll
;     for (int i = 0; i < 4; ++i) { v[i] = v[i] - mean; ss += v[i][0] * v[i][0] + v[i][1] * v[i][1] + v[i][2] * v[i][2] + v[i][3] * v[i][3]; }
; #pragma unroll
;     for (int o = 32; o >= 1; o >>= 1) ss += __shfl_xor(ss, o);
;     const float rstd = rsqrtf(ss * (1.f / 1024.f) + LN_EPS);
; #pragma unroll
;     for (int i = 0; i < 4; ++i) {
;       const f32x4 y = v[i] * rstd * gv[i] + bv[i];
;       if (r >= MP) *(f32x4*)(row + i * 256 + lane * 4) = y * samp_scale;
;       else if (f32_all) *(f32x4*)(row + i * 256 + lane * 4) = y;
;       if (xbf) {
;         u32x2 wv;
;         wv[0] = cvt_pk_bf16(y[0], y[1]); wv[1] = cvt_pk_bf16(y[2], y[3]);
;         *(u32x2*)(xbf + (size_t)r * 1024 + i * 256 + lane * 4) = wv;
.Lln2_st_14:
	s_add_u32 s2, s2, 0x400000
	s_addc_u32 s3, s3, 0
	s_waitcnt vmcnt(4)
	v_pk_add_f32 v[66:67], v[18:19], v[20:21]
	v_pk_add_f32 v[68:69], v[22:23], v[24:25]
	v_pk_add_f32 v[70:71], v[26:27], v[28:29]
	v_pk_add_f32 v[72:73], v[30:31], v[32:33]
	v_pk_add_f32 v[66:67], v[66:67], v[68:69]
	v_pk_add_f32 v[70:71], v[70:71], v[72:73]
	v_pk_add_f32 v[66:67], v[66:67], v[70:71]
	v_add_f32_e32 v66, v66, v67
	s_nop 1
	v_add_f32_dpp v66, v66, v66 row_shr:1 row_mask:0xf bank_mask:0xf bound_ctrl:1
	s_nop 1
	v_add_f32_dpp v66, v66, v66 row_shr:2 row_mask:0xf bank_mask:0xf bound_ctrl:1
	s_nop 1
	v_add_f32_dpp v66, v66, v66 row_shr:4 row_mask:0xf bank_mask:0xf bound_ctrl:1
	s_nop 1
	v_add_f32_dpp v66, v66, v66 row_shr:8 row_mask:0xf bank_mask:0xf bound_ctrl:1
	s_nop 0
	v_readlane_b32 s9, v66, 15
	v_readlane_b32 s10, v66, 31
	v_readlane_b32 s11, v66, 47
	v_readlane_b32 vcc_lo, v66, 63
	s_nop 1
	v_mov_b32_e32 v66, s9
	v_add_f32_e32 v66, s10, v66
	v_add_f32_e32 v66, s11, v66
	v_add_f32_e32 v66, vcc_lo, v66
	v_mul_f32_e32 v116, 0x3a800000, v66
	v_mov_b32_e32 v117, v116
	v_pk_add_f32 v[18:19], v[18:19], v[116:117] neg_lo:[0,1] neg_hi:[0,1]
	v_pk_add_f32 v[20:21], v[20:21], v[116:117] neg_lo:[0,1] neg_hi:[0,1]
	v_pk_add_f32 v[22:23], v[22:23], v[116:117] neg_lo:[0,1] neg_hi:[0,1]
	v_pk_add_f32 v[24:25], v[24:25], v[116:117] neg_lo:[0,1] neg_hi:[0,1]
	v_pk_add_f32 v[26:27], v[26:27], v[116:117] neg_lo:[0,1] neg_hi:[0,1]
	v_pk_add_f32 v[28:29], v[28:29], v[116:117] neg_lo:[0,1] neg_hi:[0,1]
	v_pk_add_f32 v[30:31], v[30:31], v[116:117] neg_lo:[0,1] neg_hi:[0,1]
	v_pk_add_f32 v[32:33], v[32:33], v[116:117] neg_lo:[0,1] neg_hi:[0,1]
	v_pk_mul_f32 v[66:67], v[18:19], v[18:19]
	v_pk_mul_f32 v[68:69], v[20:21], v[20:21]
	v_pk_fma_f32 v[66:67], v[22:23], v[22:23], v[66:67]
	v_pk_fma_f32 v[68:69], v[24:25], v[24:25], v[68:69]
	v_pk_fma_f32 v[66:67], v[26:27], v[26:27], v[66:67]
	v_pk_fma_f32 v[68:69], v[28:29], v[28:29], v[68:69]
	v_pk_fma_f32 v[66:67], v[30:31], v[30:31], v[66:67]
	v_pk_fma_f32 v[68:69], v[32:33], v[32:33], v[68:69]
	v_pk_add_f32 v[66:67], v[66:67], v[68:69]
	v_add_f32_e32 v66, v66, v67
	s_nop 1
	v_add_f32_dpp v66, v66, v66 row_shr:1 row_mask:0xf bank_mask:0xf bound_ctrl:1
	s_nop 1
	v_add_f32_dpp v66, v66, v66 row_shr:2 row_mask:0xf bank_mask:0xf bound_ctrl:1
	s_nop 1
	v_add_f32_dpp v66, v66, v66 row_shr:4 row_mask:0xf bank_mask:0xf bound_ctrl:1
	s_nop 1
	v_add_f32_dpp v66, v66, v66 row_shr:8 row_mask:0xf bank_mask:0xf bound_ctrl:1
	s_nop 0
	v_readlane_b32 s9, v66, 15
	v_readlane_b32 s10, v66, 31
	v_readlane_b32 s11, v66, 47
	v_readlane_b32 vcc_lo, v66, 63
	s_nop 1
	v_mov_b32_e32 v66, s9
	v_add_f32_e32 v66, s10, v66
	v_add_f32_e32 v66, s11, v66
	v_add_f32_e32 v66, vcc_lo, v66
	v_mul_f32_e32 v66, 0x3a800000, v66
	v_add_f32_e32 v66, 0x3727c5ac, v66
	v_rsq_f32_e32 v118, v66
	s_nop 0
	v_mov_b32_e32 v119, v118
	v_pk_mul_f32 v[18:19], v[18:19], v[118:119]
	v_pk_mul_f32 v[20:21], v[20:21], v[118:119]
	v_pk_mul_f32 v[22:23], v[22:23], v[118:119]
	v_pk_mul_f32 v[24:25], v[24:25], v[118:119]
	v_pk_mul_f32 v[26:27], v[26:27], v[118:119]
	v_pk_mul_f32 v[28:29], v[28:29], v[118:119]
	v_pk_mul_f32 v[30:31], v[30:31], v[118:119]
	v_pk_mul_f32 v[32:33], v[32:33], v[118:119]
	v_pk_fma_f32 v[76:77], v[18:19], v[34:35], v[50:51]
	v_pk_fma_f32 v[78:79], v[20:21], v[36:37], v[52:53]
	v_pk_fma_f32 v[80:81], v[22:23], v[38:39], v[54:55]
	v_pk_fma_f32 v[82:83], v[24:25], v[40:41], v[56:57]
	v_pk_fma_f32 v[84:85], v[26:27], v[42:43], v[58:59]
	v_pk_fma_f32 v[86:87], v[28:29], v[44:45], v[60:61]
	v_pk_fma_f32 v[88:89], v[30:31], v[46:47], v[62:63]
	v_pk_fma_f32 v[90:91], v[32:33], v[48:49], v[64:65]
	s_cmp_lg_u32 s8, 0
	s_cbranch_scc1 .Lln2_f32_15
	v_cvt_pk_bf16_f32 v92, v76, v77
	v_cvt_pk_bf16_f32 v93, v78, v79
	v_cvt_pk_bf16_f32 v94, v80, v81
	v_cvt_pk_bf16_f32 v95, v82, v83
	v_cvt_pk_bf16_f32 v96, v84, v85
	v_cvt_pk_bf16_f32 v97, v86, v87
	v_cvt_pk_bf16_f32 v98, v88, v89
	v_cvt_pk_bf16_f32 v99, v90, v91
	global_store_dwordx2 v115, v[92:93], s[2:3] offset:0 sc1
	global_store_dwordx2 v115, v[94:95], s[2:3] offset:512 sc1
	global_store_dwordx2 v115, v[96:97], s[2:3] offset:1024 sc1
	global_store_dwordx2 v115, v[98:99], s[2:3] offset:1536 sc1
	s_branch .Lln2_st_15
.Lln2_f32_15:
	global_store_dwordx4 v114, v[76:79], s[0:1] offset:0 sc1
	global_store_dwordx4 v114, v[80:83], s[0:1] offset:1024 sc1
	global_store_dwordx4 v114, v[84:87], s[0:1] offset:2048 sc1
	global_store_dwordx4 v114, v[88:91], s[0:1] offset:3072 sc1
; __device__ __forceinline__ void phase_ln(float* R, const float* __restrict__ g, const float* __restrict__ b, bf16_t* xbf, float samp_scale, const float* __restrict__ part, int nsplit, bool f32_all) {
;     ...
;   for (int r = gw; r < MT; r += nw) {
;     float* row = R + (size_t)r * 1024;
;     f32x4 v[4];
; #pragma unroll
;     for (int i = 0; i < 4; ++i) v[i] = *(const f32x4*)(row + i * 256 + lane * 4);
;     if (r >= MP) {
;       for (int sp = 0; sp < nsplit; ++sp) {
;         const float* prow = part + ((size_t)sp * MS + (r - MP)) * 1024;
; #pragma unroll
;         for (int i = 0; i < 4; ++i) v[i] = v[i] + *(const f32x4*)(prow + i * 256 + lane * 4);
;       }
;     }
.Lln2_st_15:
	s_add_u32 s2, s2, 0x400000
	s_addc_u32 s3, s3, 0
	v_readfirstlane_b32 s10, v244
	v_readlane_b32 s9, v254, 6
	s_lshr_b32 s10, s10, 6
	s_cmp_ge_u32 s10, 2
	s_cbranch_scc1 .Lln2_done
	s_lshl_b32 s9, s9, 1
	s_add_i32 s9, s9, s10
	s_lshl_b32 s11, s9, 12
	s_add_u32 s11, s11, 0x8000000
	s_add_u32 s0, s4, s11
	s_addc_u32 s1, s5, 0
	s_lshl_b32 s11, s9, 11
	s_add_u32 s11, s11, 0x79c0000
	s_add_u32 s2, s6, s11
	s_addc_u32 s3, s7, 0
	s_lshl_b32 s11, s9, 12
	s_add_u32 s11, s11, 0x1e482000
	s_add_u32 s10, s6, s11
	s_addc_u32 s11, s7, 0
	global_load_dwordx4 v[0:3], v114, s[0:1] offset:0
	global_load_dwordx4 v[4:7], v114, s[0:1] offset:1024
	global_load_dwordx4 v[8:11], v114, s[0:1] offset:2048
	global_load_dwordx4 v[12:15], v114, s[0:1] offset:3072
	global_load_dwordx4 v[18:21], v114, s[10:11] offset:0
	global_load_dwordx4 v[22:25], v114, s[10:11] offset:1024
	global_load_dwordx4 v[26:29], v114, s[10:11] offset:2048
	global_load_dwordx4 v[30:33], v114, s[10:11] offset:3072
	s_add_u32 s10, s10, 0x200000
	s_addc_u32 s11, s11, 0
	global_load_dwordx4 v[66:69], v114, s[10:11] offset:0
	global_load_dwordx4 v[70:73], v114, s[10:11] offset:1024
	global_load_dwordx4 v[74:77], v114, s[10:11] offset:2048
	global_load_dwordx4 v[78:81], v114, s[10:11] offset:3072
	s_add_u32 s10, s10, 0x200000
	s_addc_u32 s11, s11, 0
	global_load_dwordx4 v[82:85], v114, s[10:11] offset:0
	global_load_dwordx4 v[86:89], v114, s[10:11] offset:1024
	global_load_dwordx4 v[90:93], v114, s[10:11] offset:2048
	global_load_dwordx4 v[94:97], v114, s[10:11] offset:3072
	s_add_u32 s10, s10, 0x200000
	s_addc_u32 s11, s11, 0
	global_load_dwordx4 v[98:101], v114, s[10:11] offset:0
	global_load_dwordx4 v[102:105], v114, s[10:11] offset:1024
	global_load_dwordx4 v[106:109], v114, s[10:11] offset:2048
	global_load_dwordx4 v[110:113], v114, s[10:11] offset:3072
	s_add_u32 s10, s10, 0x200000
	s_addc_u32 s11, s11, 0
	s_waitcnt vmcnt(0)
	v_pk_add_f32 v[0:1], v[0:1], v[18:19]
	v_pk_add_f32 v[2:3], v[2:3], v[20:21]
	v_pk_add_f32 v[4:5], v[4:5], v[22:23]
	v_pk_add_f32 v[6:7], v[6:7], v[24:25]
	v_pk_add_f32 v[8:9], v[8:9], v[26:27]
	v_pk_add_f32 v[10:11], v[10:11], v[28:29]
	v_pk_add_f32 v[12:13], v[12:13], v[30:31]
	v_pk_add_f32 v[14:15], v[14:15], v[32:33]
	v_pk_add_f32 v[0:1], v[0:1], v[66:67]
	v_pk_add_f32 v[2:3], v[2:3], v[68:69]
	v_pk_add_f32 v[4:5], v[4:5], v[70:71]
	v_pk_add_f32 v[6:7], v[6:7], v[72:73]
	v_pk_add_f32 v[8:9], v[8:9], v[74:75]
	v_pk_add_f32 v[10:11], v[10:11], v[76:77]
	v_pk_add_f32 v[12:13], v[12:13], v[78:79]
	v_pk_add_f32 v[14:15], v[14:15], v[80:81]
	v_pk_add_f32 v[0:1], v[0:1], v[82:83]
	v_pk_add_f32 v[2:3], v[2:3], v[84:85]
	v_pk_add_f32 v[4:5], v[4:5], v[86:87]
	v_pk_add_f32 v[6:7], v[6:7], v[88:89]
	v_pk_add_f32 v[8:9], v[8:9], v[90:91]
	v_pk_add_f32 v[10:11], v[10:11], v[92:93]
	v_pk_add_f32 v[12:13], v[12:13], v[94:95]
	v_pk_add_f32 v[14:15], v[14:15], v[96:97]
	v_pk_add_f32 v[0:1], v[0:1], v[98:99]
	v_pk_add_f32 v[2:3], v[2:3], v[100:101]
	v_pk_add_f32 v[4:5], v[4:5], v[102:103]
	v_pk_add_f32 v[6:7], v[6:7], v[104:105]
	v_pk_add_f32 v[8:9], v[8:9], v[106:107]
	v_pk_add_f32 v[10:11], v[10:11], v[108:109]
	v_pk_add_f32 v[12:13], v[12:13], v[110:111]
	v_pk_add_f32 v[14:15], v[14:15], v[112:113]
	global_load_dwordx4 v[18:21], v114, s[10:11] offset:0
	global_load_dwordx4 v[22:25], v114, s[10:11] offset:1024
	global_load_dwordx4 v[26:29], v114, s[10:11] offset:2048
	global_load_dwordx4 v[30:33], v114, s[10:11] offset:3072
	s_add_u32 s10, s10, 0x200000
	s_addc_u32 s11, s11, 0
	global_load_dwordx4 v[66:69], v114, s[10:11] offset:0
	global_load_dwordx4 v[70:73], v114, s[10:11] offset:1024
	global_load_dwordx4 v[74:77], v114, s[10:11] offset:2048
	global_load_dwordx4 v[78:81], v114, s[10:11] offset:3072
	s_add_u32 s10, s10, 0x200000
	s_addc_u32 s11, s11, 0
	global_load_dwordx4 v[82:85], v114, s[10:11] offset:0
	global_load_dwordx4 v[86:89], v114, s[10:11] offset:1024
	global_load_dwordx4 v[90:93], v114, s[10:11] offset:2048
	global_load_dwordx4 v[94:97], v114, s[10:11] offset:3072
	s_add_u32 s10, s10, 0x200000
	s_addc_u32 s11, s11, 0
	global_load_dwordx4 v[98:101], v114, s[10:11] offset:0
	global_load_dwordx4 v[102:105], v114, s[10:11] offset:1024
	global_load_dwordx4 v[106:109], v114, s[10:11] offset:2048
	global_load_dwordx4 v[110:113], v114, s[10:11] offset:3072
	s_add_u32 s10, s10, 0x200000
	s_addc_u32 s11, s11, 0
	s_waitcnt vmcnt(0)
; __device__ __forceinline__ void phase_ln(float* R, const float* __restrict__ g, const float* __restrict__ b, bf16_t* xbf, float samp_scale, const float* __restrict__ part, int nsplit, bool f32_all) {
;     ...
; #pragma unroll
;         for (int i = 0; i < 4; ++i) v[i] = v[i] + *(const f32x4*)(prow + i * 256 + lane * 4);
;       }
;     }
;     float s = 0.f;
; #pragma unroll
;     for (int i = 0; i < 4; ++i) s += v[i][0] + v[i][1] + v[i][2] + v[i][3];
; #pragma unroll
;     for (int o = 32; o >= 1; o >>= 1) s += __shfl_xor(s, o);
;     const float mean = s * (1.f / 1024.f);
;     float ss = 0.f;
; #pragma unroll
;     for (int i = 0; i < 4; ++i) { v[i] = v[i] - mean; ss += v[i][0] * v[i][0] + v[i][1] * v[i][1] + v[i][2] * v[i][2] + v[i][3] * v[i][3]; }
; #pragma unroll
;     for (int o = 32; o >= 1; o >>= 1) ss += __shfl_xor(ss, o);
;     const float rstd = rsqrtf(ss * (1.f / 1024.f) + LN_EPS);
; #pragma unroll
;     for (int i = 0; i < 4; ++i) {
;       const f32x4 y = v[i] * rstd * gv[i] + bv[i];
;       if (r >= MP) *(f32x4*)(row + i * 256 + lane * 4) = y * samp_scale;
;       else if (f32_all) *(f32x4*)(row + i * 256 + lane * 4) = y;
;       if (xbf) {
;         u32x2 wv;
;         wv[0] = cvt_pk_bf16(y[0], y[1]); wv[1] = cvt_pk_bf16(y[2], y[3]);
;         *(u32x2*)(xbf + (size_t)r * 1024 + i * 256 + lane * 4) = wv;
;       }
;     }
	v_pk_add_f32 v[0:1], v[0:1], v[18:19]
	v_pk_add_f32 v[2:3], v[2:3], v[20:21]
	v_pk_add_f32 v[4:5], v[4:5], v[22:23]
	v_pk_add_f32 v[6:7], v[6:7], v[24:25]
	v_pk_add_f32 v[8:9], v[8:9], v[26:27]
	v_pk_add_f32 v[10:11], v[10:11], v[28:29]
	v_pk_add_f32 v[12:13], v[12:13], v[30:31]
	v_pk_add_f32 v[14:15], v[14:15], v[32:33]
	v_pk_add_f32 v[0:1], v[0:1], v[66:67]
	v_pk_add_f32 v[2:3], v[2:3], v[68:69]
	v_pk_add_f32 v[4:5], v[4:5], v[70:71]
	v_pk_add_f32 v[6:7], v[6:7], v[72:73]
	v_pk_add_f32 v[8:9], v[8:9], v[74:75]
	v_pk_add_f32 v[10:11], v[10:11], v[76:77]
	v_pk_add_f32 v[12:13], v[12:13], v[78:79]
	v_pk_add_f32 v[14:15], v[14:15], v[80:81]
	v_pk_add_f32 v[0:1], v[0:1], v[82:83]
	v_pk_add_f32 v[2:3], v[2:3], v[84:85]
	v_pk_add_f32 v[4:5], v[4:5], v[86:87]
	v_pk_add_f32 v[6:7], v[6:7], v[88:89]
	v_pk_add_f32 v[8:9], v[8:9], v[90:91]
	v_pk_add_f32 v[10:11], v[10:11], v[92:93]
	v_pk_add_f32 v[12:13], v[12:13], v[94:95]
	v_pk_add_f32 v[14:15], v[14:15], v[96:97]
	v_pk_add_f32 v[0:1], v[0:1], v[98:99]
	v_pk_add_f32 v[2:3], v[2:3], v[100:101]
	v_pk_add_f32 v[4:5], v[4:5], v[102:103]
	v_pk_add_f32 v[6:7], v[6:7], v[104:105]
	v_pk_add_f32 v[8:9], v[8:9], v[106:107]
	v_pk_add_f32 v[10:11], v[10:11], v[108:109]
	v_pk_add_f32 v[12:13], v[12:13], v[110:111]
	v_pk_add_f32 v[14:15], v[14:15], v[112:113]
	v_pk_add_f32 v[66:67], v[0:1], v[2:3]
	v_pk_add_f32 v[68:69], v[4:5], v[6:7]
	v_pk_add_f32 v[70:71], v[8:9], v[10:11]
	v_pk_add_f32 v[72:73], v[12:13], v[14:15]
	v_pk_add_f32 v[66:67], v[66:67], v[68:69]
	v_pk_add_f32 v[70:71], v[70:71], v[72:73]
	v_pk_add_f32 v[66:67], v[66:67], v[70:71]
	v_add_f32_e32 v66, v66, v67
	s_nop 1
	v_add_f32_dpp v66, v66, v66 row_shr:1 row_mask:0xf bank_mask:0xf bound_ctrl:1
	s_nop 1
	v_add_f32_dpp v66, v66, v66 row_shr:2 row_mask:0xf bank_mask:0xf bound_ctrl:1
	s_nop 1
	v_add_f32_dpp v66, v66, v66 row_shr:4 row_mask:0xf bank_mask:0xf bound_ctrl:1
	s_nop 1
	v_add_f32_dpp v66, v66, v66 row_shr:8 row_mask:0xf bank_mask:0xf bound_ctrl:1
	s_nop 0
	v_readlane_b32 s9, v66, 15
	v_readlane_b32 s10, v66, 31
	v_readlane_b32 s11, v66, 47
	v_readlane_b32 vcc_lo, v66, 63
	s_nop 1
	v_mov_b32_e32 v66, s9
	v_add_f32_e32 v66, s10, v66
	v_add_f32_e32 v66, s11, v66
	v_add_f32_e32 v66, vcc_lo, v66
	v_mul_f32_e32 v116, 0x3a800000, v66
	v_mov_b32_e32 v117, v116
	v_pk_add_f32 v[0:1], v[0:1], v[116:117] neg_lo:[0,1] neg_hi:[0,1]
	v_pk_add_f32 v[2:3], v[2:3], v[116:117] neg_lo:[0,1] neg_hi:[0,1]
	v_pk_add_f32 v[4:5], v[4:5], v[116:117] neg_lo:[0,1] neg_hi:[0,1]
	v_pk_add_f32 v[6:7], v[6:7], v[116:117] neg_lo:[0,1] neg_hi:[0,1]
	v_pk_add_f32 v[8:9], v[8:9], v[116:117] neg_lo:[0,1] neg_hi:[0,1]
	v_pk_add_f32 v[10:11], v[10:11], v[116:117] neg_lo:[0,1] neg_hi:[0,1]
	v_pk_add_f32 v[12:13], v[12:13], v[116:117] neg_lo:[0,1] neg_hi:[0,1]
	v_pk_add_f32 v[14:15], v[14:15], v[116:117] neg_lo:[0,1] neg_hi:[0,1]
	v_pk_mul_f32 v[66:67], v[0:1], v[0:1]
	v_pk_mul_f32 v[68:69], v[2:3], v[2:3]
	v_pk_fma_f32 v[66:67], v[4:5], v[4:5], v[66:67]
	v_pk_fma_f32 v[68:69], v[6:7], v[6:7], v[68:69]
	v_pk_fma_f32 v[66:67], v[8:9], v[8:9], v[66:67]
	v_pk_fma_f32 v[68:69], v[10:11], v[10:11], v[68:69]
	v_pk_fma_f32 v[66:67], v[12:13], v[12:13], v[66:67]
	v_pk_fma_f32 v[68:69], v[14:15], v[14:15], v[68:69]
	v_pk_add_f32 v[66:67], v[66:67], v[68:69]
	v_add_f32_e32 v66, v66, v67
	s_nop 1
	v_add_f32_dpp v66, v66, v66 row_shr:1 row_mask:0xf bank_mask:0xf bound_ctrl:1
	s_nop 1
	v_add_f32_dpp v66, v66, v66 row_shr:2 row_mask:0xf bank_mask:0xf bound_ctrl:1
	s_nop 1
	v_add_f32_dpp v66, v66, v66 row_shr:4 row_mask:0xf bank_mask:0xf bound_ctrl:1
	s_nop 1
	v_add_f32_dpp v66, v66, v66 row_shr:8 row_mask:0xf bank_mask:0xf bound_ctrl:1
	s_nop 0
	v_readlane_b32 s9, v66, 15
	v_readlane_b32 s10, v66, 31
	v_readlane_b32 s11, v66, 47
	v_readlane_b32 vcc_lo, v66, 63
	s_nop 1
	v_mov_b32_e32 v66, s9
	v_add_f32_e32 v66, s10, v66
	v_add_f32_e32 v66, s11, v66
	v_add_f32_e32 v66, vcc_lo, v66
	v_mul_f32_e32 v66, 0x3a800000, v66
	v_add_f32_e32 v66, 0x3727c5ac, v66
	v_rsq_f32_e32 v118, v66
	s_nop 0
	v_mov_b32_e32 v119, v118
	v_pk_mul_f32 v[0:1], v[0:1], v[118:119]
	v_pk_mul_f32 v[2:3], v[2:3], v[118:119]
	v_pk_mul_f32 v[4:5], v[4:5], v[118:119]
	v_pk_mul_f32 v[6:7], v[6:7], v[118:119]
	v_pk_mul_f32 v[8:9], v[8:9], v[118:119]
	v_pk_mul_f32 v[10:11], v[10:11], v[118:119]
	v_pk_mul_f32 v[12:13], v[12:13], v[118:119]
	v_pk_mul_f32 v[14:15], v[14:15], v[118:119]
	v_pk_fma_f32 v[76:77], v[0:1], v[34:35], v[50:51]
	v_pk_fma_f32 v[78:79], v[2:3], v[36:37], v[52:53]
	v_pk_fma_f32 v[80:81], v[4:5], v[38:39], v[54:55]
	v_pk_fma_f32 v[82:83], v[6:7], v[40:41], v[56:57]
	v_pk_fma_f32 v[84:85], v[8:9], v[42:43], v[58:59]
	v_pk_fma_f32 v[86:87], v[10:11], v[44:45], v[60:61]
	v_pk_fma_f32 v[88:89], v[12:13], v[46:47], v[62:63]
	v_pk_fma_f32 v[90:91], v[14:15], v[48:49], v[64:65]
	s_cmp_lg_u32 s8, 0
	s_cselect_b32 s9, 1.0, 0x3fb504f3
	v_mov_b32_e32 v120, s9
	v_mov_b32_e32 v121, s9
	v_pk_mul_f32 v[0:1], v[76:77], v[120:121]
	v_pk_mul_f32 v[2:3], v[78:79], v[120:121]
	v_pk_mul_f32 v[4:5], v[80:81], v[120:121]
	v_pk_mul_f32 v[6:7], v[82:83], v[120:121]
	v_pk_mul_f32 v[8:9], v[84:85], v[120:121]
	v_pk_mul_f32 v[10:11], v[86:87], v[120:121]
	v_pk_mul_f32 v[12:13], v[88:89], v[120:121]
	v_pk_mul_f32 v[14:15], v[90:91], v[120:121]
	global_store_dwordx4 v114, v[0:3], s[0:1] offset:0 sc1
	global_store_dwordx4 v114, v[4:7], s[0:1] offset:1024 sc1
	global_store_dwordx4 v114, v[8:11], s[0:1] offset:2048 sc1
	global_store_dwordx4 v114, v[12:15], s[0:1] offset:3072 sc1
	s_cmp_lg_u32 s8, 0
	s_cbranch_scc1 .Lln2_done
	v_cvt_pk_bf16_f32 v92, v76, v77
	v_cvt_pk_bf16_f32 v93, v78, v79
	v_cvt_pk_bf16_f32 v94, v80, v81
	v_cvt_pk_bf16_f32 v95, v82, v83
	v_cvt_pk_bf16_f32 v96, v84, v85
	v_cvt_pk_bf16_f32 v97, v86, v87
	v_cvt_pk_bf16_f32 v98, v88, v89
	v_cvt_pk_bf16_f32 v99, v90, v91
	global_store_dwordx2 v115, v[92:93], s[2:3] offset:0 sc1
	global_store_dwordx2 v115, v[94:95], s[2:3] offset:512 sc1
	global_store_dwordx2 v115, v[96:97], s[2:3] offset:1024 sc1
	global_store_dwordx2 v115, v[98:99], s[2:3] offset:1536 sc1
